# loop-edge edit: GEMM trip loops' scalar induction updates + exit compare hoisted from behind the closing s_barrier into the last MFMA segment's shadow (11 loops)
# baseline (speedup 1.0000x reference)
.LBB0_119:
	s_add_u32 s6, s46, 0xfffc0080
	s_addc_u32 s7, s47, -1
	s_add_i32 s8, 0, 0x10000
	s_cmp_eq_u32 s30, 12
	s_cselect_b32 s19, s12, s7
	s_cselect_b32 s18, s14, s6
	v_add_u32_e32 v143, s8, v139
	s_cselect_b32 s7, s15, s23
	s_cselect_b32 s6, s16, s17
	s_add_i32 s31, 0, 0x14000
	ds_read_b128 v[156:159], v143
	ds_read_b128 v[160:163], v143 offset:1024
	ds_read_b128 v[164:167], v143 offset:2048
	ds_read_b128 v[168:171], v143 offset:3072
	v_add_u32_e32 v143, s31, v139
	ds_read_b128 v[172:175], v143
	ds_read_b128 v[176:179], v143 offset:1024
	ds_read_b128 v[180:183], v143 offset:2048
	ds_read_b128 v[184:187], v143 offset:3072
	v_lshl_add_u64 v[226:227], s[46:47], 0, v[134:135]
	s_add_i32 m0, s13, 0xc000
	ds_read_b128 v[188:191], v142
	ds_read_b128 v[198:201], v142 offset:1024
	ds_read_b128 v[202:205], v142 offset:2048
	ds_read_b128 v[206:209], v142 offset:3072
	ds_read_b128 v[210:213], v142 offset:4096
	ds_read_b128 v[214:217], v142 offset:5120
	ds_read_b128 v[218:221], v142 offset:6144
	ds_read_b128 v[222:225], v142 offset:7168
	global_load_lds_dwordx4 v[226:227], off
	v_lshl_add_u64 v[226:227], s[46:47], 0, v[136:137]
	s_add_i32 m0, s13, 0xe000
	s_nop 0
	global_load_lds_dwordx4 v[226:227], off
	s_waitcnt vmcnt(8)
	s_waitcnt lgkmcnt(0)
	s_barrier
	s_setprio 1
	s_waitcnt lgkmcnt(0)
	v_mfma_f32_16x16x32_bf16 v[124:127], v[156:159], v[188:191], v[124:127]
	v_mfma_f32_16x16x32_bf16 v[120:123], v[164:167], v[188:191], v[120:123]
	v_mfma_f32_16x16x32_bf16 v[108:111], v[156:159], v[202:205], v[108:111]
	v_mfma_f32_16x16x32_bf16 v[104:107], v[164:167], v[202:205], v[104:107]
	v_mfma_f32_16x16x32_bf16 v[92:95], v[156:159], v[210:213], v[92:95]
	v_mfma_f32_16x16x32_bf16 v[88:91], v[164:167], v[210:213], v[88:91]
	v_mfma_f32_16x16x32_bf16 v[76:79], v[156:159], v[218:221], v[76:79]
	v_mfma_f32_16x16x32_bf16 v[72:75], v[164:167], v[218:221], v[72:75]
	v_mfma_f32_16x16x32_bf16 v[124:127], v[160:163], v[198:201], v[124:127]
	v_mfma_f32_16x16x32_bf16 v[120:123], v[168:171], v[198:201], v[120:123]
	v_mfma_f32_16x16x32_bf16 v[108:111], v[160:163], v[206:209], v[108:111]
	v_mfma_f32_16x16x32_bf16 v[104:107], v[168:171], v[206:209], v[104:107]
	v_mfma_f32_16x16x32_bf16 v[92:95], v[160:163], v[214:217], v[92:95]
	v_mfma_f32_16x16x32_bf16 v[88:91], v[168:171], v[214:217], v[88:91]
	v_mfma_f32_16x16x32_bf16 v[76:79], v[160:163], v[222:225], v[76:79]
	v_mfma_f32_16x16x32_bf16 v[72:75], v[168:171], v[222:225], v[72:75]
	s_setprio 0
	s_setprio 1
	v_mfma_f32_16x16x32_bf16 v[116:119], v[172:175], v[188:191], v[116:119]
	v_mfma_f32_16x16x32_bf16 v[112:115], v[180:183], v[188:191], v[112:115]
	v_mfma_f32_16x16x32_bf16 v[100:103], v[172:175], v[202:205], v[100:103]
	v_mfma_f32_16x16x32_bf16 v[96:99], v[180:183], v[202:205], v[96:99]
	v_mfma_f32_16x16x32_bf16 v[84:87], v[172:175], v[210:213], v[84:87]
	v_mfma_f32_16x16x32_bf16 v[80:83], v[180:183], v[210:213], v[80:83]
	v_mfma_f32_16x16x32_bf16 v[68:71], v[172:175], v[218:221], v[68:71]
	v_mfma_f32_16x16x32_bf16 v[64:67], v[180:183], v[218:221], v[64:67]
	v_mfma_f32_16x16x32_bf16 v[116:119], v[176:179], v[198:201], v[116:119]
	v_mfma_f32_16x16x32_bf16 v[112:115], v[184:187], v[198:201], v[112:115]
	v_mfma_f32_16x16x32_bf16 v[100:103], v[176:179], v[206:209], v[100:103]
	v_mfma_f32_16x16x32_bf16 v[96:99], v[184:187], v[206:209], v[96:99]
	v_mfma_f32_16x16x32_bf16 v[84:87], v[176:179], v[214:217], v[84:87]
	v_mfma_f32_16x16x32_bf16 v[80:83], v[184:187], v[214:217], v[80:83]
	v_mfma_f32_16x16x32_bf16 v[68:71], v[176:179], v[222:225], v[68:71]
	v_mfma_f32_16x16x32_bf16 v[64:67], v[184:187], v[222:225], v[64:67]
	s_setprio 0
	s_barrier
	s_add_i32 s8, s8, s0
	v_lshl_add_u64 v[226:227], s[6:7], 0, v[144:145]
	s_mov_b32 m0, s8
	ds_read_b128 v[188:191], v142 offset:16384
	ds_read_b128 v[198:201], v142 offset:17408
	ds_read_b128 v[202:205], v142 offset:18432
	ds_read_b128 v[206:209], v142 offset:19456
	ds_read_b128 v[210:213], v142 offset:20480
	ds_read_b128 v[214:217], v142 offset:21504
	ds_read_b128 v[218:221], v142 offset:22528
	ds_read_b128 v[222:225], v142 offset:23552
	global_load_lds_dwordx4 v[226:227], off
	s_add_i32 m0, s8, 0x2000
	s_add_u32 s8, s6, 0x40000
	v_lshl_add_u64 v[228:229], s[6:7], 0, v[128:129]
	s_addc_u32 s9, s7, 0
	s_add_i32 s31, s31, s0
	global_load_lds_dwordx4 v[228:229], off
	v_lshl_add_u64 v[230:231], s[8:9], 0, v[144:145]
	s_mov_b32 m0, s31
	v_lshl_add_u64 v[232:233], s[18:19], 0, v[130:131]
	global_load_lds_dwordx4 v[230:231], off
	v_lshl_add_u64 v[230:231], s[8:9], 0, v[128:129]
	s_add_i32 m0, s31, 0x2000
	s_nop 0
	global_load_lds_dwordx4 v[230:231], off
	v_lshl_add_u64 v[230:231], s[18:19], 0, v[132:133]
	s_mov_b32 m0, s13
	s_nop 0
	global_load_lds_dwordx4 v[230:231], off
	s_mov_b32 m0, s24
	s_nop 0
	global_load_lds_dwordx4 v[232:233], off
	s_waitcnt vmcnt(8)
	s_waitcnt lgkmcnt(0)
	s_barrier
	s_setprio 1
	s_waitcnt lgkmcnt(0)
	v_mfma_f32_16x16x32_bf16 v[60:63], v[156:159], v[188:191], v[60:63]
	v_mfma_f32_16x16x32_bf16 v[56:59], v[164:167], v[188:191], v[56:59]
	v_mfma_f32_16x16x32_bf16 v[44:47], v[156:159], v[202:205], v[44:47]
	v_mfma_f32_16x16x32_bf16 v[40:43], v[164:167], v[202:205], v[40:43]
	v_mfma_f32_16x16x32_bf16 v[28:31], v[156:159], v[210:213], v[28:31]
	v_mfma_f32_16x16x32_bf16 v[24:27], v[164:167], v[210:213], v[24:27]
	v_mfma_f32_16x16x32_bf16 v[12:15], v[156:159], v[218:221], v[12:15]
	v_mfma_f32_16x16x32_bf16 v[8:11], v[164:167], v[218:221], v[8:11]
	v_mfma_f32_16x16x32_bf16 v[60:63], v[160:163], v[198:201], v[60:63]
	v_mfma_f32_16x16x32_bf16 v[56:59], v[168:171], v[198:201], v[56:59]
	v_mfma_f32_16x16x32_bf16 v[44:47], v[160:163], v[206:209], v[44:47]
	v_mfma_f32_16x16x32_bf16 v[40:43], v[168:171], v[206:209], v[40:43]
	v_mfma_f32_16x16x32_bf16 v[28:31], v[160:163], v[214:217], v[28:31]
	v_mfma_f32_16x16x32_bf16 v[24:27], v[168:171], v[214:217], v[24:27]
	v_mfma_f32_16x16x32_bf16 v[12:15], v[160:163], v[222:225], v[12:15]
	v_mfma_f32_16x16x32_bf16 v[8:11], v[168:171], v[222:225], v[8:11]
	s_setprio 0
	s_setprio 1
	v_mfma_f32_16x16x32_bf16 v[52:55], v[172:175], v[188:191], v[52:55]
	v_mfma_f32_16x16x32_bf16 v[48:51], v[180:183], v[188:191], v[48:51]
	v_mfma_f32_16x16x32_bf16 v[36:39], v[172:175], v[202:205], v[36:39]
	v_mfma_f32_16x16x32_bf16 v[32:35], v[180:183], v[202:205], v[32:35]
	v_mfma_f32_16x16x32_bf16 v[20:23], v[172:175], v[210:213], v[20:23]
	v_mfma_f32_16x16x32_bf16 v[16:19], v[180:183], v[210:213], v[16:19]
	v_mfma_f32_16x16x32_bf16 v[4:7], v[172:175], v[218:221], v[4:7]
	v_mfma_f32_16x16x32_bf16 v[0:3], v[180:183], v[218:221], v[0:3]
	v_mfma_f32_16x16x32_bf16 v[52:55], v[176:179], v[198:201], v[52:55]
	v_mfma_f32_16x16x32_bf16 v[48:51], v[184:187], v[198:201], v[48:51]
	v_mfma_f32_16x16x32_bf16 v[36:39], v[176:179], v[206:209], v[36:39]
	v_mfma_f32_16x16x32_bf16 v[32:35], v[184:187], v[206:209], v[32:35]
	v_mfma_f32_16x16x32_bf16 v[20:23], v[176:179], v[214:217], v[20:23]
	v_mfma_f32_16x16x32_bf16 v[16:19], v[184:187], v[214:217], v[16:19]
	v_mfma_f32_16x16x32_bf16 v[4:7], v[176:179], v[222:225], v[4:7]
	v_mfma_f32_16x16x32_bf16 v[0:3], v[184:187], v[222:225], v[0:3]
	s_setprio 0
	s_barrier
	s_add_i32 s31, 0, 0x18000
	v_add_u32_e32 v143, s31, v139
	s_add_i32 s33, 0, 0x1c000
	ds_read_b128 v[156:159], v143
	ds_read_b128 v[160:163], v143 offset:1024
	ds_read_b128 v[164:167], v143 offset:2048
	ds_read_b128 v[168:171], v143 offset:3072
	v_add_u32_e32 v143, s33, v139
	ds_read_b128 v[172:175], v143
	ds_read_b128 v[176:179], v143 offset:1024
	ds_read_b128 v[180:183], v143 offset:2048
	ds_read_b128 v[184:187], v143 offset:3072
	s_add_u32 s8, s18, 0x40000
	s_addc_u32 s9, s19, 0
	s_mov_b32 m0, s25
	v_lshl_add_u64 v[234:235], s[8:9], 0, v[132:133]
	ds_read_b128 v[188:191], v142 offset:32768
	ds_read_b128 v[198:201], v142 offset:33792
	ds_read_b128 v[202:205], v142 offset:34816
	ds_read_b128 v[206:209], v142 offset:35840
	ds_read_b128 v[210:213], v142 offset:36864
	ds_read_b128 v[214:217], v142 offset:37888
	ds_read_b128 v[218:221], v142 offset:38912
	ds_read_b128 v[222:225], v142 offset:39936
	global_load_lds_dwordx4 v[234:235], off
	v_lshl_add_u64 v[234:235], s[8:9], 0, v[130:131]
	s_mov_b32 m0, s50
	s_nop 0
	global_load_lds_dwordx4 v[234:235], off
	s_waitcnt vmcnt(8)
	s_waitcnt lgkmcnt(0)
	s_barrier
	s_setprio 1
	s_waitcnt lgkmcnt(0)
	v_mfma_f32_16x16x32_bf16 v[124:127], v[156:159], v[188:191], v[124:127]
	v_mfma_f32_16x16x32_bf16 v[120:123], v[164:167], v[188:191], v[120:123]
	v_mfma_f32_16x16x32_bf16 v[108:111], v[156:159], v[202:205], v[108:111]
	v_mfma_f32_16x16x32_bf16 v[104:107], v[164:167], v[202:205], v[104:107]
	v_mfma_f32_16x16x32_bf16 v[92:95], v[156:159], v[210:213], v[92:95]
	v_mfma_f32_16x16x32_bf16 v[88:91], v[164:167], v[210:213], v[88:91]
	v_mfma_f32_16x16x32_bf16 v[76:79], v[156:159], v[218:221], v[76:79]
	v_mfma_f32_16x16x32_bf16 v[72:75], v[164:167], v[218:221], v[72:75]
	v_mfma_f32_16x16x32_bf16 v[124:127], v[160:163], v[198:201], v[124:127]
	v_mfma_f32_16x16x32_bf16 v[120:123], v[168:171], v[198:201], v[120:123]
	v_mfma_f32_16x16x32_bf16 v[108:111], v[160:163], v[206:209], v[108:111]
	v_mfma_f32_16x16x32_bf16 v[104:107], v[168:171], v[206:209], v[104:107]
	v_mfma_f32_16x16x32_bf16 v[92:95], v[160:163], v[214:217], v[92:95]
	v_mfma_f32_16x16x32_bf16 v[88:91], v[168:171], v[214:217], v[88:91]
	v_mfma_f32_16x16x32_bf16 v[76:79], v[160:163], v[222:225], v[76:79]
	v_mfma_f32_16x16x32_bf16 v[72:75], v[168:171], v[222:225], v[72:75]
	s_setprio 0
	s_setprio 1
	v_mfma_f32_16x16x32_bf16 v[116:119], v[172:175], v[188:191], v[116:119]
	v_mfma_f32_16x16x32_bf16 v[112:115], v[180:183], v[188:191], v[112:115]
	v_mfma_f32_16x16x32_bf16 v[100:103], v[172:175], v[202:205], v[100:103]
	v_mfma_f32_16x16x32_bf16 v[96:99], v[180:183], v[202:205], v[96:99]
	v_mfma_f32_16x16x32_bf16 v[84:87], v[172:175], v[210:213], v[84:87]
	v_mfma_f32_16x16x32_bf16 v[80:83], v[180:183], v[210:213], v[80:83]
	v_mfma_f32_16x16x32_bf16 v[68:71], v[172:175], v[218:221], v[68:71]
	v_mfma_f32_16x16x32_bf16 v[64:67], v[180:183], v[218:221], v[64:67]
	v_mfma_f32_16x16x32_bf16 v[116:119], v[176:179], v[198:201], v[116:119]
	v_mfma_f32_16x16x32_bf16 v[112:115], v[184:187], v[198:201], v[112:115]
	v_mfma_f32_16x16x32_bf16 v[100:103], v[176:179], v[206:209], v[100:103]
	v_mfma_f32_16x16x32_bf16 v[96:99], v[184:187], v[206:209], v[96:99]
	v_mfma_f32_16x16x32_bf16 v[84:87], v[176:179], v[214:217], v[84:87]
	v_mfma_f32_16x16x32_bf16 v[80:83], v[184:187], v[214:217], v[80:83]
	v_mfma_f32_16x16x32_bf16 v[68:71], v[176:179], v[222:225], v[68:71]
	v_mfma_f32_16x16x32_bf16 v[64:67], v[184:187], v[222:225], v[64:67]
	s_setprio 0
	s_barrier
	s_add_i32 s8, s31, s0
	v_lshl_add_u64 v[226:227], v[226:227], 0, s[70:71]
	s_mov_b32 m0, s8
	ds_read_b128 v[188:191], v142 offset:49152
	ds_read_b128 v[198:201], v142 offset:50176
	ds_read_b128 v[202:205], v142 offset:51200
	ds_read_b128 v[206:209], v142 offset:52224
	ds_read_b128 v[210:213], v142 offset:53248
	ds_read_b128 v[214:217], v142 offset:54272
	ds_read_b128 v[218:221], v142 offset:55296
	ds_read_b128 v[222:225], v142 offset:56320
	global_load_lds_dwordx4 v[226:227], off
	s_add_i32 m0, s8, 0x2000
	s_add_u32 s6, s6, 0x40080
	v_lshl_add_u64 v[226:227], v[228:229], 0, s[70:71]
	s_addc_u32 s7, s7, 0
	s_add_i32 s8, s33, s0
	global_load_lds_dwordx4 v[226:227], off
	v_lshl_add_u64 v[226:227], s[6:7], 0, v[144:145]
	s_mov_b32 m0, s8
	s_nop 0
	global_load_lds_dwordx4 v[226:227], off
	v_lshl_add_u64 v[226:227], s[6:7], 0, v[128:129]
	s_add_i32 m0, s8, 0x2000
	s_nop 0
	global_load_lds_dwordx4 v[226:227], off
	v_lshl_add_u64 v[226:227], v[230:231], 0, s[70:71]
	s_mov_b32 m0, s51
	s_nop 0
	global_load_lds_dwordx4 v[226:227], off
	v_lshl_add_u64 v[226:227], v[232:233], 0, s[70:71]
	s_mov_b32 m0, s65
	s_nop 0
	global_load_lds_dwordx4 v[226:227], off
	s_waitcnt vmcnt(8)
	s_waitcnt lgkmcnt(0)
	s_barrier
	s_setprio 1
	s_waitcnt lgkmcnt(0)
	v_mfma_f32_16x16x32_bf16 v[60:63], v[156:159], v[188:191], v[60:63]
	v_mfma_f32_16x16x32_bf16 v[56:59], v[164:167], v[188:191], v[56:59]
	v_mfma_f32_16x16x32_bf16 v[44:47], v[156:159], v[202:205], v[44:47]
	v_mfma_f32_16x16x32_bf16 v[40:43], v[164:167], v[202:205], v[40:43]
	v_mfma_f32_16x16x32_bf16 v[28:31], v[156:159], v[210:213], v[28:31]
	v_mfma_f32_16x16x32_bf16 v[24:27], v[164:167], v[210:213], v[24:27]
	v_mfma_f32_16x16x32_bf16 v[12:15], v[156:159], v[218:221], v[12:15]
	v_mfma_f32_16x16x32_bf16 v[8:11], v[164:167], v[218:221], v[8:11]
	v_mfma_f32_16x16x32_bf16 v[60:63], v[160:163], v[198:201], v[60:63]
	v_mfma_f32_16x16x32_bf16 v[56:59], v[168:171], v[198:201], v[56:59]
	v_mfma_f32_16x16x32_bf16 v[44:47], v[160:163], v[206:209], v[44:47]
	v_mfma_f32_16x16x32_bf16 v[40:43], v[168:171], v[206:209], v[40:43]
	v_mfma_f32_16x16x32_bf16 v[28:31], v[160:163], v[214:217], v[28:31]
	v_mfma_f32_16x16x32_bf16 v[24:27], v[168:171], v[214:217], v[24:27]
	v_mfma_f32_16x16x32_bf16 v[12:15], v[160:163], v[222:225], v[12:15]
	v_mfma_f32_16x16x32_bf16 v[8:11], v[168:171], v[222:225], v[8:11]
	s_setprio 0
	s_setprio 1
	v_mfma_f32_16x16x32_bf16 v[52:55], v[172:175], v[188:191], v[52:55]
	s_add_i32 s30, s30, 2
	s_add_u32 s46, s46, 0x100
	s_addc_u32 s47, s47, 0
	s_add_u32 s17, s17, 0x100
	s_addc_u32 s23, s23, 0
	s_cmp_gt_u32 s30, 13
	v_mfma_f32_16x16x32_bf16 v[48:51], v[180:183], v[188:191], v[48:51]
	v_mfma_f32_16x16x32_bf16 v[36:39], v[172:175], v[202:205], v[36:39]
	v_mfma_f32_16x16x32_bf16 v[32:35], v[180:183], v[202:205], v[32:35]
	v_mfma_f32_16x16x32_bf16 v[20:23], v[172:175], v[210:213], v[20:23]
	v_mfma_f32_16x16x32_bf16 v[16:19], v[180:183], v[210:213], v[16:19]
	v_mfma_f32_16x16x32_bf16 v[4:7], v[172:175], v[218:221], v[4:7]
	v_mfma_f32_16x16x32_bf16 v[0:3], v[180:183], v[218:221], v[0:3]
	v_mfma_f32_16x16x32_bf16 v[52:55], v[176:179], v[198:201], v[52:55]
	v_mfma_f32_16x16x32_bf16 v[48:51], v[184:187], v[198:201], v[48:51]
	v_mfma_f32_16x16x32_bf16 v[36:39], v[176:179], v[206:209], v[36:39]
	v_mfma_f32_16x16x32_bf16 v[32:35], v[184:187], v[206:209], v[32:35]
	v_mfma_f32_16x16x32_bf16 v[20:23], v[176:179], v[214:217], v[20:23]
	v_mfma_f32_16x16x32_bf16 v[16:19], v[184:187], v[214:217], v[16:19]
	v_mfma_f32_16x16x32_bf16 v[4:7], v[176:179], v[222:225], v[4:7]
	v_mfma_f32_16x16x32_bf16 v[0:3], v[184:187], v[222:225], v[0:3]
	s_setprio 0
	s_barrier
	s_cbranch_scc0 .LBB0_119
	s_and_b64 vcc, exec, s[4:5]
	s_cbranch_vccz .LBB0_122
	s_barrier

.LBB0_156:
	s_add_u32 s6, s48, 0xfffc0080
	s_addc_u32 s7, s49, -1
	s_add_i32 s8, 0, 0x10000
	s_cmp_eq_u32 s37, 12
	s_cselect_b32 s19, s23, s7
	s_cselect_b32 s18, s24, s6
	v_add_u32_e32 v142, s8, v139
	s_cselect_b32 s7, s25, s33
	s_cselect_b32 s6, s30, s31
	s_add_i32 s41, 0, 0x14000
	ds_read_b128 v[156:159], v142
	ds_read_b128 v[160:163], v142 offset:1024
	ds_read_b128 v[164:167], v142 offset:2048
	ds_read_b128 v[168:171], v142 offset:3072
	v_add_u32_e32 v142, s41, v139
	ds_read_b128 v[172:175], v142
	ds_read_b128 v[176:179], v142 offset:1024
	ds_read_b128 v[180:183], v142 offset:2048
	ds_read_b128 v[184:187], v142 offset:3072
	v_lshl_add_u64 v[142:143], s[48:49], 0, v[134:135]
	s_add_i32 m0, s13, 0xc000
	ds_read_b128 v[188:191], v141
	ds_read_b128 v[198:201], v141 offset:1024
	ds_read_b128 v[202:205], v141 offset:2048
	ds_read_b128 v[206:209], v141 offset:3072
	ds_read_b128 v[210:213], v141 offset:4096
	ds_read_b128 v[214:217], v141 offset:5120
	ds_read_b128 v[218:221], v141 offset:6144
	ds_read_b128 v[222:225], v141 offset:7168
	global_load_lds_dwordx4 v[142:143], off
	v_lshl_add_u64 v[142:143], s[48:49], 0, v[136:137]
	s_add_i32 m0, s13, 0xe000
	s_nop 0
	global_load_lds_dwordx4 v[142:143], off
	s_waitcnt vmcnt(8)
	s_waitcnt lgkmcnt(0)
	s_barrier
	s_setprio 1
	s_waitcnt lgkmcnt(0)
	v_mfma_f32_16x16x32_bf16 v[124:127], v[156:159], v[188:191], v[124:127]
	v_mfma_f32_16x16x32_bf16 v[120:123], v[164:167], v[188:191], v[120:123]
	v_mfma_f32_16x16x32_bf16 v[116:119], v[156:159], v[202:205], v[116:119]
	v_mfma_f32_16x16x32_bf16 v[112:115], v[164:167], v[202:205], v[112:115]
	v_mfma_f32_16x16x32_bf16 v[100:103], v[156:159], v[210:213], v[100:103]
	v_mfma_f32_16x16x32_bf16 v[96:99], v[164:167], v[210:213], v[96:99]
	v_mfma_f32_16x16x32_bf16 v[84:87], v[156:159], v[218:221], v[84:87]
	v_mfma_f32_16x16x32_bf16 v[80:83], v[164:167], v[218:221], v[80:83]
	v_mfma_f32_16x16x32_bf16 v[124:127], v[160:163], v[198:201], v[124:127]
	v_mfma_f32_16x16x32_bf16 v[120:123], v[168:171], v[198:201], v[120:123]
	v_mfma_f32_16x16x32_bf16 v[116:119], v[160:163], v[206:209], v[116:119]
	v_mfma_f32_16x16x32_bf16 v[112:115], v[168:171], v[206:209], v[112:115]
	v_mfma_f32_16x16x32_bf16 v[100:103], v[160:163], v[214:217], v[100:103]
	v_mfma_f32_16x16x32_bf16 v[96:99], v[168:171], v[214:217], v[96:99]
	v_mfma_f32_16x16x32_bf16 v[84:87], v[160:163], v[222:225], v[84:87]
	v_mfma_f32_16x16x32_bf16 v[80:83], v[168:171], v[222:225], v[80:83]
	s_setprio 0
	s_setprio 1
	v_mfma_f32_16x16x32_bf16 v[108:111], v[172:175], v[188:191], v[108:111]
	v_mfma_f32_16x16x32_bf16 v[104:107], v[180:183], v[188:191], v[104:107]
	v_mfma_f32_16x16x32_bf16 v[92:95], v[172:175], v[202:205], v[92:95]
	v_mfma_f32_16x16x32_bf16 v[88:91], v[180:183], v[202:205], v[88:91]
	v_mfma_f32_16x16x32_bf16 v[76:79], v[172:175], v[210:213], v[76:79]
	v_mfma_f32_16x16x32_bf16 v[72:75], v[180:183], v[210:213], v[72:75]
	v_mfma_f32_16x16x32_bf16 v[68:71], v[172:175], v[218:221], v[68:71]
	v_mfma_f32_16x16x32_bf16 v[64:67], v[180:183], v[218:221], v[64:67]
	v_mfma_f32_16x16x32_bf16 v[108:111], v[176:179], v[198:201], v[108:111]
	v_mfma_f32_16x16x32_bf16 v[104:107], v[184:187], v[198:201], v[104:107]
	v_mfma_f32_16x16x32_bf16 v[92:95], v[176:179], v[206:209], v[92:95]
	v_mfma_f32_16x16x32_bf16 v[88:91], v[184:187], v[206:209], v[88:91]
	v_mfma_f32_16x16x32_bf16 v[76:79], v[176:179], v[214:217], v[76:79]
	v_mfma_f32_16x16x32_bf16 v[72:75], v[184:187], v[214:217], v[72:75]
	v_mfma_f32_16x16x32_bf16 v[68:71], v[176:179], v[222:225], v[68:71]
	v_mfma_f32_16x16x32_bf16 v[64:67], v[184:187], v[222:225], v[64:67]
	s_setprio 0
	s_barrier
	s_add_i32 s8, s8, s12
	v_lshl_add_u64 v[142:143], s[6:7], 0, v[144:145]
	s_mov_b32 m0, s8
	ds_read_b128 v[188:191], v141 offset:16384
	ds_read_b128 v[198:201], v141 offset:17408
	ds_read_b128 v[202:205], v141 offset:18432
	ds_read_b128 v[206:209], v141 offset:19456
	ds_read_b128 v[210:213], v141 offset:20480
	ds_read_b128 v[214:217], v141 offset:21504
	ds_read_b128 v[218:221], v141 offset:22528
	ds_read_b128 v[222:225], v141 offset:23552
	global_load_lds_dwordx4 v[142:143], off
	s_add_i32 m0, s8, 0x2000
	s_add_u32 s8, s6, 0x40000
	v_lshl_add_u64 v[226:227], s[6:7], 0, v[132:133]
	s_addc_u32 s9, s7, 0
	s_add_i32 s41, s41, s12
	global_load_lds_dwordx4 v[226:227], off
	v_lshl_add_u64 v[228:229], s[8:9], 0, v[144:145]
	s_mov_b32 m0, s41
	v_lshl_add_u64 v[230:231], s[18:19], 0, v[130:131]
	global_load_lds_dwordx4 v[228:229], off
	v_lshl_add_u64 v[228:229], s[8:9], 0, v[132:133]
	s_add_i32 m0, s41, 0x2000
	s_nop 0
	global_load_lds_dwordx4 v[228:229], off
	v_lshl_add_u64 v[228:229], s[18:19], 0, v[128:129]
	s_mov_b32 m0, s13
	s_nop 0
	global_load_lds_dwordx4 v[228:229], off
	s_mov_b32 m0, s14
	s_nop 0
	global_load_lds_dwordx4 v[230:231], off
	s_waitcnt vmcnt(8)
	s_waitcnt lgkmcnt(0)
	s_barrier
	s_setprio 1
	s_waitcnt lgkmcnt(0)
	v_mfma_f32_16x16x32_bf16 v[60:63], v[156:159], v[188:191], v[60:63]
	v_mfma_f32_16x16x32_bf16 v[56:59], v[164:167], v[188:191], v[56:59]
	v_mfma_f32_16x16x32_bf16 v[52:55], v[156:159], v[202:205], v[52:55]
	v_mfma_f32_16x16x32_bf16 v[48:51], v[164:167], v[202:205], v[48:51]
	v_mfma_f32_16x16x32_bf16 v[36:39], v[156:159], v[210:213], v[36:39]
	v_mfma_f32_16x16x32_bf16 v[32:35], v[164:167], v[210:213], v[32:35]
	v_mfma_f32_16x16x32_bf16 v[20:23], v[156:159], v[218:221], v[20:23]
	v_mfma_f32_16x16x32_bf16 v[16:19], v[164:167], v[218:221], v[16:19]
	v_mfma_f32_16x16x32_bf16 v[60:63], v[160:163], v[198:201], v[60:63]
	v_mfma_f32_16x16x32_bf16 v[56:59], v[168:171], v[198:201], v[56:59]
	v_mfma_f32_16x16x32_bf16 v[52:55], v[160:163], v[206:209], v[52:55]
	v_mfma_f32_16x16x32_bf16 v[48:51], v[168:171], v[206:209], v[48:51]
	v_mfma_f32_16x16x32_bf16 v[36:39], v[160:163], v[214:217], v[36:39]
	v_mfma_f32_16x16x32_bf16 v[32:35], v[168:171], v[214:217], v[32:35]
	v_mfma_f32_16x16x32_bf16 v[20:23], v[160:163], v[222:225], v[20:23]
	v_mfma_f32_16x16x32_bf16 v[16:19], v[168:171], v[222:225], v[16:19]
	s_setprio 0
	s_setprio 1
	v_mfma_f32_16x16x32_bf16 v[44:47], v[172:175], v[188:191], v[44:47]
	v_mfma_f32_16x16x32_bf16 v[40:43], v[180:183], v[188:191], v[40:43]
	v_mfma_f32_16x16x32_bf16 v[28:31], v[172:175], v[202:205], v[28:31]
	v_mfma_f32_16x16x32_bf16 v[24:27], v[180:183], v[202:205], v[24:27]
	v_mfma_f32_16x16x32_bf16 v[12:15], v[172:175], v[210:213], v[12:15]
	v_mfma_f32_16x16x32_bf16 v[8:11], v[180:183], v[210:213], v[8:11]
	v_mfma_f32_16x16x32_bf16 v[4:7], v[172:175], v[218:221], v[4:7]
	v_mfma_f32_16x16x32_bf16 v[0:3], v[180:183], v[218:221], v[0:3]
	v_mfma_f32_16x16x32_bf16 v[44:47], v[176:179], v[198:201], v[44:47]
	v_mfma_f32_16x16x32_bf16 v[40:43], v[184:187], v[198:201], v[40:43]
	v_mfma_f32_16x16x32_bf16 v[28:31], v[176:179], v[206:209], v[28:31]
	v_mfma_f32_16x16x32_bf16 v[24:27], v[184:187], v[206:209], v[24:27]
	v_mfma_f32_16x16x32_bf16 v[12:15], v[176:179], v[214:217], v[12:15]
	v_mfma_f32_16x16x32_bf16 v[8:11], v[184:187], v[214:217], v[8:11]
	v_mfma_f32_16x16x32_bf16 v[4:7], v[176:179], v[222:225], v[4:7]
	v_mfma_f32_16x16x32_bf16 v[0:3], v[184:187], v[222:225], v[0:3]
	s_setprio 0
	s_barrier
	s_add_i32 s41, 0, 0x18000
	v_add_u32_e32 v146, s41, v139
	s_add_i32 s43, 0, 0x1c000
	ds_read_b128 v[156:159], v146
	ds_read_b128 v[160:163], v146 offset:1024
	ds_read_b128 v[164:167], v146 offset:2048
	ds_read_b128 v[168:171], v146 offset:3072
	v_add_u32_e32 v146, s43, v139
	ds_read_b128 v[172:175], v146
	ds_read_b128 v[176:179], v146 offset:1024
	ds_read_b128 v[180:183], v146 offset:2048
	ds_read_b128 v[184:187], v146 offset:3072
	s_add_u32 s8, s18, 0x40000
	s_addc_u32 s9, s19, 0
	s_mov_b32 m0, s15
	v_lshl_add_u64 v[232:233], s[8:9], 0, v[128:129]
	ds_read_b128 v[188:191], v141 offset:32768
	ds_read_b128 v[198:201], v141 offset:33792
	ds_read_b128 v[202:205], v141 offset:34816
	ds_read_b128 v[206:209], v141 offset:35840
	ds_read_b128 v[210:213], v141 offset:36864
	ds_read_b128 v[214:217], v141 offset:37888
	ds_read_b128 v[218:221], v141 offset:38912
	ds_read_b128 v[222:225], v141 offset:39936
	global_load_lds_dwordx4 v[232:233], off
	v_lshl_add_u64 v[232:233], s[8:9], 0, v[130:131]
	s_mov_b32 m0, s16
	s_nop 0
	global_load_lds_dwordx4 v[232:233], off
	s_waitcnt vmcnt(8)
	s_waitcnt lgkmcnt(0)
	s_barrier
	s_setprio 1
	s_waitcnt lgkmcnt(0)
	v_mfma_f32_16x16x32_bf16 v[124:127], v[156:159], v[188:191], v[124:127]
	v_mfma_f32_16x16x32_bf16 v[120:123], v[164:167], v[188:191], v[120:123]
	v_mfma_f32_16x16x32_bf16 v[116:119], v[156:159], v[202:205], v[116:119]
	v_mfma_f32_16x16x32_bf16 v[112:115], v[164:167], v[202:205], v[112:115]
	v_mfma_f32_16x16x32_bf16 v[100:103], v[156:159], v[210:213], v[100:103]
	v_mfma_f32_16x16x32_bf16 v[96:99], v[164:167], v[210:213], v[96:99]
	v_mfma_f32_16x16x32_bf16 v[84:87], v[156:159], v[218:221], v[84:87]
	v_mfma_f32_16x16x32_bf16 v[80:83], v[164:167], v[218:221], v[80:83]
	v_mfma_f32_16x16x32_bf16 v[124:127], v[160:163], v[198:201], v[124:127]
	v_mfma_f32_16x16x32_bf16 v[120:123], v[168:171], v[198:201], v[120:123]
	v_mfma_f32_16x16x32_bf16 v[116:119], v[160:163], v[206:209], v[116:119]
	v_mfma_f32_16x16x32_bf16 v[112:115], v[168:171], v[206:209], v[112:115]
	v_mfma_f32_16x16x32_bf16 v[100:103], v[160:163], v[214:217], v[100:103]
	v_mfma_f32_16x16x32_bf16 v[96:99], v[168:171], v[214:217], v[96:99]
	v_mfma_f32_16x16x32_bf16 v[84:87], v[160:163], v[222:225], v[84:87]
	v_mfma_f32_16x16x32_bf16 v[80:83], v[168:171], v[222:225], v[80:83]
	s_setprio 0
	s_setprio 1
	v_mfma_f32_16x16x32_bf16 v[108:111], v[172:175], v[188:191], v[108:111]
	v_mfma_f32_16x16x32_bf16 v[104:107], v[180:183], v[188:191], v[104:107]
	v_mfma_f32_16x16x32_bf16 v[92:95], v[172:175], v[202:205], v[92:95]
	v_mfma_f32_16x16x32_bf16 v[88:91], v[180:183], v[202:205], v[88:91]
	v_mfma_f32_16x16x32_bf16 v[76:79], v[172:175], v[210:213], v[76:79]
	v_mfma_f32_16x16x32_bf16 v[72:75], v[180:183], v[210:213], v[72:75]
	v_mfma_f32_16x16x32_bf16 v[68:71], v[172:175], v[218:221], v[68:71]
	v_mfma_f32_16x16x32_bf16 v[64:67], v[180:183], v[218:221], v[64:67]
	v_mfma_f32_16x16x32_bf16 v[108:111], v[176:179], v[198:201], v[108:111]
	v_mfma_f32_16x16x32_bf16 v[104:107], v[184:187], v[198:201], v[104:107]
	v_mfma_f32_16x16x32_bf16 v[92:95], v[176:179], v[206:209], v[92:95]
	v_mfma_f32_16x16x32_bf16 v[88:91], v[184:187], v[206:209], v[88:91]
	v_mfma_f32_16x16x32_bf16 v[76:79], v[176:179], v[214:217], v[76:79]
	v_mfma_f32_16x16x32_bf16 v[72:75], v[184:187], v[214:217], v[72:75]
	v_mfma_f32_16x16x32_bf16 v[68:71], v[176:179], v[222:225], v[68:71]
	v_mfma_f32_16x16x32_bf16 v[64:67], v[184:187], v[222:225], v[64:67]
	s_setprio 0
	s_barrier
	s_add_i32 s8, s41, s12
	v_lshl_add_u64 v[142:143], v[142:143], 0, s[70:71]
	s_mov_b32 m0, s8
	ds_read_b128 v[188:191], v141 offset:49152
	ds_read_b128 v[198:201], v141 offset:50176
	ds_read_b128 v[202:205], v141 offset:51200
	ds_read_b128 v[206:209], v141 offset:52224
	ds_read_b128 v[210:213], v141 offset:53248
	ds_read_b128 v[214:217], v141 offset:54272
	ds_read_b128 v[218:221], v141 offset:55296
	ds_read_b128 v[222:225], v141 offset:56320
	global_load_lds_dwordx4 v[142:143], off
	s_add_i32 m0, s8, 0x2000
	s_add_u32 s6, s6, 0x40080
	v_lshl_add_u64 v[142:143], v[226:227], 0, s[70:71]
	s_addc_u32 s7, s7, 0
	s_add_i32 s8, s43, s12
	global_load_lds_dwordx4 v[142:143], off
	v_lshl_add_u64 v[142:143], s[6:7], 0, v[144:145]
	s_mov_b32 m0, s8
	s_nop 0
	global_load_lds_dwordx4 v[142:143], off
	v_lshl_add_u64 v[142:143], s[6:7], 0, v[132:133]
	s_add_i32 m0, s8, 0x2000
	s_nop 0
	global_load_lds_dwordx4 v[142:143], off
	v_lshl_add_u64 v[142:143], v[228:229], 0, s[70:71]
	s_mov_b32 m0, s0
	s_nop 0
	global_load_lds_dwordx4 v[142:143], off
	v_lshl_add_u64 v[142:143], v[230:231], 0, s[70:71]
	s_mov_b32 m0, s17
	s_nop 0
	global_load_lds_dwordx4 v[142:143], off
	s_waitcnt vmcnt(8)
	s_waitcnt lgkmcnt(0)
	s_barrier
	s_setprio 1
	s_waitcnt lgkmcnt(0)
	v_mfma_f32_16x16x32_bf16 v[60:63], v[156:159], v[188:191], v[60:63]
	v_mfma_f32_16x16x32_bf16 v[56:59], v[164:167], v[188:191], v[56:59]
	v_mfma_f32_16x16x32_bf16 v[52:55], v[156:159], v[202:205], v[52:55]
	v_mfma_f32_16x16x32_bf16 v[48:51], v[164:167], v[202:205], v[48:51]
	v_mfma_f32_16x16x32_bf16 v[36:39], v[156:159], v[210:213], v[36:39]
	v_mfma_f32_16x16x32_bf16 v[32:35], v[164:167], v[210:213], v[32:35]
	v_mfma_f32_16x16x32_bf16 v[20:23], v[156:159], v[218:221], v[20:23]
	v_mfma_f32_16x16x32_bf16 v[16:19], v[164:167], v[218:221], v[16:19]
	v_mfma_f32_16x16x32_bf16 v[60:63], v[160:163], v[198:201], v[60:63]
	v_mfma_f32_16x16x32_bf16 v[56:59], v[168:171], v[198:201], v[56:59]
	v_mfma_f32_16x16x32_bf16 v[52:55], v[160:163], v[206:209], v[52:55]
	v_mfma_f32_16x16x32_bf16 v[48:51], v[168:171], v[206:209], v[48:51]
	v_mfma_f32_16x16x32_bf16 v[36:39], v[160:163], v[214:217], v[36:39]
	v_mfma_f32_16x16x32_bf16 v[32:35], v[168:171], v[214:217], v[32:35]
	v_mfma_f32_16x16x32_bf16 v[20:23], v[160:163], v[222:225], v[20:23]
	v_mfma_f32_16x16x32_bf16 v[16:19], v[168:171], v[222:225], v[16:19]
	s_setprio 0
	s_setprio 1
	v_mfma_f32_16x16x32_bf16 v[44:47], v[172:175], v[188:191], v[44:47]
	s_add_i32 s37, s37, 2
	s_add_u32 s48, s48, 0x100
	s_addc_u32 s49, s49, 0
	s_add_u32 s31, s31, 0x100
	s_addc_u32 s33, s33, 0
	s_cmp_gt_u32 s37, 13
	v_mfma_f32_16x16x32_bf16 v[40:43], v[180:183], v[188:191], v[40:43]
	v_mfma_f32_16x16x32_bf16 v[28:31], v[172:175], v[202:205], v[28:31]
	v_mfma_f32_16x16x32_bf16 v[24:27], v[180:183], v[202:205], v[24:27]
	v_mfma_f32_16x16x32_bf16 v[12:15], v[172:175], v[210:213], v[12:15]
	v_mfma_f32_16x16x32_bf16 v[8:11], v[180:183], v[210:213], v[8:11]
	v_mfma_f32_16x16x32_bf16 v[4:7], v[172:175], v[218:221], v[4:7]
	v_mfma_f32_16x16x32_bf16 v[0:3], v[180:183], v[218:221], v[0:3]
	v_mfma_f32_16x16x32_bf16 v[44:47], v[176:179], v[198:201], v[44:47]
	v_mfma_f32_16x16x32_bf16 v[40:43], v[184:187], v[198:201], v[40:43]
	v_mfma_f32_16x16x32_bf16 v[28:31], v[176:179], v[206:209], v[28:31]
	v_mfma_f32_16x16x32_bf16 v[24:27], v[184:187], v[206:209], v[24:27]
	v_mfma_f32_16x16x32_bf16 v[12:15], v[176:179], v[214:217], v[12:15]
	v_mfma_f32_16x16x32_bf16 v[8:11], v[184:187], v[214:217], v[8:11]
	v_mfma_f32_16x16x32_bf16 v[4:7], v[176:179], v[222:225], v[4:7]
	v_mfma_f32_16x16x32_bf16 v[0:3], v[184:187], v[222:225], v[0:3]
	s_setprio 0
	s_barrier
	s_cbranch_scc0 .LBB0_156
	s_and_b64 vcc, exec, s[4:5]
	s_movk_i32 s23, 0xf000
	s_movk_i32 s33, 0xe000
	s_mov_b32 s30, s52
	s_cbranch_vccz .LBB0_159
	s_barrier

.LBB0_286:
	s_add_i32 s30, 0, 0x10000
	s_add_i32 s15, 0, 0x14000
	v_add_u32_e32 v169, s30, v166
	v_add_u32_e32 v170, s15, v166
	ds_read_b128 v[172:175], v169
	ds_read_b128 v[176:179], v169 offset:1024
	ds_read_b128 v[180:183], v169 offset:2048
	ds_read_b128 v[184:187], v169 offset:3072
	ds_read_b128 v[188:191], v170
	ds_read_b128 v[198:201], v170 offset:1024
	ds_read_b128 v[202:205], v170 offset:2048
	ds_read_b128 v[206:209], v170 offset:3072
	v_lshl_add_u64 v[246:247], v[142:143], 0, s[48:49]
	s_add_i32 s31, s51, 0xc000
	v_lshl_add_u64 v[242:243], v[246:247], 0, s[28:29]
	s_mov_b32 m0, s31
	v_lshl_add_u64 v[248:249], v[156:157], 0, s[48:49]
	s_add_i32 s11, s51, 0xe000
	ds_read_b128 v[210:213], v168
	ds_read_b128 v[214:217], v168 offset:1024
	ds_read_b128 v[218:221], v168 offset:2048
	ds_read_b128 v[222:225], v168 offset:3072
	ds_read_b128 v[226:229], v168 offset:4096
	ds_read_b128 v[230:233], v168 offset:5120
	ds_read_b128 v[234:237], v168 offset:6144
	ds_read_b128 v[238:241], v168 offset:7168
	global_load_lds_dwordx4 v[242:243], off
	v_lshl_add_u64 v[242:243], v[248:249], 0, s[28:29]
	s_mov_b32 m0, s11
	s_nop 0
	global_load_lds_dwordx4 v[242:243], off
	s_waitcnt vmcnt(8)
	s_waitcnt lgkmcnt(0)
	s_barrier
	s_setprio 1
	s_waitcnt lgkmcnt(0)
	v_mfma_f32_16x16x32_bf16 v[136:139], v[172:175], v[210:213], v[136:139]
	v_mfma_f32_16x16x32_bf16 v[132:135], v[180:183], v[210:213], v[132:135]
	v_mfma_f32_16x16x32_bf16 v[116:119], v[172:175], v[218:221], v[116:119]
	v_mfma_f32_16x16x32_bf16 v[112:115], v[180:183], v[218:221], v[112:115]
	v_mfma_f32_16x16x32_bf16 v[96:99], v[172:175], v[226:229], v[96:99]
	v_mfma_f32_16x16x32_bf16 v[92:95], v[180:183], v[226:229], v[92:95]
	v_mfma_f32_16x16x32_bf16 v[76:79], v[172:175], v[234:237], v[76:79]
	v_mfma_f32_16x16x32_bf16 v[72:75], v[180:183], v[234:237], v[72:75]
	v_mfma_f32_16x16x32_bf16 v[136:139], v[176:179], v[214:217], v[136:139]
	v_mfma_f32_16x16x32_bf16 v[132:135], v[184:187], v[214:217], v[132:135]
	v_mfma_f32_16x16x32_bf16 v[116:119], v[176:179], v[222:225], v[116:119]
	v_mfma_f32_16x16x32_bf16 v[112:115], v[184:187], v[222:225], v[112:115]
	v_mfma_f32_16x16x32_bf16 v[96:99], v[176:179], v[230:233], v[96:99]
	v_mfma_f32_16x16x32_bf16 v[92:95], v[184:187], v[230:233], v[92:95]
	v_mfma_f32_16x16x32_bf16 v[76:79], v[176:179], v[238:241], v[76:79]
	v_mfma_f32_16x16x32_bf16 v[72:75], v[184:187], v[238:241], v[72:75]
	s_setprio 0
	s_setprio 1
	v_mfma_f32_16x16x32_bf16 v[124:127], v[188:191], v[210:213], v[124:127]
	v_mfma_f32_16x16x32_bf16 v[120:123], v[202:205], v[210:213], v[120:123]
	v_mfma_f32_16x16x32_bf16 v[104:107], v[188:191], v[218:221], v[104:107]
	v_mfma_f32_16x16x32_bf16 v[100:103], v[202:205], v[218:221], v[100:103]
	v_mfma_f32_16x16x32_bf16 v[84:87], v[188:191], v[226:229], v[84:87]
	v_mfma_f32_16x16x32_bf16 v[80:83], v[202:205], v[226:229], v[80:83]
	v_mfma_f32_16x16x32_bf16 v[68:71], v[188:191], v[234:237], v[68:71]
	v_mfma_f32_16x16x32_bf16 v[64:67], v[202:205], v[234:237], v[64:67]
	v_mfma_f32_16x16x32_bf16 v[124:127], v[198:201], v[214:217], v[124:127]
	v_mfma_f32_16x16x32_bf16 v[120:123], v[206:209], v[214:217], v[120:123]
	v_mfma_f32_16x16x32_bf16 v[104:107], v[198:201], v[222:225], v[104:107]
	v_mfma_f32_16x16x32_bf16 v[100:103], v[206:209], v[222:225], v[100:103]
	v_mfma_f32_16x16x32_bf16 v[84:87], v[198:201], v[230:233], v[84:87]
	v_mfma_f32_16x16x32_bf16 v[80:83], v[206:209], v[230:233], v[80:83]
	v_mfma_f32_16x16x32_bf16 v[68:71], v[198:201], v[238:241], v[68:71]
	v_mfma_f32_16x16x32_bf16 v[64:67], v[206:209], v[238:241], v[64:67]
	s_setprio 0
	s_barrier
	v_lshl_add_u64 v[154:155], v[158:159], 0, s[48:49]
	s_add_i32 s30, s30, s50
	v_lshl_add_u64 v[242:243], v[154:155], 0, s[96:97]
	s_mov_b32 m0, s30
	v_lshl_add_u64 v[146:147], v[160:161], 0, s[48:49]
	s_add_i32 s12, s30, 0x2000
	ds_read_b128 v[210:213], v168 offset:16384
	ds_read_b128 v[214:217], v168 offset:17408
	ds_read_b128 v[218:221], v168 offset:18432
	ds_read_b128 v[222:225], v168 offset:19456
	ds_read_b128 v[226:229], v168 offset:20480
	ds_read_b128 v[230:233], v168 offset:21504
	ds_read_b128 v[234:237], v168 offset:22528
	ds_read_b128 v[238:241], v168 offset:23552
	global_load_lds_dwordx4 v[242:243], off
	v_lshl_add_u64 v[242:243], v[146:147], 0, s[96:97]
	s_mov_b32 m0, s12
	s_add_i32 s15, s15, s50
	global_load_lds_dwordx4 v[242:243], off
	v_lshl_add_u64 v[242:243], v[154:155], 0, s[56:57]
	s_mov_b32 m0, s15
	s_add_i32 s17, s15, 0x2000
	global_load_lds_dwordx4 v[242:243], off
	v_lshl_add_u64 v[242:243], v[146:147], 0, s[56:57]
	s_mov_b32 m0, s17
	s_nop 0
	global_load_lds_dwordx4 v[242:243], off
	v_lshl_add_u64 v[242:243], v[246:247], 0, s[96:97]
	s_mov_b32 m0, s51
	s_nop 0
	global_load_lds_dwordx4 v[242:243], off
	v_lshl_add_u64 v[242:243], v[248:249], 0, s[96:97]
	s_mov_b32 m0, s65
	s_nop 0
	global_load_lds_dwordx4 v[242:243], off
	s_waitcnt vmcnt(8)
	s_waitcnt lgkmcnt(0)
	s_barrier
	s_setprio 1
	s_waitcnt lgkmcnt(0)
	v_mfma_f32_16x16x32_bf16 v[60:63], v[172:175], v[210:213], v[60:63]
	v_mfma_f32_16x16x32_bf16 v[56:59], v[180:183], v[210:213], v[56:59]
	v_mfma_f32_16x16x32_bf16 v[44:47], v[172:175], v[218:221], v[44:47]
	v_mfma_f32_16x16x32_bf16 v[40:43], v[180:183], v[218:221], v[40:43]
	v_mfma_f32_16x16x32_bf16 v[28:31], v[172:175], v[226:229], v[28:31]
	v_mfma_f32_16x16x32_bf16 v[24:27], v[180:183], v[226:229], v[24:27]
	v_mfma_f32_16x16x32_bf16 v[4:7], v[172:175], v[234:237], v[4:7]
	v_mfma_f32_16x16x32_bf16 v[0:3], v[180:183], v[234:237], v[0:3]
	v_mfma_f32_16x16x32_bf16 v[60:63], v[176:179], v[214:217], v[60:63]
	v_mfma_f32_16x16x32_bf16 v[56:59], v[184:187], v[214:217], v[56:59]
	v_mfma_f32_16x16x32_bf16 v[44:47], v[176:179], v[222:225], v[44:47]
	v_mfma_f32_16x16x32_bf16 v[40:43], v[184:187], v[222:225], v[40:43]
	v_mfma_f32_16x16x32_bf16 v[28:31], v[176:179], v[230:233], v[28:31]
	v_mfma_f32_16x16x32_bf16 v[24:27], v[184:187], v[230:233], v[24:27]
	v_mfma_f32_16x16x32_bf16 v[4:7], v[176:179], v[238:241], v[4:7]
	v_mfma_f32_16x16x32_bf16 v[0:3], v[184:187], v[238:241], v[0:3]
	s_setprio 0
	s_setprio 1
	v_mfma_f32_16x16x32_bf16 v[52:55], v[188:191], v[210:213], v[52:55]
	v_mfma_f32_16x16x32_bf16 v[48:51], v[202:205], v[210:213], v[48:51]
	v_mfma_f32_16x16x32_bf16 v[36:39], v[188:191], v[218:221], v[36:39]
	v_mfma_f32_16x16x32_bf16 v[32:35], v[202:205], v[218:221], v[32:35]
	v_mfma_f32_16x16x32_bf16 v[12:15], v[188:191], v[226:229], v[12:15]
	v_mfma_f32_16x16x32_bf16 v[8:11], v[202:205], v[226:229], v[8:11]
	v_mfma_f32_16x16x32_bf16 v[20:23], v[188:191], v[234:237], v[20:23]
	v_mfma_f32_16x16x32_bf16 v[16:19], v[202:205], v[234:237], v[16:19]
	v_mfma_f32_16x16x32_bf16 v[52:55], v[198:201], v[214:217], v[52:55]
	v_mfma_f32_16x16x32_bf16 v[48:51], v[206:209], v[214:217], v[48:51]
	v_mfma_f32_16x16x32_bf16 v[36:39], v[198:201], v[222:225], v[36:39]
	v_mfma_f32_16x16x32_bf16 v[32:35], v[206:209], v[222:225], v[32:35]
	v_mfma_f32_16x16x32_bf16 v[12:15], v[198:201], v[230:233], v[12:15]
	v_mfma_f32_16x16x32_bf16 v[8:11], v[206:209], v[230:233], v[8:11]
	v_mfma_f32_16x16x32_bf16 v[20:23], v[198:201], v[238:241], v[20:23]
	v_mfma_f32_16x16x32_bf16 v[16:19], v[206:209], v[238:241], v[16:19]
	s_setprio 0
	s_barrier
	s_add_i32 s33, 0, 0x18000
	s_add_i32 s14, 0, 0x1c000
	v_add_u32_e32 v171, s33, v166
	v_add_u32_e32 v172, s14, v166
	ds_read_b128 v[174:177], v171
	ds_read_b128 v[178:181], v171 offset:1024
	ds_read_b128 v[182:185], v171 offset:2048
	ds_read_b128 v[186:189], v171 offset:3072
	ds_read_b128 v[198:201], v172
	ds_read_b128 v[202:205], v172 offset:1024
	ds_read_b128 v[206:209], v172 offset:2048
	ds_read_b128 v[210:213], v172 offset:3072
	s_mov_b32 m0, s68
	v_lshl_add_u64 v[190:191], v[246:247], 0, s[34:35]
	ds_read_b128 v[214:217], v168 offset:32768
	ds_read_b128 v[218:221], v168 offset:33792
	ds_read_b128 v[222:225], v168 offset:34816
	ds_read_b128 v[226:229], v168 offset:35840
	ds_read_b128 v[230:233], v168 offset:36864
	ds_read_b128 v[234:237], v168 offset:37888
	ds_read_b128 v[238:241], v168 offset:38912
	ds_read_b128 v[242:245], v168 offset:39936
	global_load_lds_dwordx4 v[190:191], off
	v_lshl_add_u64 v[190:191], v[248:249], 0, s[34:35]
	s_mov_b32 m0, s69
	s_nop 0
	global_load_lds_dwordx4 v[190:191], off
	s_waitcnt vmcnt(8)
	s_waitcnt lgkmcnt(0)
	s_barrier
	s_setprio 1
	s_waitcnt lgkmcnt(0)
	v_mfma_f32_16x16x32_bf16 v[136:139], v[174:177], v[214:217], v[136:139]
	v_mfma_f32_16x16x32_bf16 v[132:135], v[182:185], v[214:217], v[132:135]
	v_mfma_f32_16x16x32_bf16 v[116:119], v[174:177], v[222:225], v[116:119]
	v_mfma_f32_16x16x32_bf16 v[112:115], v[182:185], v[222:225], v[112:115]
	v_mfma_f32_16x16x32_bf16 v[96:99], v[174:177], v[230:233], v[96:99]
	v_mfma_f32_16x16x32_bf16 v[92:95], v[182:185], v[230:233], v[92:95]
	v_mfma_f32_16x16x32_bf16 v[76:79], v[174:177], v[238:241], v[76:79]
	v_mfma_f32_16x16x32_bf16 v[72:75], v[182:185], v[238:241], v[72:75]
	v_mfma_f32_16x16x32_bf16 v[136:139], v[178:181], v[218:221], v[136:139]
	v_mfma_f32_16x16x32_bf16 v[132:135], v[186:189], v[218:221], v[132:135]
	v_mfma_f32_16x16x32_bf16 v[116:119], v[178:181], v[226:229], v[116:119]
	v_mfma_f32_16x16x32_bf16 v[112:115], v[186:189], v[226:229], v[112:115]
	v_mfma_f32_16x16x32_bf16 v[96:99], v[178:181], v[234:237], v[96:99]
	v_mfma_f32_16x16x32_bf16 v[92:95], v[186:189], v[234:237], v[92:95]
	v_mfma_f32_16x16x32_bf16 v[76:79], v[178:181], v[242:245], v[76:79]
	v_mfma_f32_16x16x32_bf16 v[72:75], v[186:189], v[242:245], v[72:75]
	s_setprio 0
	s_setprio 1
	v_mfma_f32_16x16x32_bf16 v[124:127], v[198:201], v[214:217], v[124:127]
	v_mfma_f32_16x16x32_bf16 v[120:123], v[206:209], v[214:217], v[120:123]
	v_mfma_f32_16x16x32_bf16 v[104:107], v[198:201], v[222:225], v[104:107]
	v_mfma_f32_16x16x32_bf16 v[100:103], v[206:209], v[222:225], v[100:103]
	v_mfma_f32_16x16x32_bf16 v[84:87], v[198:201], v[230:233], v[84:87]
	v_mfma_f32_16x16x32_bf16 v[80:83], v[206:209], v[230:233], v[80:83]
	v_mfma_f32_16x16x32_bf16 v[68:71], v[198:201], v[238:241], v[68:71]
	v_mfma_f32_16x16x32_bf16 v[64:67], v[206:209], v[238:241], v[64:67]
	v_mfma_f32_16x16x32_bf16 v[124:127], v[202:205], v[218:221], v[124:127]
	v_mfma_f32_16x16x32_bf16 v[120:123], v[210:213], v[218:221], v[120:123]
	v_mfma_f32_16x16x32_bf16 v[104:107], v[202:205], v[226:229], v[104:107]
	v_mfma_f32_16x16x32_bf16 v[100:103], v[210:213], v[226:229], v[100:103]
	v_mfma_f32_16x16x32_bf16 v[84:87], v[202:205], v[234:237], v[84:87]
	v_mfma_f32_16x16x32_bf16 v[80:83], v[210:213], v[234:237], v[80:83]
	v_mfma_f32_16x16x32_bf16 v[68:71], v[202:205], v[242:245], v[68:71]
	v_mfma_f32_16x16x32_bf16 v[64:67], v[210:213], v[242:245], v[64:67]
	s_setprio 0
	s_barrier
	s_add_i32 s33, s33, s50
	v_lshl_add_u64 v[190:191], v[154:155], 0, s[58:59]
	s_mov_b32 m0, s33
	s_add_i32 s23, s33, 0x2000
	ds_read_b128 v[214:217], v168 offset:49152
	ds_read_b128 v[218:221], v168 offset:50176
	ds_read_b128 v[222:225], v168 offset:51200
	ds_read_b128 v[226:229], v168 offset:52224
	ds_read_b128 v[230:233], v168 offset:53248
	ds_read_b128 v[234:237], v168 offset:54272
	ds_read_b128 v[238:241], v168 offset:55296
	ds_read_b128 v[242:245], v168 offset:56320
	global_load_lds_dwordx4 v[190:191], off
	v_lshl_add_u64 v[190:191], v[146:147], 0, s[58:59]
	s_mov_b32 m0, s23
	s_add_i32 s14, s14, s50
	global_load_lds_dwordx4 v[190:191], off
	v_lshl_add_u64 v[154:155], v[154:155], 0, s[72:73]
	s_mov_b32 m0, s14
	s_add_i32 s16, s14, 0x2000
	global_load_lds_dwordx4 v[154:155], off
	v_lshl_add_u64 v[146:147], v[146:147], 0, s[72:73]
	s_mov_b32 m0, s16
	s_nop 0
	global_load_lds_dwordx4 v[146:147], off
	v_lshl_add_u64 v[146:147], v[246:247], 0, s[58:59]
	s_mov_b32 m0, s84
	s_nop 0
	global_load_lds_dwordx4 v[146:147], off
	v_lshl_add_u64 v[146:147], v[248:249], 0, s[58:59]
	s_mov_b32 m0, s85
	s_nop 0
	global_load_lds_dwordx4 v[146:147], off
	s_waitcnt vmcnt(8)
	s_waitcnt lgkmcnt(0)
	s_barrier
	s_setprio 1
	s_waitcnt lgkmcnt(0)
	v_mfma_f32_16x16x32_bf16 v[60:63], v[174:177], v[214:217], v[60:63]
	v_mfma_f32_16x16x32_bf16 v[56:59], v[182:185], v[214:217], v[56:59]
	v_mfma_f32_16x16x32_bf16 v[44:47], v[174:177], v[222:225], v[44:47]
	v_mfma_f32_16x16x32_bf16 v[40:43], v[182:185], v[222:225], v[40:43]
	v_mfma_f32_16x16x32_bf16 v[28:31], v[174:177], v[230:233], v[28:31]
	v_mfma_f32_16x16x32_bf16 v[24:27], v[182:185], v[230:233], v[24:27]
	v_mfma_f32_16x16x32_bf16 v[4:7], v[174:177], v[238:241], v[4:7]
	v_mfma_f32_16x16x32_bf16 v[0:3], v[182:185], v[238:241], v[0:3]
	v_mfma_f32_16x16x32_bf16 v[60:63], v[178:181], v[218:221], v[60:63]
	v_mfma_f32_16x16x32_bf16 v[56:59], v[186:189], v[218:221], v[56:59]
	v_mfma_f32_16x16x32_bf16 v[44:47], v[178:181], v[226:229], v[44:47]
	v_mfma_f32_16x16x32_bf16 v[40:43], v[186:189], v[226:229], v[40:43]
	v_mfma_f32_16x16x32_bf16 v[28:31], v[178:181], v[234:237], v[28:31]
	v_mfma_f32_16x16x32_bf16 v[24:27], v[186:189], v[234:237], v[24:27]
	v_mfma_f32_16x16x32_bf16 v[4:7], v[178:181], v[242:245], v[4:7]
	v_mfma_f32_16x16x32_bf16 v[0:3], v[186:189], v[242:245], v[0:3]
	s_setprio 0
	s_setprio 1
	v_mfma_f32_16x16x32_bf16 v[52:55], v[198:201], v[214:217], v[52:55]
	s_add_i32 s3, s3, 2
	s_add_u32 s48, s48, 0x100
	s_addc_u32 s49, s49, 0
	s_cmp_gt_u32 s3, 39
	v_mfma_f32_16x16x32_bf16 v[48:51], v[206:209], v[214:217], v[48:51]
	v_mfma_f32_16x16x32_bf16 v[36:39], v[198:201], v[222:225], v[36:39]
	v_mfma_f32_16x16x32_bf16 v[32:35], v[206:209], v[222:225], v[32:35]
	v_mfma_f32_16x16x32_bf16 v[12:15], v[198:201], v[230:233], v[12:15]
	v_mfma_f32_16x16x32_bf16 v[8:11], v[206:209], v[230:233], v[8:11]
	v_mfma_f32_16x16x32_bf16 v[20:23], v[198:201], v[238:241], v[20:23]
	v_mfma_f32_16x16x32_bf16 v[16:19], v[206:209], v[238:241], v[16:19]
	v_mfma_f32_16x16x32_bf16 v[52:55], v[202:205], v[218:221], v[52:55]
	v_mfma_f32_16x16x32_bf16 v[48:51], v[210:213], v[218:221], v[48:51]
	v_mfma_f32_16x16x32_bf16 v[36:39], v[202:205], v[226:229], v[36:39]
	v_mfma_f32_16x16x32_bf16 v[32:35], v[210:213], v[226:229], v[32:35]
	v_mfma_f32_16x16x32_bf16 v[12:15], v[202:205], v[234:237], v[12:15]
	v_mfma_f32_16x16x32_bf16 v[8:11], v[210:213], v[234:237], v[8:11]
	v_mfma_f32_16x16x32_bf16 v[20:23], v[202:205], v[242:245], v[20:23]
	v_mfma_f32_16x16x32_bf16 v[16:19], v[210:213], v[242:245], v[16:19]
	s_setprio 0
	s_barrier
	s_cbranch_scc0 .LBB0_286
	ds_read_b128 v[156:159], v169
	ds_read_b128 v[174:177], v169 offset:1024
	ds_read_b128 v[178:181], v169 offset:2048
	ds_read_b128 v[182:185], v169 offset:3072
	ds_read_b128 v[186:189], v170
	ds_read_b128 v[198:201], v170 offset:1024
	ds_read_b128 v[202:205], v170 offset:2048
	ds_read_b128 v[206:209], v170 offset:3072
	s_ashr_i32 s43, s42, 31
	s_ashr_i32 s3, s2, 31
	s_lshl_b64 s[6:7], s[2:3], 9
	s_lshl_b64 s[8:9], s[42:43], 19
	s_add_u32 s3, s60, s8
	s_addc_u32 s8, s61, s9
	s_add_u32 s6, s3, s6
	s_addc_u32 s7, s8, s7
	s_add_u32 s8, s44, 0xc1580
	s_addc_u32 s9, s45, 0
	s_mov_b32 m0, s31
	v_lshl_add_u64 v[142:143], s[8:9], 0, v[144:145]
	ds_read_b128 v[210:213], v168
	ds_read_b128 v[214:217], v168 offset:1024
	ds_read_b128 v[218:221], v168 offset:2048
	ds_read_b128 v[222:225], v168 offset:3072
	ds_read_b128 v[226:229], v168 offset:4096
	ds_read_b128 v[230:233], v168 offset:5120
	ds_read_b128 v[234:237], v168 offset:6144
	ds_read_b128 v[238:241], v168 offset:7168
	global_load_lds_dwordx4 v[142:143], off
	v_lshl_add_u64 v[142:143], s[8:9], 0, v[88:89]
	s_mov_b32 m0, s11
	s_nop 0
	global_load_lds_dwordx4 v[142:143], off
	s_waitcnt vmcnt(8)
	s_waitcnt lgkmcnt(0)
	s_barrier
	s_setprio 1
	s_waitcnt lgkmcnt(0)
	v_mfma_f32_16x16x32_bf16 v[136:139], v[156:159], v[210:213], v[136:139]
	v_mfma_f32_16x16x32_bf16 v[132:135], v[178:181], v[210:213], v[132:135]
	v_mfma_f32_16x16x32_bf16 v[116:119], v[156:159], v[218:221], v[116:119]
	v_mfma_f32_16x16x32_bf16 v[112:115], v[178:181], v[218:221], v[112:115]
	v_mfma_f32_16x16x32_bf16 v[96:99], v[156:159], v[226:229], v[96:99]
	v_mfma_f32_16x16x32_bf16 v[92:95], v[178:181], v[226:229], v[92:95]
	v_mfma_f32_16x16x32_bf16 v[76:79], v[156:159], v[234:237], v[76:79]
	v_mfma_f32_16x16x32_bf16 v[72:75], v[178:181], v[234:237], v[72:75]
	v_mfma_f32_16x16x32_bf16 v[136:139], v[174:177], v[214:217], v[136:139]
	v_mfma_f32_16x16x32_bf16 v[132:135], v[182:185], v[214:217], v[132:135]
	v_mfma_f32_16x16x32_bf16 v[116:119], v[174:177], v[222:225], v[116:119]
	v_mfma_f32_16x16x32_bf16 v[112:115], v[182:185], v[222:225], v[112:115]
	v_mfma_f32_16x16x32_bf16 v[96:99], v[174:177], v[230:233], v[96:99]
	v_mfma_f32_16x16x32_bf16 v[92:95], v[182:185], v[230:233], v[92:95]
	v_mfma_f32_16x16x32_bf16 v[76:79], v[174:177], v[238:241], v[76:79]
	v_mfma_f32_16x16x32_bf16 v[72:75], v[182:185], v[238:241], v[72:75]
	s_setprio 0
	s_setprio 1
	v_mfma_f32_16x16x32_bf16 v[124:127], v[186:189], v[210:213], v[124:127]
	v_mfma_f32_16x16x32_bf16 v[120:123], v[202:205], v[210:213], v[120:123]
	v_mfma_f32_16x16x32_bf16 v[104:107], v[186:189], v[218:221], v[104:107]
	v_mfma_f32_16x16x32_bf16 v[100:103], v[202:205], v[218:221], v[100:103]
	v_mfma_f32_16x16x32_bf16 v[84:87], v[186:189], v[226:229], v[84:87]
	v_mfma_f32_16x16x32_bf16 v[80:83], v[202:205], v[226:229], v[80:83]
	v_mfma_f32_16x16x32_bf16 v[68:71], v[186:189], v[234:237], v[68:71]
	v_mfma_f32_16x16x32_bf16 v[64:67], v[202:205], v[234:237], v[64:67]
	v_mfma_f32_16x16x32_bf16 v[124:127], v[198:201], v[214:217], v[124:127]
	v_mfma_f32_16x16x32_bf16 v[120:123], v[206:209], v[214:217], v[120:123]
	v_mfma_f32_16x16x32_bf16 v[104:107], v[198:201], v[222:225], v[104:107]
	v_mfma_f32_16x16x32_bf16 v[100:103], v[206:209], v[222:225], v[100:103]
	v_mfma_f32_16x16x32_bf16 v[84:87], v[198:201], v[230:233], v[84:87]
	v_mfma_f32_16x16x32_bf16 v[80:83], v[206:209], v[230:233], v[80:83]
	v_mfma_f32_16x16x32_bf16 v[68:71], v[198:201], v[238:241], v[68:71]
	v_mfma_f32_16x16x32_bf16 v[64:67], v[206:209], v[238:241], v[64:67]
	s_setprio 0
	s_barrier
	s_mov_b32 m0, s30
	v_lshl_add_u64 v[142:143], s[6:7], 0, v[90:91]
	ds_read_b128 v[210:213], v168 offset:16384
	ds_read_b128 v[214:217], v168 offset:17408
	ds_read_b128 v[218:221], v168 offset:18432
	ds_read_b128 v[222:225], v168 offset:19456
	ds_read_b128 v[226:229], v168 offset:20480
	ds_read_b128 v[230:233], v168 offset:21504
	ds_read_b128 v[234:237], v168 offset:22528
	ds_read_b128 v[238:241], v168 offset:23552
	global_load_lds_dwordx4 v[142:143], off
	v_lshl_add_u64 v[160:161], s[6:7], 0, v[108:109]
	s_mov_b32 m0, s12
	v_lshl_add_u64 v[190:191], v[142:143], 0, s[70:71]
	global_load_lds_dwordx4 v[160:161], off
	s_mov_b32 m0, s15
	s_nop 0
	global_load_lds_dwordx4 v[190:191], off
	v_lshl_add_u64 v[190:191], v[160:161], 0, s[70:71]
	s_mov_b32 m0, s17
	s_nop 0
	global_load_lds_dwordx4 v[190:191], off
	v_lshl_add_u64 v[190:191], v[142:143], 0, s[96:97]
	s_mov_b32 m0, s51
	s_nop 0
	global_load_lds_dwordx4 v[190:191], off
	v_lshl_add_u64 v[190:191], v[160:161], 0, s[96:97]
	s_mov_b32 m0, s65
	s_nop 0
	global_load_lds_dwordx4 v[190:191], off
	s_waitcnt vmcnt(8)
	s_waitcnt lgkmcnt(0)
	s_barrier
	s_setprio 1
	s_waitcnt lgkmcnt(0)
	v_mfma_f32_16x16x32_bf16 v[60:63], v[156:159], v[210:213], v[60:63]
	v_mfma_f32_16x16x32_bf16 v[56:59], v[178:181], v[210:213], v[56:59]
	v_mfma_f32_16x16x32_bf16 v[44:47], v[156:159], v[218:221], v[44:47]
	v_mfma_f32_16x16x32_bf16 v[40:43], v[178:181], v[218:221], v[40:43]
	v_mfma_f32_16x16x32_bf16 v[28:31], v[156:159], v[226:229], v[28:31]
	v_mfma_f32_16x16x32_bf16 v[24:27], v[178:181], v[226:229], v[24:27]
	v_mfma_f32_16x16x32_bf16 v[4:7], v[156:159], v[234:237], v[4:7]
	v_mfma_f32_16x16x32_bf16 v[0:3], v[178:181], v[234:237], v[0:3]
	v_mfma_f32_16x16x32_bf16 v[60:63], v[174:177], v[214:217], v[60:63]
	v_mfma_f32_16x16x32_bf16 v[56:59], v[182:185], v[214:217], v[56:59]
	v_mfma_f32_16x16x32_bf16 v[44:47], v[174:177], v[222:225], v[44:47]
	v_mfma_f32_16x16x32_bf16 v[40:43], v[182:185], v[222:225], v[40:43]
	v_mfma_f32_16x16x32_bf16 v[28:31], v[174:177], v[230:233], v[28:31]
	v_mfma_f32_16x16x32_bf16 v[24:27], v[182:185], v[230:233], v[24:27]
	v_mfma_f32_16x16x32_bf16 v[4:7], v[174:177], v[238:241], v[4:7]
	v_mfma_f32_16x16x32_bf16 v[0:3], v[182:185], v[238:241], v[0:3]
	s_setprio 0
	s_setprio 1
	v_mfma_f32_16x16x32_bf16 v[52:55], v[186:189], v[210:213], v[52:55]
	v_mfma_f32_16x16x32_bf16 v[48:51], v[202:205], v[210:213], v[48:51]
	v_mfma_f32_16x16x32_bf16 v[36:39], v[186:189], v[218:221], v[36:39]
	v_mfma_f32_16x16x32_bf16 v[32:35], v[202:205], v[218:221], v[32:35]
	v_mfma_f32_16x16x32_bf16 v[12:15], v[186:189], v[226:229], v[12:15]
	v_mfma_f32_16x16x32_bf16 v[8:11], v[202:205], v[226:229], v[8:11]
	v_mfma_f32_16x16x32_bf16 v[20:23], v[186:189], v[234:237], v[20:23]
	v_mfma_f32_16x16x32_bf16 v[16:19], v[202:205], v[234:237], v[16:19]
	v_mfma_f32_16x16x32_bf16 v[52:55], v[198:201], v[214:217], v[52:55]
	v_mfma_f32_16x16x32_bf16 v[48:51], v[206:209], v[214:217], v[48:51]
	v_mfma_f32_16x16x32_bf16 v[36:39], v[198:201], v[222:225], v[36:39]
	v_mfma_f32_16x16x32_bf16 v[32:35], v[206:209], v[222:225], v[32:35]
	v_mfma_f32_16x16x32_bf16 v[12:15], v[198:201], v[230:233], v[12:15]
	v_mfma_f32_16x16x32_bf16 v[8:11], v[206:209], v[230:233], v[8:11]
	v_mfma_f32_16x16x32_bf16 v[20:23], v[198:201], v[238:241], v[20:23]
	v_mfma_f32_16x16x32_bf16 v[16:19], v[206:209], v[238:241], v[16:19]
	s_setprio 0
	s_barrier
	ds_read_b128 v[156:159], v171
	ds_read_b128 v[174:177], v171 offset:1024
	ds_read_b128 v[178:181], v171 offset:2048
	ds_read_b128 v[182:185], v171 offset:3072
	ds_read_b128 v[186:189], v172
	ds_read_b128 v[198:201], v172 offset:1024
	ds_read_b128 v[202:205], v172 offset:2048
	ds_read_b128 v[170:173], v172 offset:3072
	s_mov_b32 m0, s68
	v_lshl_add_u64 v[142:143], v[142:143], 0, s[58:59]
	ds_read_b128 v[206:209], v168 offset:32768
	ds_read_b128 v[210:213], v168 offset:33792
	ds_read_b128 v[214:217], v168 offset:34816
	ds_read_b128 v[218:221], v168 offset:35840
	ds_read_b128 v[222:225], v168 offset:36864
	ds_read_b128 v[226:229], v168 offset:37888
	ds_read_b128 v[230:233], v168 offset:38912
	ds_read_b128 v[234:237], v168 offset:39936
	global_load_lds_dwordx4 v[142:143], off
	v_lshl_add_u64 v[142:143], v[160:161], 0, s[58:59]
	s_mov_b32 m0, s69
	s_nop 0
	global_load_lds_dwordx4 v[142:143], off
	s_waitcnt vmcnt(8)
	s_waitcnt lgkmcnt(0)
	s_barrier
	s_setprio 1
	s_waitcnt lgkmcnt(0)
	v_mfma_f32_16x16x32_bf16 v[136:139], v[156:159], v[206:209], v[136:139]
	v_mfma_f32_16x16x32_bf16 v[132:135], v[178:181], v[206:209], v[132:135]
	v_mfma_f32_16x16x32_bf16 v[116:119], v[156:159], v[214:217], v[116:119]
	v_mfma_f32_16x16x32_bf16 v[112:115], v[178:181], v[214:217], v[112:115]
	v_mfma_f32_16x16x32_bf16 v[96:99], v[156:159], v[222:225], v[96:99]
	v_mfma_f32_16x16x32_bf16 v[92:95], v[178:181], v[222:225], v[92:95]
	v_mfma_f32_16x16x32_bf16 v[76:79], v[156:159], v[230:233], v[76:79]
	v_mfma_f32_16x16x32_bf16 v[72:75], v[178:181], v[230:233], v[72:75]
	v_mfma_f32_16x16x32_bf16 v[136:139], v[174:177], v[210:213], v[136:139]
	v_mfma_f32_16x16x32_bf16 v[132:135], v[182:185], v[210:213], v[132:135]
	v_mfma_f32_16x16x32_bf16 v[116:119], v[174:177], v[218:221], v[116:119]
	v_mfma_f32_16x16x32_bf16 v[112:115], v[182:185], v[218:221], v[112:115]
	v_mfma_f32_16x16x32_bf16 v[96:99], v[174:177], v[226:229], v[96:99]
	v_mfma_f32_16x16x32_bf16 v[92:95], v[182:185], v[226:229], v[92:95]
	v_mfma_f32_16x16x32_bf16 v[76:79], v[174:177], v[234:237], v[76:79]
	v_mfma_f32_16x16x32_bf16 v[72:75], v[182:185], v[234:237], v[72:75]
	s_setprio 0
	s_setprio 1
	v_mfma_f32_16x16x32_bf16 v[124:127], v[186:189], v[206:209], v[124:127]
	v_mfma_f32_16x16x32_bf16 v[120:123], v[202:205], v[206:209], v[120:123]
	v_mfma_f32_16x16x32_bf16 v[104:107], v[186:189], v[214:217], v[104:107]
	v_mfma_f32_16x16x32_bf16 v[100:103], v[202:205], v[214:217], v[100:103]
	v_mfma_f32_16x16x32_bf16 v[84:87], v[186:189], v[222:225], v[84:87]
	v_mfma_f32_16x16x32_bf16 v[80:83], v[202:205], v[222:225], v[80:83]
	v_mfma_f32_16x16x32_bf16 v[68:71], v[186:189], v[230:233], v[68:71]
	v_mfma_f32_16x16x32_bf16 v[64:67], v[202:205], v[230:233], v[64:67]
	v_mfma_f32_16x16x32_bf16 v[124:127], v[198:201], v[210:213], v[124:127]
	v_mfma_f32_16x16x32_bf16 v[120:123], v[170:173], v[210:213], v[120:123]
	v_mfma_f32_16x16x32_bf16 v[104:107], v[198:201], v[218:221], v[104:107]
	v_mfma_f32_16x16x32_bf16 v[100:103], v[170:173], v[218:221], v[100:103]
	v_mfma_f32_16x16x32_bf16 v[84:87], v[198:201], v[226:229], v[84:87]
	v_mfma_f32_16x16x32_bf16 v[80:83], v[170:173], v[226:229], v[80:83]
	v_mfma_f32_16x16x32_bf16 v[68:71], v[198:201], v[234:237], v[68:71]
	v_mfma_f32_16x16x32_bf16 v[64:67], v[170:173], v[234:237], v[64:67]
	s_setprio 0
	s_barrier
	s_add_u32 s8, s6, 0x40000
	s_addc_u32 s9, s7, 0
	s_mov_b32 m0, s33
	v_lshl_add_u64 v[142:143], s[8:9], 0, v[90:91]
	ds_read_b128 v[206:209], v168 offset:49152
	ds_read_b128 v[210:213], v168 offset:50176
	ds_read_b128 v[214:217], v168 offset:51200
	ds_read_b128 v[218:221], v168 offset:52224
	ds_read_b128 v[222:225], v168 offset:53248
	ds_read_b128 v[226:229], v168 offset:54272
	ds_read_b128 v[230:233], v168 offset:55296
	ds_read_b128 v[234:237], v168 offset:56320
	global_load_lds_dwordx4 v[142:143], off
	v_lshl_add_u64 v[142:143], s[8:9], 0, v[108:109]
	s_add_u32 s8, s6, 0x40080
	s_mov_b32 m0, s23
	s_addc_u32 s9, s7, 0
	global_load_lds_dwordx4 v[142:143], off
	v_lshl_add_u64 v[142:143], s[8:9], 0, v[90:91]
	s_mov_b32 m0, s14
	s_add_u32 s6, s6, 0x40100
	global_load_lds_dwordx4 v[142:143], off
	v_lshl_add_u64 v[142:143], s[8:9], 0, v[108:109]
	s_mov_b32 m0, s16
	s_addc_u32 s7, s7, 0
	global_load_lds_dwordx4 v[142:143], off
	v_lshl_add_u64 v[142:143], s[6:7], 0, v[90:91]
	s_mov_b32 m0, s84
	s_nop 0
	global_load_lds_dwordx4 v[142:143], off
	v_lshl_add_u64 v[142:143], s[6:7], 0, v[108:109]
	s_mov_b32 m0, s85
	s_nop 0
	global_load_lds_dwordx4 v[142:143], off
	s_waitcnt vmcnt(8)
	s_waitcnt lgkmcnt(0)
	s_barrier
	s_setprio 1
	s_waitcnt lgkmcnt(0)
	v_mfma_f32_16x16x32_bf16 v[60:63], v[156:159], v[206:209], v[60:63]
	v_mfma_f32_16x16x32_bf16 v[56:59], v[178:181], v[206:209], v[56:59]
	v_mfma_f32_16x16x32_bf16 v[44:47], v[156:159], v[214:217], v[44:47]
	v_mfma_f32_16x16x32_bf16 v[40:43], v[178:181], v[214:217], v[40:43]
	v_mfma_f32_16x16x32_bf16 v[28:31], v[156:159], v[222:225], v[28:31]
	v_mfma_f32_16x16x32_bf16 v[24:27], v[178:181], v[222:225], v[24:27]
	v_mfma_f32_16x16x32_bf16 v[4:7], v[156:159], v[230:233], v[4:7]
	v_mfma_f32_16x16x32_bf16 v[0:3], v[178:181], v[230:233], v[0:3]
	v_mfma_f32_16x16x32_bf16 v[60:63], v[174:177], v[210:213], v[60:63]
	v_mfma_f32_16x16x32_bf16 v[56:59], v[182:185], v[210:213], v[56:59]
	v_mfma_f32_16x16x32_bf16 v[44:47], v[174:177], v[218:221], v[44:47]
	v_mfma_f32_16x16x32_bf16 v[40:43], v[182:185], v[218:221], v[40:43]
	v_mfma_f32_16x16x32_bf16 v[28:31], v[174:177], v[226:229], v[28:31]
	v_mfma_f32_16x16x32_bf16 v[24:27], v[182:185], v[226:229], v[24:27]
	v_mfma_f32_16x16x32_bf16 v[4:7], v[174:177], v[234:237], v[4:7]
	v_mfma_f32_16x16x32_bf16 v[0:3], v[182:185], v[234:237], v[0:3]
	s_setprio 0
	s_setprio 1
	v_mfma_f32_16x16x32_bf16 v[52:55], v[186:189], v[206:209], v[52:55]
	v_mfma_f32_16x16x32_bf16 v[48:51], v[202:205], v[206:209], v[48:51]
	v_mfma_f32_16x16x32_bf16 v[36:39], v[186:189], v[214:217], v[36:39]
	v_mfma_f32_16x16x32_bf16 v[32:35], v[202:205], v[214:217], v[32:35]
	v_mfma_f32_16x16x32_bf16 v[12:15], v[186:189], v[222:225], v[12:15]
	v_mfma_f32_16x16x32_bf16 v[8:11], v[202:205], v[222:225], v[8:11]
	v_mfma_f32_16x16x32_bf16 v[20:23], v[186:189], v[230:233], v[20:23]
	v_mfma_f32_16x16x32_bf16 v[16:19], v[202:205], v[230:233], v[16:19]
	v_mfma_f32_16x16x32_bf16 v[52:55], v[198:201], v[210:213], v[52:55]
	v_mfma_f32_16x16x32_bf16 v[48:51], v[170:173], v[210:213], v[48:51]
	v_mfma_f32_16x16x32_bf16 v[36:39], v[198:201], v[218:221], v[36:39]
	v_mfma_f32_16x16x32_bf16 v[32:35], v[170:173], v[218:221], v[32:35]
	v_mfma_f32_16x16x32_bf16 v[12:15], v[198:201], v[226:229], v[12:15]
	v_mfma_f32_16x16x32_bf16 v[8:11], v[170:173], v[226:229], v[8:11]
	v_mfma_f32_16x16x32_bf16 v[20:23], v[198:201], v[234:237], v[20:23]
	v_mfma_f32_16x16x32_bf16 v[16:19], v[170:173], v[234:237], v[16:19]
	s_setprio 0
	s_barrier
	s_and_b64 vcc, exec, s[38:39]
	s_cbranch_vccz .LBB0_274
	s_nop 1
	v_mov_b32_e32 v8, 0
	s_mov_b32 s42, s64
	s_mov_b32 s2, s87
	s_mov_b64 s[4:5], s[40:41]
	s_mov_b64 s[44:45], s[46:47]
	s_mov_b32 s86, s10
	v_mov_b32_e32 v9, v8
	v_mov_b32_e32 v10, v8
	v_mov_b32_e32 v11, v8
	v_mov_b32_e32 v12, v8
	v_mov_b32_e32 v13, v8
	v_mov_b32_e32 v14, v8
	v_mov_b32_e32 v15, v8
	v_mov_b32_e32 v32, v8
	v_mov_b32_e32 v33, v8
	v_mov_b32_e32 v34, v8
	v_mov_b32_e32 v35, v8
	v_mov_b32_e32 v36, v8
	v_mov_b32_e32 v37, v8
	v_mov_b32_e32 v38, v8
	v_mov_b32_e32 v39, v8
	v_mov_b32_e32 v48, v8
	v_mov_b32_e32 v49, v8
	v_mov_b32_e32 v50, v8
	v_mov_b32_e32 v51, v8
	v_mov_b32_e32 v52, v8
	v_mov_b32_e32 v53, v8
	v_mov_b32_e32 v54, v8
	v_mov_b32_e32 v55, v8
	v_mov_b32_e32 v0, v8
	v_mov_b32_e32 v1, v8
	v_mov_b32_e32 v2, v8
	v_mov_b32_e32 v3, v8
	v_mov_b32_e32 v4, v8
	v_mov_b32_e32 v5, v8
	v_mov_b32_e32 v6, v8
	v_mov_b32_e32 v7, v8
	v_mov_b32_e32 v24, v8
	v_mov_b32_e32 v25, v8
	v_mov_b32_e32 v26, v8
	v_mov_b32_e32 v27, v8
	v_mov_b32_e32 v28, v8
	v_mov_b32_e32 v29, v8
	v_mov_b32_e32 v30, v8
	v_mov_b32_e32 v31, v8
	v_mov_b32_e32 v40, v8
	v_mov_b32_e32 v41, v8
	v_mov_b32_e32 v42, v8
	v_mov_b32_e32 v43, v8
	v_mov_b32_e32 v44, v8
	v_mov_b32_e32 v45, v8
	v_mov_b32_e32 v46, v8
	v_mov_b32_e32 v47, v8
	v_mov_b32_e32 v56, v8
	v_mov_b32_e32 v57, v8
	v_mov_b32_e32 v58, v8
	v_mov_b32_e32 v59, v8
	v_mov_b32_e32 v60, v8
	v_mov_b32_e32 v61, v8
	v_mov_b32_e32 v62, v8
	v_mov_b32_e32 v63, v8
	v_mov_b32_e32 v64, v8
	v_mov_b32_e32 v65, v8
	v_mov_b32_e32 v66, v8
	v_mov_b32_e32 v67, v8
	v_mov_b32_e32 v68, v8
	v_mov_b32_e32 v69, v8
	v_mov_b32_e32 v70, v8
	v_mov_b32_e32 v71, v8
	v_mov_b32_e32 v80, v8
	v_mov_b32_e32 v81, v8
	v_mov_b32_e32 v82, v8
	v_mov_b32_e32 v83, v8
	v_mov_b32_e32 v84, v8
	v_mov_b32_e32 v85, v8
	v_mov_b32_e32 v86, v8
	v_mov_b32_e32 v87, v8
	v_mov_b32_e32 v100, v8
	v_mov_b32_e32 v101, v8
	v_mov_b32_e32 v102, v8
	v_mov_b32_e32 v103, v8
	v_mov_b32_e32 v104, v8
	v_mov_b32_e32 v105, v8
	v_mov_b32_e32 v106, v8
	v_mov_b32_e32 v107, v8
	v_mov_b32_e32 v120, v8
	v_mov_b32_e32 v121, v8
	v_mov_b32_e32 v122, v8
	v_mov_b32_e32 v123, v8
	v_mov_b32_e32 v124, v8
	v_mov_b32_e32 v125, v8
	v_mov_b32_e32 v126, v8
	v_mov_b32_e32 v127, v8
	v_mov_b32_e32 v72, v8
	v_mov_b32_e32 v73, v8
	v_mov_b32_e32 v74, v8
	v_mov_b32_e32 v75, v8
	v_mov_b32_e32 v76, v8
	v_mov_b32_e32 v77, v8
	v_mov_b32_e32 v78, v8
	v_mov_b32_e32 v79, v8
	v_mov_b32_e32 v92, v8
	v_mov_b32_e32 v93, v8
	v_mov_b32_e32 v94, v8
	v_mov_b32_e32 v95, v8
	v_mov_b32_e32 v96, v8
	v_mov_b32_e32 v97, v8
	v_mov_b32_e32 v98, v8
	v_mov_b32_e32 v99, v8
	v_mov_b32_e32 v112, v8
	v_mov_b32_e32 v113, v8
	v_mov_b32_e32 v114, v8
	v_mov_b32_e32 v115, v8
	v_mov_b32_e32 v116, v8
	v_mov_b32_e32 v117, v8
	v_mov_b32_e32 v118, v8
	v_mov_b32_e32 v119, v8
	v_mov_b32_e32 v132, v8
	v_mov_b32_e32 v133, v8
	v_mov_b32_e32 v134, v8
	v_mov_b32_e32 v135, v8
	v_mov_b32_e32 v136, v8
	v_mov_b32_e32 v137, v8
	v_mov_b32_e32 v138, v8
	v_mov_b32_e32 v139, v8
	v_mov_b32_e32 v20, v8
	v_mov_b32_e32 v21, v8
	v_mov_b32_e32 v22, v8
	v_mov_b32_e32 v23, v8
	v_mov_b32_e32 v16, v8
	v_mov_b32_e32 v17, v8
	v_mov_b32_e32 v18, v8
	v_mov_b32_e32 v19, v8
	s_branch .LBB0_274

.LBB0_409:
	s_add_u32 s6, s46, 0xfffc0080
	s_addc_u32 s7, s47, -1
	s_add_i32 s8, 0, 0x10000
	s_cmp_eq_u32 s30, 12
	s_cselect_b32 s19, s12, s7
	s_cselect_b32 s18, s14, s6
	v_add_u32_e32 v146, s8, v143
	s_cselect_b32 s7, s15, s23
	s_cselect_b32 s6, s16, s17
	s_add_i32 s31, 0, 0x14000
	ds_read_b128 v[138:141], v146
	ds_read_b128 v[160:163], v146 offset:1024
	ds_read_b128 v[164:167], v146 offset:2048
	ds_read_b128 v[168:171], v146 offset:3072
	v_add_u32_e32 v146, s31, v143
	ds_read_b128 v[172:175], v146
	ds_read_b128 v[176:179], v146 offset:1024
	ds_read_b128 v[180:183], v146 offset:2048
	ds_read_b128 v[184:187], v146 offset:3072
	v_lshl_add_u64 v[146:147], s[46:47], 0, v[134:135]
	s_add_i32 m0, s25, 0xc000
	ds_read_b128 v[188:191], v158
	ds_read_b128 v[198:201], v158 offset:1024
	ds_read_b128 v[202:205], v158 offset:2048
	ds_read_b128 v[206:209], v158 offset:3072
	ds_read_b128 v[210:213], v158 offset:4096
	ds_read_b128 v[214:217], v158 offset:5120
	ds_read_b128 v[218:221], v158 offset:6144
	ds_read_b128 v[222:225], v158 offset:7168
	global_load_lds_dwordx4 v[146:147], off
	v_lshl_add_u64 v[146:147], s[46:47], 0, v[136:137]
	s_add_i32 m0, s25, 0xe000
	s_nop 0
	global_load_lds_dwordx4 v[146:147], off
	s_waitcnt vmcnt(8)
	s_waitcnt lgkmcnt(0)
	s_barrier
	s_setprio 1
	s_waitcnt lgkmcnt(0)
	v_mfma_f32_16x16x32_bf16 v[124:127], v[138:141], v[188:191], v[124:127]
	v_mfma_f32_16x16x32_bf16 v[120:123], v[164:167], v[188:191], v[120:123]
	v_mfma_f32_16x16x32_bf16 v[108:111], v[138:141], v[202:205], v[108:111]
	v_mfma_f32_16x16x32_bf16 v[104:107], v[164:167], v[202:205], v[104:107]
	v_mfma_f32_16x16x32_bf16 v[92:95], v[138:141], v[210:213], v[92:95]
	v_mfma_f32_16x16x32_bf16 v[88:91], v[164:167], v[210:213], v[88:91]
	v_mfma_f32_16x16x32_bf16 v[76:79], v[138:141], v[218:221], v[76:79]
	v_mfma_f32_16x16x32_bf16 v[72:75], v[164:167], v[218:221], v[72:75]
	v_mfma_f32_16x16x32_bf16 v[124:127], v[160:163], v[198:201], v[124:127]
	v_mfma_f32_16x16x32_bf16 v[120:123], v[168:171], v[198:201], v[120:123]
	v_mfma_f32_16x16x32_bf16 v[108:111], v[160:163], v[206:209], v[108:111]
	v_mfma_f32_16x16x32_bf16 v[104:107], v[168:171], v[206:209], v[104:107]
	v_mfma_f32_16x16x32_bf16 v[92:95], v[160:163], v[214:217], v[92:95]
	v_mfma_f32_16x16x32_bf16 v[88:91], v[168:171], v[214:217], v[88:91]
	v_mfma_f32_16x16x32_bf16 v[76:79], v[160:163], v[222:225], v[76:79]
	v_mfma_f32_16x16x32_bf16 v[72:75], v[168:171], v[222:225], v[72:75]
	s_setprio 0
	s_setprio 1
	v_mfma_f32_16x16x32_bf16 v[116:119], v[172:175], v[188:191], v[116:119]
	v_mfma_f32_16x16x32_bf16 v[112:115], v[180:183], v[188:191], v[112:115]
	v_mfma_f32_16x16x32_bf16 v[100:103], v[172:175], v[202:205], v[100:103]
	v_mfma_f32_16x16x32_bf16 v[96:99], v[180:183], v[202:205], v[96:99]
	v_mfma_f32_16x16x32_bf16 v[84:87], v[172:175], v[210:213], v[84:87]
	v_mfma_f32_16x16x32_bf16 v[80:83], v[180:183], v[210:213], v[80:83]
	v_mfma_f32_16x16x32_bf16 v[68:71], v[172:175], v[218:221], v[68:71]
	v_mfma_f32_16x16x32_bf16 v[64:67], v[180:183], v[218:221], v[64:67]
	v_mfma_f32_16x16x32_bf16 v[116:119], v[176:179], v[198:201], v[116:119]
	v_mfma_f32_16x16x32_bf16 v[112:115], v[184:187], v[198:201], v[112:115]
	v_mfma_f32_16x16x32_bf16 v[100:103], v[176:179], v[206:209], v[100:103]
	v_mfma_f32_16x16x32_bf16 v[96:99], v[184:187], v[206:209], v[96:99]
	v_mfma_f32_16x16x32_bf16 v[84:87], v[176:179], v[214:217], v[84:87]
	v_mfma_f32_16x16x32_bf16 v[80:83], v[184:187], v[214:217], v[80:83]
	v_mfma_f32_16x16x32_bf16 v[68:71], v[176:179], v[222:225], v[68:71]
	v_mfma_f32_16x16x32_bf16 v[64:67], v[184:187], v[222:225], v[64:67]
	s_setprio 0
	s_barrier
	s_add_i32 s8, s8, s0
	v_lshl_add_u64 v[146:147], s[6:7], 0, v[144:145]
	s_mov_b32 m0, s8
	ds_read_b128 v[188:191], v158 offset:16384
	ds_read_b128 v[198:201], v158 offset:17408
	ds_read_b128 v[202:205], v158 offset:18432
	ds_read_b128 v[206:209], v158 offset:19456
	ds_read_b128 v[210:213], v158 offset:20480
	ds_read_b128 v[214:217], v158 offset:21504
	ds_read_b128 v[218:221], v158 offset:22528
	ds_read_b128 v[222:225], v158 offset:23552
	global_load_lds_dwordx4 v[146:147], off
	s_add_i32 m0, s8, 0x2000
	s_add_u32 s8, s6, 0x40000
	v_lshl_add_u64 v[154:155], s[6:7], 0, v[128:129]
	s_addc_u32 s9, s7, 0
	s_add_i32 s31, s31, s0
	global_load_lds_dwordx4 v[154:155], off
	v_lshl_add_u64 v[226:227], s[8:9], 0, v[144:145]
	s_mov_b32 m0, s31
	v_lshl_add_u64 v[228:229], s[18:19], 0, v[130:131]
	global_load_lds_dwordx4 v[226:227], off
	v_lshl_add_u64 v[226:227], s[8:9], 0, v[128:129]
	s_add_i32 m0, s31, 0x2000
	s_nop 0
	global_load_lds_dwordx4 v[226:227], off
	v_lshl_add_u64 v[226:227], s[18:19], 0, v[132:133]
	s_mov_b32 m0, s25
	s_nop 0
	global_load_lds_dwordx4 v[226:227], off
	s_mov_b32 m0, s50
	s_nop 0
	global_load_lds_dwordx4 v[228:229], off
	s_waitcnt vmcnt(8)
	s_waitcnt lgkmcnt(0)
	s_barrier
	s_setprio 1
	s_waitcnt lgkmcnt(0)
	v_mfma_f32_16x16x32_bf16 v[60:63], v[138:141], v[188:191], v[60:63]
	v_mfma_f32_16x16x32_bf16 v[56:59], v[164:167], v[188:191], v[56:59]
	v_mfma_f32_16x16x32_bf16 v[52:55], v[138:141], v[202:205], v[52:55]
	v_mfma_f32_16x16x32_bf16 v[44:47], v[164:167], v[202:205], v[44:47]
	v_mfma_f32_16x16x32_bf16 v[32:35], v[138:141], v[210:213], v[32:35]
	v_mfma_f32_16x16x32_bf16 v[24:27], v[164:167], v[210:213], v[24:27]
	v_mfma_f32_16x16x32_bf16 v[20:23], v[138:141], v[218:221], v[20:23]
	v_mfma_f32_16x16x32_bf16 v[12:15], v[164:167], v[218:221], v[12:15]
	v_mfma_f32_16x16x32_bf16 v[60:63], v[160:163], v[198:201], v[60:63]
	v_mfma_f32_16x16x32_bf16 v[56:59], v[168:171], v[198:201], v[56:59]
	v_mfma_f32_16x16x32_bf16 v[52:55], v[160:163], v[206:209], v[52:55]
	v_mfma_f32_16x16x32_bf16 v[44:47], v[168:171], v[206:209], v[44:47]
	v_mfma_f32_16x16x32_bf16 v[32:35], v[160:163], v[214:217], v[32:35]
	v_mfma_f32_16x16x32_bf16 v[24:27], v[168:171], v[214:217], v[24:27]
	v_mfma_f32_16x16x32_bf16 v[20:23], v[160:163], v[222:225], v[20:23]
	v_mfma_f32_16x16x32_bf16 v[12:15], v[168:171], v[222:225], v[12:15]
	s_setprio 0
	s_setprio 1
	v_mfma_f32_16x16x32_bf16 v[48:51], v[172:175], v[188:191], v[48:51]
	v_mfma_f32_16x16x32_bf16 v[40:43], v[180:183], v[188:191], v[40:43]
	v_mfma_f32_16x16x32_bf16 v[36:39], v[172:175], v[202:205], v[36:39]
	v_mfma_f32_16x16x32_bf16 v[28:31], v[180:183], v[202:205], v[28:31]
	v_mfma_f32_16x16x32_bf16 v[16:19], v[172:175], v[210:213], v[16:19]
	v_mfma_f32_16x16x32_bf16 v[8:11], v[180:183], v[210:213], v[8:11]
	v_mfma_f32_16x16x32_bf16 v[4:7], v[172:175], v[218:221], v[4:7]
	v_mfma_f32_16x16x32_bf16 v[0:3], v[180:183], v[218:221], v[0:3]
	v_mfma_f32_16x16x32_bf16 v[48:51], v[176:179], v[198:201], v[48:51]
	v_mfma_f32_16x16x32_bf16 v[40:43], v[184:187], v[198:201], v[40:43]
	v_mfma_f32_16x16x32_bf16 v[36:39], v[176:179], v[206:209], v[36:39]
	v_mfma_f32_16x16x32_bf16 v[28:31], v[184:187], v[206:209], v[28:31]
	v_mfma_f32_16x16x32_bf16 v[16:19], v[176:179], v[214:217], v[16:19]
	v_mfma_f32_16x16x32_bf16 v[8:11], v[184:187], v[214:217], v[8:11]
	v_mfma_f32_16x16x32_bf16 v[4:7], v[176:179], v[222:225], v[4:7]
	v_mfma_f32_16x16x32_bf16 v[0:3], v[184:187], v[222:225], v[0:3]
	s_setprio 0
	s_barrier
	s_add_i32 s31, 0, 0x18000
	v_add_u32_e32 v159, s31, v143
	s_add_i32 s33, 0, 0x1c000
	ds_read_b128 v[138:141], v159
	ds_read_b128 v[160:163], v159 offset:1024
	ds_read_b128 v[164:167], v159 offset:2048
	ds_read_b128 v[168:171], v159 offset:3072
	v_add_u32_e32 v159, s33, v143
	ds_read_b128 v[172:175], v159
	ds_read_b128 v[176:179], v159 offset:1024
	ds_read_b128 v[180:183], v159 offset:2048
	ds_read_b128 v[184:187], v159 offset:3072
	s_add_u32 s8, s18, 0x40000
	s_addc_u32 s9, s19, 0
	s_mov_b32 m0, s51
	v_lshl_add_u64 v[230:231], s[8:9], 0, v[132:133]
	ds_read_b128 v[188:191], v158 offset:32768
	ds_read_b128 v[198:201], v158 offset:33792
	ds_read_b128 v[202:205], v158 offset:34816
	ds_read_b128 v[206:209], v158 offset:35840
	ds_read_b128 v[210:213], v158 offset:36864
	ds_read_b128 v[214:217], v158 offset:37888
	ds_read_b128 v[218:221], v158 offset:38912
	ds_read_b128 v[222:225], v158 offset:39936
	global_load_lds_dwordx4 v[230:231], off
	v_lshl_add_u64 v[230:231], s[8:9], 0, v[130:131]
	s_mov_b32 m0, s64
	s_nop 0
	global_load_lds_dwordx4 v[230:231], off
	s_waitcnt vmcnt(8)
	s_waitcnt lgkmcnt(0)
	s_barrier
	s_setprio 1
	s_waitcnt lgkmcnt(0)
	v_mfma_f32_16x16x32_bf16 v[124:127], v[138:141], v[188:191], v[124:127]
	v_mfma_f32_16x16x32_bf16 v[120:123], v[164:167], v[188:191], v[120:123]
	v_mfma_f32_16x16x32_bf16 v[108:111], v[138:141], v[202:205], v[108:111]
	v_mfma_f32_16x16x32_bf16 v[104:107], v[164:167], v[202:205], v[104:107]
	v_mfma_f32_16x16x32_bf16 v[92:95], v[138:141], v[210:213], v[92:95]
	v_mfma_f32_16x16x32_bf16 v[88:91], v[164:167], v[210:213], v[88:91]
	v_mfma_f32_16x16x32_bf16 v[76:79], v[138:141], v[218:221], v[76:79]
	v_mfma_f32_16x16x32_bf16 v[72:75], v[164:167], v[218:221], v[72:75]
	v_mfma_f32_16x16x32_bf16 v[124:127], v[160:163], v[198:201], v[124:127]
	v_mfma_f32_16x16x32_bf16 v[120:123], v[168:171], v[198:201], v[120:123]
	v_mfma_f32_16x16x32_bf16 v[108:111], v[160:163], v[206:209], v[108:111]
	v_mfma_f32_16x16x32_bf16 v[104:107], v[168:171], v[206:209], v[104:107]
	v_mfma_f32_16x16x32_bf16 v[92:95], v[160:163], v[214:217], v[92:95]
	v_mfma_f32_16x16x32_bf16 v[88:91], v[168:171], v[214:217], v[88:91]
	v_mfma_f32_16x16x32_bf16 v[76:79], v[160:163], v[222:225], v[76:79]
	v_mfma_f32_16x16x32_bf16 v[72:75], v[168:171], v[222:225], v[72:75]
	s_setprio 0
	s_setprio 1
	v_mfma_f32_16x16x32_bf16 v[116:119], v[172:175], v[188:191], v[116:119]
	v_mfma_f32_16x16x32_bf16 v[112:115], v[180:183], v[188:191], v[112:115]
	v_mfma_f32_16x16x32_bf16 v[100:103], v[172:175], v[202:205], v[100:103]
	v_mfma_f32_16x16x32_bf16 v[96:99], v[180:183], v[202:205], v[96:99]
	v_mfma_f32_16x16x32_bf16 v[84:87], v[172:175], v[210:213], v[84:87]
	v_mfma_f32_16x16x32_bf16 v[80:83], v[180:183], v[210:213], v[80:83]
	v_mfma_f32_16x16x32_bf16 v[68:71], v[172:175], v[218:221], v[68:71]
	v_mfma_f32_16x16x32_bf16 v[64:67], v[180:183], v[218:221], v[64:67]
	v_mfma_f32_16x16x32_bf16 v[116:119], v[176:179], v[198:201], v[116:119]
	v_mfma_f32_16x16x32_bf16 v[112:115], v[184:187], v[198:201], v[112:115]
	v_mfma_f32_16x16x32_bf16 v[100:103], v[176:179], v[206:209], v[100:103]
	v_mfma_f32_16x16x32_bf16 v[96:99], v[184:187], v[206:209], v[96:99]
	v_mfma_f32_16x16x32_bf16 v[84:87], v[176:179], v[214:217], v[84:87]
	v_mfma_f32_16x16x32_bf16 v[80:83], v[184:187], v[214:217], v[80:83]
	v_mfma_f32_16x16x32_bf16 v[68:71], v[176:179], v[222:225], v[68:71]
	v_mfma_f32_16x16x32_bf16 v[64:67], v[184:187], v[222:225], v[64:67]
	s_setprio 0
	s_barrier
	s_add_i32 s8, s31, s0
	v_lshl_add_u64 v[146:147], v[146:147], 0, s[70:71]
	s_mov_b32 m0, s8
	ds_read_b128 v[188:191], v158 offset:49152
	ds_read_b128 v[198:201], v158 offset:50176
	ds_read_b128 v[202:205], v158 offset:51200
	ds_read_b128 v[206:209], v158 offset:52224
	ds_read_b128 v[210:213], v158 offset:53248
	ds_read_b128 v[214:217], v158 offset:54272
	ds_read_b128 v[218:221], v158 offset:55296
	ds_read_b128 v[222:225], v158 offset:56320
	global_load_lds_dwordx4 v[146:147], off
	s_add_i32 m0, s8, 0x2000
	s_add_u32 s6, s6, 0x40080
	v_lshl_add_u64 v[146:147], v[154:155], 0, s[70:71]
	s_addc_u32 s7, s7, 0
	s_add_i32 s8, s33, s0
	global_load_lds_dwordx4 v[146:147], off
	v_lshl_add_u64 v[146:147], s[6:7], 0, v[144:145]
	s_mov_b32 m0, s8
	s_nop 0
	global_load_lds_dwordx4 v[146:147], off
	v_lshl_add_u64 v[146:147], s[6:7], 0, v[128:129]
	s_add_i32 m0, s8, 0x2000
	s_nop 0
	global_load_lds_dwordx4 v[146:147], off
	v_lshl_add_u64 v[146:147], v[226:227], 0, s[70:71]
	s_mov_b32 m0, s65
	s_nop 0
	global_load_lds_dwordx4 v[146:147], off
	v_lshl_add_u64 v[146:147], v[228:229], 0, s[70:71]
	s_mov_b32 m0, s68
	s_nop 0
	global_load_lds_dwordx4 v[146:147], off
	s_waitcnt vmcnt(8)
	s_waitcnt lgkmcnt(0)
	s_barrier
	s_setprio 1
	s_waitcnt lgkmcnt(0)
	v_mfma_f32_16x16x32_bf16 v[60:63], v[138:141], v[188:191], v[60:63]
	v_mfma_f32_16x16x32_bf16 v[56:59], v[164:167], v[188:191], v[56:59]
	v_mfma_f32_16x16x32_bf16 v[52:55], v[138:141], v[202:205], v[52:55]
	v_mfma_f32_16x16x32_bf16 v[44:47], v[164:167], v[202:205], v[44:47]
	v_mfma_f32_16x16x32_bf16 v[32:35], v[138:141], v[210:213], v[32:35]
	v_mfma_f32_16x16x32_bf16 v[24:27], v[164:167], v[210:213], v[24:27]
	v_mfma_f32_16x16x32_bf16 v[20:23], v[138:141], v[218:221], v[20:23]
	v_mfma_f32_16x16x32_bf16 v[12:15], v[164:167], v[218:221], v[12:15]
	v_mfma_f32_16x16x32_bf16 v[60:63], v[160:163], v[198:201], v[60:63]
	v_mfma_f32_16x16x32_bf16 v[56:59], v[168:171], v[198:201], v[56:59]
	v_mfma_f32_16x16x32_bf16 v[52:55], v[160:163], v[206:209], v[52:55]
	v_mfma_f32_16x16x32_bf16 v[44:47], v[168:171], v[206:209], v[44:47]
	v_mfma_f32_16x16x32_bf16 v[32:35], v[160:163], v[214:217], v[32:35]
	v_mfma_f32_16x16x32_bf16 v[24:27], v[168:171], v[214:217], v[24:27]
	v_mfma_f32_16x16x32_bf16 v[20:23], v[160:163], v[222:225], v[20:23]
	v_mfma_f32_16x16x32_bf16 v[12:15], v[168:171], v[222:225], v[12:15]
	s_setprio 0
	s_setprio 1
	v_mfma_f32_16x16x32_bf16 v[48:51], v[172:175], v[188:191], v[48:51]
	s_add_i32 s30, s30, 2
	s_add_u32 s46, s46, 0x100
	s_addc_u32 s47, s47, 0
	s_add_u32 s17, s17, 0x100
	s_addc_u32 s23, s23, 0
	s_cmp_gt_u32 s30, 13
	v_mfma_f32_16x16x32_bf16 v[40:43], v[180:183], v[188:191], v[40:43]
	v_mfma_f32_16x16x32_bf16 v[36:39], v[172:175], v[202:205], v[36:39]
	v_mfma_f32_16x16x32_bf16 v[28:31], v[180:183], v[202:205], v[28:31]
	v_mfma_f32_16x16x32_bf16 v[16:19], v[172:175], v[210:213], v[16:19]
	v_mfma_f32_16x16x32_bf16 v[8:11], v[180:183], v[210:213], v[8:11]
	v_mfma_f32_16x16x32_bf16 v[4:7], v[172:175], v[218:221], v[4:7]
	v_mfma_f32_16x16x32_bf16 v[0:3], v[180:183], v[218:221], v[0:3]
	v_mfma_f32_16x16x32_bf16 v[48:51], v[176:179], v[198:201], v[48:51]
	v_mfma_f32_16x16x32_bf16 v[40:43], v[184:187], v[198:201], v[40:43]
	v_mfma_f32_16x16x32_bf16 v[36:39], v[176:179], v[206:209], v[36:39]
	v_mfma_f32_16x16x32_bf16 v[28:31], v[184:187], v[206:209], v[28:31]
	v_mfma_f32_16x16x32_bf16 v[16:19], v[176:179], v[214:217], v[16:19]
	v_mfma_f32_16x16x32_bf16 v[8:11], v[184:187], v[214:217], v[8:11]
	v_mfma_f32_16x16x32_bf16 v[4:7], v[176:179], v[222:225], v[4:7]
	v_mfma_f32_16x16x32_bf16 v[0:3], v[184:187], v[222:225], v[0:3]
	s_setprio 0
	s_barrier
	s_cbranch_scc0 .LBB0_409
	s_and_b64 vcc, exec, s[4:5]
	s_movk_i32 s23, 0xf000
	s_mov_b32 s30, s52
	s_cbranch_vccz .LBB0_412
	s_barrier

.LBB0_618:
	s_add_i32 s31, 0, 0x10000
	s_add_i32 s16, 0, 0x14000
	v_add_u32_e32 v169, s31, v166
	v_add_u32_e32 v170, s16, v166
	ds_read_b128 v[172:175], v169
	ds_read_b128 v[176:179], v169 offset:1024
	ds_read_b128 v[180:183], v169 offset:2048
	ds_read_b128 v[184:187], v169 offset:3072
	ds_read_b128 v[188:191], v170
	ds_read_b128 v[198:201], v170 offset:1024
	ds_read_b128 v[202:205], v170 offset:2048
	ds_read_b128 v[206:209], v170 offset:3072
	v_lshl_add_u64 v[146:147], v[142:143], 0, s[46:47]
	s_add_i32 s33, s50, 0xc000
	v_lshl_add_u64 v[154:155], v[146:147], 0, s[28:29]
	s_mov_b32 m0, s33
	ds_read_b128 v[210:213], v168
	ds_read_b128 v[214:217], v168 offset:1024
	ds_read_b128 v[218:221], v168 offset:2048
	ds_read_b128 v[222:225], v168 offset:3072
	ds_read_b128 v[226:229], v168 offset:4096
	ds_read_b128 v[230:233], v168 offset:5120
	ds_read_b128 v[234:237], v168 offset:6144
	ds_read_b128 v[238:241], v168 offset:7168
	global_load_lds_dwordx4 v[154:155], off
	v_lshl_add_u64 v[154:155], v[156:157], 0, s[46:47]
	s_add_i32 s11, s50, 0xe000
	v_lshl_add_u64 v[242:243], v[154:155], 0, s[28:29]
	s_mov_b32 m0, s11
	s_nop 0
	global_load_lds_dwordx4 v[242:243], off
	s_waitcnt vmcnt(8)
	s_waitcnt lgkmcnt(0)
	s_barrier
	s_setprio 1
	s_waitcnt lgkmcnt(0)
	v_mfma_f32_16x16x32_bf16 v[136:139], v[172:175], v[210:213], v[136:139]
	v_mfma_f32_16x16x32_bf16 v[132:135], v[180:183], v[210:213], v[132:135]
	v_mfma_f32_16x16x32_bf16 v[116:119], v[172:175], v[218:221], v[116:119]
	v_mfma_f32_16x16x32_bf16 v[112:115], v[180:183], v[218:221], v[112:115]
	v_mfma_f32_16x16x32_bf16 v[96:99], v[172:175], v[226:229], v[96:99]
	v_mfma_f32_16x16x32_bf16 v[92:95], v[180:183], v[226:229], v[92:95]
	v_mfma_f32_16x16x32_bf16 v[76:79], v[172:175], v[234:237], v[76:79]
	v_mfma_f32_16x16x32_bf16 v[72:75], v[180:183], v[234:237], v[72:75]
	v_mfma_f32_16x16x32_bf16 v[136:139], v[176:179], v[214:217], v[136:139]
	v_mfma_f32_16x16x32_bf16 v[132:135], v[184:187], v[214:217], v[132:135]
	v_mfma_f32_16x16x32_bf16 v[116:119], v[176:179], v[222:225], v[116:119]
	v_mfma_f32_16x16x32_bf16 v[112:115], v[184:187], v[222:225], v[112:115]
	v_mfma_f32_16x16x32_bf16 v[96:99], v[176:179], v[230:233], v[96:99]
	v_mfma_f32_16x16x32_bf16 v[92:95], v[184:187], v[230:233], v[92:95]
	v_mfma_f32_16x16x32_bf16 v[76:79], v[176:179], v[238:241], v[76:79]
	v_mfma_f32_16x16x32_bf16 v[72:75], v[184:187], v[238:241], v[72:75]
	s_setprio 0
	s_setprio 1
	v_mfma_f32_16x16x32_bf16 v[124:127], v[188:191], v[210:213], v[124:127]
	v_mfma_f32_16x16x32_bf16 v[120:123], v[202:205], v[210:213], v[120:123]
	v_mfma_f32_16x16x32_bf16 v[104:107], v[188:191], v[218:221], v[104:107]
	v_mfma_f32_16x16x32_bf16 v[100:103], v[202:205], v[218:221], v[100:103]
	v_mfma_f32_16x16x32_bf16 v[84:87], v[188:191], v[226:229], v[84:87]
	v_mfma_f32_16x16x32_bf16 v[80:83], v[202:205], v[226:229], v[80:83]
	v_mfma_f32_16x16x32_bf16 v[68:71], v[188:191], v[234:237], v[68:71]
	v_mfma_f32_16x16x32_bf16 v[64:67], v[202:205], v[234:237], v[64:67]
	v_mfma_f32_16x16x32_bf16 v[124:127], v[198:201], v[214:217], v[124:127]
	v_mfma_f32_16x16x32_bf16 v[120:123], v[206:209], v[214:217], v[120:123]
	v_mfma_f32_16x16x32_bf16 v[104:107], v[198:201], v[222:225], v[104:107]
	v_mfma_f32_16x16x32_bf16 v[100:103], v[206:209], v[222:225], v[100:103]
	v_mfma_f32_16x16x32_bf16 v[84:87], v[198:201], v[230:233], v[84:87]
	v_mfma_f32_16x16x32_bf16 v[80:83], v[206:209], v[230:233], v[80:83]
	v_mfma_f32_16x16x32_bf16 v[68:71], v[198:201], v[238:241], v[68:71]
	v_mfma_f32_16x16x32_bf16 v[64:67], v[206:209], v[238:241], v[64:67]
	s_setprio 0
	s_barrier
	v_lshl_add_u64 v[246:247], v[158:159], 0, s[46:47]
	s_add_i32 s31, s31, s49
	v_lshl_add_u64 v[242:243], v[246:247], 0, s[96:97]
	s_mov_b32 m0, s31
	v_lshl_add_u64 v[248:249], v[160:161], 0, s[46:47]
	s_add_i32 s14, s31, 0x2000
	ds_read_b128 v[210:213], v168 offset:16384
	ds_read_b128 v[214:217], v168 offset:17408
	ds_read_b128 v[218:221], v168 offset:18432
	ds_read_b128 v[222:225], v168 offset:19456
	ds_read_b128 v[226:229], v168 offset:20480
	ds_read_b128 v[230:233], v168 offset:21504
	ds_read_b128 v[234:237], v168 offset:22528
	ds_read_b128 v[238:241], v168 offset:23552
	global_load_lds_dwordx4 v[242:243], off
	v_lshl_add_u64 v[242:243], v[248:249], 0, s[96:97]
	s_mov_b32 m0, s14
	s_add_i32 s16, s16, s49
	global_load_lds_dwordx4 v[242:243], off
	v_lshl_add_u64 v[242:243], v[246:247], 0, s[74:75]
	s_mov_b32 m0, s16
	s_add_i32 s23, s16, 0x2000
	global_load_lds_dwordx4 v[242:243], off
	v_lshl_add_u64 v[242:243], v[248:249], 0, s[74:75]
	s_mov_b32 m0, s23
	s_nop 0
	global_load_lds_dwordx4 v[242:243], off
	v_lshl_add_u64 v[242:243], v[146:147], 0, s[96:97]
	s_mov_b32 m0, s50
	s_nop 0
	global_load_lds_dwordx4 v[242:243], off
	v_lshl_add_u64 v[242:243], v[154:155], 0, s[96:97]
	s_mov_b32 m0, s51
	s_nop 0
	global_load_lds_dwordx4 v[242:243], off
	s_waitcnt vmcnt(8)
	s_waitcnt lgkmcnt(0)
	s_barrier
	s_setprio 1
	s_waitcnt lgkmcnt(0)
	v_mfma_f32_16x16x32_bf16 v[60:63], v[172:175], v[210:213], v[60:63]
	v_mfma_f32_16x16x32_bf16 v[56:59], v[180:183], v[210:213], v[56:59]
	v_mfma_f32_16x16x32_bf16 v[44:47], v[172:175], v[218:221], v[44:47]
	v_mfma_f32_16x16x32_bf16 v[40:43], v[180:183], v[218:221], v[40:43]
	v_mfma_f32_16x16x32_bf16 v[28:31], v[172:175], v[226:229], v[28:31]
	v_mfma_f32_16x16x32_bf16 v[24:27], v[180:183], v[226:229], v[24:27]
	v_mfma_f32_16x16x32_bf16 v[4:7], v[172:175], v[234:237], v[4:7]
	v_mfma_f32_16x16x32_bf16 v[0:3], v[180:183], v[234:237], v[0:3]
	v_mfma_f32_16x16x32_bf16 v[60:63], v[176:179], v[214:217], v[60:63]
	v_mfma_f32_16x16x32_bf16 v[56:59], v[184:187], v[214:217], v[56:59]
	v_mfma_f32_16x16x32_bf16 v[44:47], v[176:179], v[222:225], v[44:47]
	v_mfma_f32_16x16x32_bf16 v[40:43], v[184:187], v[222:225], v[40:43]
	v_mfma_f32_16x16x32_bf16 v[28:31], v[176:179], v[230:233], v[28:31]
	v_mfma_f32_16x16x32_bf16 v[24:27], v[184:187], v[230:233], v[24:27]
	v_mfma_f32_16x16x32_bf16 v[4:7], v[176:179], v[238:241], v[4:7]
	v_mfma_f32_16x16x32_bf16 v[0:3], v[184:187], v[238:241], v[0:3]
	s_setprio 0
	s_setprio 1
	v_mfma_f32_16x16x32_bf16 v[52:55], v[188:191], v[210:213], v[52:55]
	v_mfma_f32_16x16x32_bf16 v[48:51], v[202:205], v[210:213], v[48:51]
	v_mfma_f32_16x16x32_bf16 v[36:39], v[188:191], v[218:221], v[36:39]
	v_mfma_f32_16x16x32_bf16 v[32:35], v[202:205], v[218:221], v[32:35]
	v_mfma_f32_16x16x32_bf16 v[12:15], v[188:191], v[226:229], v[12:15]
	v_mfma_f32_16x16x32_bf16 v[8:11], v[202:205], v[226:229], v[8:11]
	v_mfma_f32_16x16x32_bf16 v[20:23], v[188:191], v[234:237], v[20:23]
	v_mfma_f32_16x16x32_bf16 v[16:19], v[202:205], v[234:237], v[16:19]
	v_mfma_f32_16x16x32_bf16 v[52:55], v[198:201], v[214:217], v[52:55]
	v_mfma_f32_16x16x32_bf16 v[48:51], v[206:209], v[214:217], v[48:51]
	v_mfma_f32_16x16x32_bf16 v[36:39], v[198:201], v[222:225], v[36:39]
	v_mfma_f32_16x16x32_bf16 v[32:35], v[206:209], v[222:225], v[32:35]
	v_mfma_f32_16x16x32_bf16 v[12:15], v[198:201], v[230:233], v[12:15]
	v_mfma_f32_16x16x32_bf16 v[8:11], v[206:209], v[230:233], v[8:11]
	v_mfma_f32_16x16x32_bf16 v[20:23], v[198:201], v[238:241], v[20:23]
	v_mfma_f32_16x16x32_bf16 v[16:19], v[206:209], v[238:241], v[16:19]
	s_setprio 0
	s_barrier
	s_add_i32 s54, 0, 0x18000
	s_add_i32 s15, 0, 0x1c000
	v_add_u32_e32 v171, s54, v166
	v_add_u32_e32 v172, s15, v166
	ds_read_b128 v[174:177], v171
	ds_read_b128 v[178:181], v171 offset:1024
	ds_read_b128 v[182:185], v171 offset:2048
	ds_read_b128 v[186:189], v171 offset:3072
	ds_read_b128 v[198:201], v172
	ds_read_b128 v[202:205], v172 offset:1024
	ds_read_b128 v[206:209], v172 offset:2048
	ds_read_b128 v[210:213], v172 offset:3072
	s_mov_b32 m0, s64
	v_lshl_add_u64 v[190:191], v[146:147], 0, s[34:35]
	ds_read_b128 v[214:217], v168 offset:32768
	ds_read_b128 v[218:221], v168 offset:33792
	ds_read_b128 v[222:225], v168 offset:34816
	ds_read_b128 v[226:229], v168 offset:35840
	ds_read_b128 v[230:233], v168 offset:36864
	ds_read_b128 v[234:237], v168 offset:37888
	ds_read_b128 v[238:241], v168 offset:38912
	ds_read_b128 v[242:245], v168 offset:39936
	global_load_lds_dwordx4 v[190:191], off
	v_lshl_add_u64 v[190:191], v[154:155], 0, s[34:35]
	s_mov_b32 m0, s65
	s_nop 0
	global_load_lds_dwordx4 v[190:191], off
	s_waitcnt vmcnt(8)
	s_waitcnt lgkmcnt(0)
	s_barrier
	s_setprio 1
	s_waitcnt lgkmcnt(0)
	v_mfma_f32_16x16x32_bf16 v[136:139], v[174:177], v[214:217], v[136:139]
	v_mfma_f32_16x16x32_bf16 v[132:135], v[182:185], v[214:217], v[132:135]
	v_mfma_f32_16x16x32_bf16 v[116:119], v[174:177], v[222:225], v[116:119]
	v_mfma_f32_16x16x32_bf16 v[112:115], v[182:185], v[222:225], v[112:115]
	v_mfma_f32_16x16x32_bf16 v[96:99], v[174:177], v[230:233], v[96:99]
	v_mfma_f32_16x16x32_bf16 v[92:95], v[182:185], v[230:233], v[92:95]
	v_mfma_f32_16x16x32_bf16 v[76:79], v[174:177], v[238:241], v[76:79]
	v_mfma_f32_16x16x32_bf16 v[72:75], v[182:185], v[238:241], v[72:75]
	v_mfma_f32_16x16x32_bf16 v[136:139], v[178:181], v[218:221], v[136:139]
	v_mfma_f32_16x16x32_bf16 v[132:135], v[186:189], v[218:221], v[132:135]
	v_mfma_f32_16x16x32_bf16 v[116:119], v[178:181], v[226:229], v[116:119]
	v_mfma_f32_16x16x32_bf16 v[112:115], v[186:189], v[226:229], v[112:115]
	v_mfma_f32_16x16x32_bf16 v[96:99], v[178:181], v[234:237], v[96:99]
	v_mfma_f32_16x16x32_bf16 v[92:95], v[186:189], v[234:237], v[92:95]
	v_mfma_f32_16x16x32_bf16 v[76:79], v[178:181], v[242:245], v[76:79]
	v_mfma_f32_16x16x32_bf16 v[72:75], v[186:189], v[242:245], v[72:75]
	s_setprio 0
	s_setprio 1
	v_mfma_f32_16x16x32_bf16 v[124:127], v[198:201], v[214:217], v[124:127]
	v_mfma_f32_16x16x32_bf16 v[120:123], v[206:209], v[214:217], v[120:123]
	v_mfma_f32_16x16x32_bf16 v[104:107], v[198:201], v[222:225], v[104:107]
	v_mfma_f32_16x16x32_bf16 v[100:103], v[206:209], v[222:225], v[100:103]
	v_mfma_f32_16x16x32_bf16 v[84:87], v[198:201], v[230:233], v[84:87]
	v_mfma_f32_16x16x32_bf16 v[80:83], v[206:209], v[230:233], v[80:83]
	v_mfma_f32_16x16x32_bf16 v[68:71], v[198:201], v[238:241], v[68:71]
	v_mfma_f32_16x16x32_bf16 v[64:67], v[206:209], v[238:241], v[64:67]
	v_mfma_f32_16x16x32_bf16 v[124:127], v[202:205], v[218:221], v[124:127]
	v_mfma_f32_16x16x32_bf16 v[120:123], v[210:213], v[218:221], v[120:123]
	v_mfma_f32_16x16x32_bf16 v[104:107], v[202:205], v[226:229], v[104:107]
	v_mfma_f32_16x16x32_bf16 v[100:103], v[210:213], v[226:229], v[100:103]
	v_mfma_f32_16x16x32_bf16 v[84:87], v[202:205], v[234:237], v[84:87]
	v_mfma_f32_16x16x32_bf16 v[80:83], v[210:213], v[234:237], v[80:83]
	v_mfma_f32_16x16x32_bf16 v[68:71], v[202:205], v[242:245], v[68:71]
	v_mfma_f32_16x16x32_bf16 v[64:67], v[210:213], v[242:245], v[64:67]
	s_setprio 0
	s_barrier
	s_add_i32 s54, s54, s49
	v_lshl_add_u64 v[190:191], v[246:247], 0, s[58:59]
	s_mov_b32 m0, s54
	s_add_i32 s30, s54, 0x2000
	ds_read_b128 v[214:217], v168 offset:49152
	ds_read_b128 v[218:221], v168 offset:50176
	ds_read_b128 v[222:225], v168 offset:51200
	ds_read_b128 v[226:229], v168 offset:52224
	ds_read_b128 v[230:233], v168 offset:53248
	ds_read_b128 v[234:237], v168 offset:54272
	ds_read_b128 v[238:241], v168 offset:55296
	ds_read_b128 v[242:245], v168 offset:56320
	global_load_lds_dwordx4 v[190:191], off
	v_lshl_add_u64 v[190:191], v[248:249], 0, s[58:59]
	s_mov_b32 m0, s30
	s_add_i32 s15, s15, s49
	global_load_lds_dwordx4 v[190:191], off
	v_lshl_add_u64 v[190:191], v[246:247], 0, s[82:83]
	s_mov_b32 m0, s15
	s_add_i32 s17, s15, 0x2000
	global_load_lds_dwordx4 v[190:191], off
	v_lshl_add_u64 v[190:191], v[248:249], 0, s[82:83]
	s_mov_b32 m0, s17
	v_lshl_add_u64 v[146:147], v[146:147], 0, s[58:59]
	global_load_lds_dwordx4 v[190:191], off
	s_mov_b32 m0, s68
	s_nop 0
	global_load_lds_dwordx4 v[146:147], off
	v_lshl_add_u64 v[146:147], v[154:155], 0, s[58:59]
	s_mov_b32 m0, s69
	s_nop 0
	global_load_lds_dwordx4 v[146:147], off
	s_waitcnt vmcnt(8)
	s_waitcnt lgkmcnt(0)
	s_barrier
	s_setprio 1
	s_waitcnt lgkmcnt(0)
	v_mfma_f32_16x16x32_bf16 v[60:63], v[174:177], v[214:217], v[60:63]
	v_mfma_f32_16x16x32_bf16 v[56:59], v[182:185], v[214:217], v[56:59]
	v_mfma_f32_16x16x32_bf16 v[44:47], v[174:177], v[222:225], v[44:47]
	v_mfma_f32_16x16x32_bf16 v[40:43], v[182:185], v[222:225], v[40:43]
	v_mfma_f32_16x16x32_bf16 v[28:31], v[174:177], v[230:233], v[28:31]
	v_mfma_f32_16x16x32_bf16 v[24:27], v[182:185], v[230:233], v[24:27]
	v_mfma_f32_16x16x32_bf16 v[4:7], v[174:177], v[238:241], v[4:7]
	v_mfma_f32_16x16x32_bf16 v[0:3], v[182:185], v[238:241], v[0:3]
	v_mfma_f32_16x16x32_bf16 v[60:63], v[178:181], v[218:221], v[60:63]
	v_mfma_f32_16x16x32_bf16 v[56:59], v[186:189], v[218:221], v[56:59]
	v_mfma_f32_16x16x32_bf16 v[44:47], v[178:181], v[226:229], v[44:47]
	v_mfma_f32_16x16x32_bf16 v[40:43], v[186:189], v[226:229], v[40:43]
	v_mfma_f32_16x16x32_bf16 v[28:31], v[178:181], v[234:237], v[28:31]
	v_mfma_f32_16x16x32_bf16 v[24:27], v[186:189], v[234:237], v[24:27]
	v_mfma_f32_16x16x32_bf16 v[4:7], v[178:181], v[242:245], v[4:7]
	v_mfma_f32_16x16x32_bf16 v[0:3], v[186:189], v[242:245], v[0:3]
	s_setprio 0
	s_setprio 1
	v_mfma_f32_16x16x32_bf16 v[52:55], v[198:201], v[214:217], v[52:55]
	s_add_i32 s3, s3, 2
	s_add_u32 s46, s46, 0x100
	s_addc_u32 s47, s47, 0
	s_cmp_gt_u32 s3, 11
	v_mfma_f32_16x16x32_bf16 v[48:51], v[206:209], v[214:217], v[48:51]
	v_mfma_f32_16x16x32_bf16 v[36:39], v[198:201], v[222:225], v[36:39]
	v_mfma_f32_16x16x32_bf16 v[32:35], v[206:209], v[222:225], v[32:35]
	v_mfma_f32_16x16x32_bf16 v[12:15], v[198:201], v[230:233], v[12:15]
	v_mfma_f32_16x16x32_bf16 v[8:11], v[206:209], v[230:233], v[8:11]
	v_mfma_f32_16x16x32_bf16 v[20:23], v[198:201], v[238:241], v[20:23]
	v_mfma_f32_16x16x32_bf16 v[16:19], v[206:209], v[238:241], v[16:19]
	v_mfma_f32_16x16x32_bf16 v[52:55], v[202:205], v[218:221], v[52:55]
	v_mfma_f32_16x16x32_bf16 v[48:51], v[210:213], v[218:221], v[48:51]
	v_mfma_f32_16x16x32_bf16 v[36:39], v[202:205], v[226:229], v[36:39]
	v_mfma_f32_16x16x32_bf16 v[32:35], v[210:213], v[226:229], v[32:35]
	v_mfma_f32_16x16x32_bf16 v[12:15], v[202:205], v[234:237], v[12:15]
	v_mfma_f32_16x16x32_bf16 v[8:11], v[210:213], v[234:237], v[8:11]
	v_mfma_f32_16x16x32_bf16 v[20:23], v[202:205], v[242:245], v[20:23]
	v_mfma_f32_16x16x32_bf16 v[16:19], v[210:213], v[242:245], v[16:19]
	s_setprio 0
	s_barrier
	s_cbranch_scc0 .LBB0_618
	ds_read_b128 v[156:159], v169
	ds_read_b128 v[174:177], v169 offset:1024
	ds_read_b128 v[178:181], v169 offset:2048
	ds_read_b128 v[182:185], v169 offset:3072
	ds_read_b128 v[186:189], v170
	ds_read_b128 v[198:201], v170 offset:1024
	ds_read_b128 v[202:205], v170 offset:2048
	ds_read_b128 v[206:209], v170 offset:3072
	s_ashr_i32 s13, s12, 31
	s_ashr_i32 s3, s2, 31
	s_lshl_b64 s[6:7], s[2:3], 9
	s_lshl_b64 s[8:9], s[12:13], 19
	s_add_u32 s3, s60, s8
	s_addc_u32 s8, s61, s9
	s_add_u32 s6, s3, s6
	s_addc_u32 s7, s8, s7
	s_add_u32 s8, s40, 0xc0780
	s_addc_u32 s9, s41, 0
	s_mov_b32 m0, s33
	v_lshl_add_u64 v[142:143], s[8:9], 0, v[144:145]
	ds_read_b128 v[210:213], v168
	ds_read_b128 v[214:217], v168 offset:1024
	ds_read_b128 v[218:221], v168 offset:2048
	ds_read_b128 v[222:225], v168 offset:3072
	ds_read_b128 v[226:229], v168 offset:4096
	ds_read_b128 v[230:233], v168 offset:5120
	ds_read_b128 v[234:237], v168 offset:6144
	ds_read_b128 v[238:241], v168 offset:7168
	global_load_lds_dwordx4 v[142:143], off
	v_lshl_add_u64 v[142:143], s[8:9], 0, v[88:89]
	s_mov_b32 m0, s11
	s_nop 0
	global_load_lds_dwordx4 v[142:143], off
	s_waitcnt vmcnt(8)
	s_waitcnt lgkmcnt(0)
	s_barrier
	s_setprio 1
	s_waitcnt lgkmcnt(0)
	v_mfma_f32_16x16x32_bf16 v[136:139], v[156:159], v[210:213], v[136:139]
	v_mfma_f32_16x16x32_bf16 v[132:135], v[178:181], v[210:213], v[132:135]
	v_mfma_f32_16x16x32_bf16 v[116:119], v[156:159], v[218:221], v[116:119]
	v_mfma_f32_16x16x32_bf16 v[112:115], v[178:181], v[218:221], v[112:115]
	v_mfma_f32_16x16x32_bf16 v[96:99], v[156:159], v[226:229], v[96:99]
	v_mfma_f32_16x16x32_bf16 v[92:95], v[178:181], v[226:229], v[92:95]
	v_mfma_f32_16x16x32_bf16 v[76:79], v[156:159], v[234:237], v[76:79]
	v_mfma_f32_16x16x32_bf16 v[72:75], v[178:181], v[234:237], v[72:75]
	v_mfma_f32_16x16x32_bf16 v[136:139], v[174:177], v[214:217], v[136:139]
	v_mfma_f32_16x16x32_bf16 v[132:135], v[182:185], v[214:217], v[132:135]
	v_mfma_f32_16x16x32_bf16 v[116:119], v[174:177], v[222:225], v[116:119]
	v_mfma_f32_16x16x32_bf16 v[112:115], v[182:185], v[222:225], v[112:115]
	v_mfma_f32_16x16x32_bf16 v[96:99], v[174:177], v[230:233], v[96:99]
	v_mfma_f32_16x16x32_bf16 v[92:95], v[182:185], v[230:233], v[92:95]
	v_mfma_f32_16x16x32_bf16 v[76:79], v[174:177], v[238:241], v[76:79]
	v_mfma_f32_16x16x32_bf16 v[72:75], v[182:185], v[238:241], v[72:75]
	s_setprio 0
	s_setprio 1
	v_mfma_f32_16x16x32_bf16 v[124:127], v[186:189], v[210:213], v[124:127]
	v_mfma_f32_16x16x32_bf16 v[120:123], v[202:205], v[210:213], v[120:123]
	v_mfma_f32_16x16x32_bf16 v[104:107], v[186:189], v[218:221], v[104:107]
	v_mfma_f32_16x16x32_bf16 v[100:103], v[202:205], v[218:221], v[100:103]
	v_mfma_f32_16x16x32_bf16 v[84:87], v[186:189], v[226:229], v[84:87]
	v_mfma_f32_16x16x32_bf16 v[80:83], v[202:205], v[226:229], v[80:83]
	v_mfma_f32_16x16x32_bf16 v[68:71], v[186:189], v[234:237], v[68:71]
	v_mfma_f32_16x16x32_bf16 v[64:67], v[202:205], v[234:237], v[64:67]
	v_mfma_f32_16x16x32_bf16 v[124:127], v[198:201], v[214:217], v[124:127]
	v_mfma_f32_16x16x32_bf16 v[120:123], v[206:209], v[214:217], v[120:123]
	v_mfma_f32_16x16x32_bf16 v[104:107], v[198:201], v[222:225], v[104:107]
	v_mfma_f32_16x16x32_bf16 v[100:103], v[206:209], v[222:225], v[100:103]
	v_mfma_f32_16x16x32_bf16 v[84:87], v[198:201], v[230:233], v[84:87]
	v_mfma_f32_16x16x32_bf16 v[80:83], v[206:209], v[230:233], v[80:83]
	v_mfma_f32_16x16x32_bf16 v[68:71], v[198:201], v[238:241], v[68:71]
	v_mfma_f32_16x16x32_bf16 v[64:67], v[206:209], v[238:241], v[64:67]
	s_setprio 0
	s_barrier
	s_mov_b32 m0, s31
	v_lshl_add_u64 v[142:143], s[6:7], 0, v[90:91]
	ds_read_b128 v[210:213], v168 offset:16384
	ds_read_b128 v[214:217], v168 offset:17408
	ds_read_b128 v[218:221], v168 offset:18432
	ds_read_b128 v[222:225], v168 offset:19456
	ds_read_b128 v[226:229], v168 offset:20480
	ds_read_b128 v[230:233], v168 offset:21504
	ds_read_b128 v[234:237], v168 offset:22528
	ds_read_b128 v[238:241], v168 offset:23552
	global_load_lds_dwordx4 v[142:143], off
	v_lshl_add_u64 v[146:147], s[6:7], 0, v[108:109]
	s_mov_b32 m0, s14
	v_lshl_add_u64 v[154:155], v[142:143], 0, s[70:71]
	global_load_lds_dwordx4 v[146:147], off
	s_mov_b32 m0, s16
	s_nop 0
	global_load_lds_dwordx4 v[154:155], off
	v_lshl_add_u64 v[154:155], v[146:147], 0, s[70:71]
	s_mov_b32 m0, s23
	s_nop 0
	global_load_lds_dwordx4 v[154:155], off
	v_lshl_add_u64 v[154:155], v[142:143], 0, s[96:97]
	s_mov_b32 m0, s50
	s_nop 0
	global_load_lds_dwordx4 v[154:155], off
	v_lshl_add_u64 v[154:155], v[146:147], 0, s[96:97]
	s_mov_b32 m0, s51
	s_nop 0
	global_load_lds_dwordx4 v[154:155], off
	s_waitcnt vmcnt(8)
	s_waitcnt lgkmcnt(0)
	s_barrier
	s_setprio 1
	s_waitcnt lgkmcnt(0)
	v_mfma_f32_16x16x32_bf16 v[60:63], v[156:159], v[210:213], v[60:63]
	v_mfma_f32_16x16x32_bf16 v[56:59], v[178:181], v[210:213], v[56:59]
	v_mfma_f32_16x16x32_bf16 v[44:47], v[156:159], v[218:221], v[44:47]
	v_mfma_f32_16x16x32_bf16 v[40:43], v[178:181], v[218:221], v[40:43]
	v_mfma_f32_16x16x32_bf16 v[28:31], v[156:159], v[226:229], v[28:31]
	v_mfma_f32_16x16x32_bf16 v[24:27], v[178:181], v[226:229], v[24:27]
	v_mfma_f32_16x16x32_bf16 v[4:7], v[156:159], v[234:237], v[4:7]
	v_mfma_f32_16x16x32_bf16 v[0:3], v[178:181], v[234:237], v[0:3]
	v_mfma_f32_16x16x32_bf16 v[60:63], v[174:177], v[214:217], v[60:63]
	v_mfma_f32_16x16x32_bf16 v[56:59], v[182:185], v[214:217], v[56:59]
	v_mfma_f32_16x16x32_bf16 v[44:47], v[174:177], v[222:225], v[44:47]
	v_mfma_f32_16x16x32_bf16 v[40:43], v[182:185], v[222:225], v[40:43]
	v_mfma_f32_16x16x32_bf16 v[28:31], v[174:177], v[230:233], v[28:31]
	v_mfma_f32_16x16x32_bf16 v[24:27], v[182:185], v[230:233], v[24:27]
	v_mfma_f32_16x16x32_bf16 v[4:7], v[174:177], v[238:241], v[4:7]
	v_mfma_f32_16x16x32_bf16 v[0:3], v[182:185], v[238:241], v[0:3]
	s_setprio 0
	s_setprio 1
	v_mfma_f32_16x16x32_bf16 v[52:55], v[186:189], v[210:213], v[52:55]
	v_mfma_f32_16x16x32_bf16 v[48:51], v[202:205], v[210:213], v[48:51]
	v_mfma_f32_16x16x32_bf16 v[36:39], v[186:189], v[218:221], v[36:39]
	v_mfma_f32_16x16x32_bf16 v[32:35], v[202:205], v[218:221], v[32:35]
	v_mfma_f32_16x16x32_bf16 v[12:15], v[186:189], v[226:229], v[12:15]
	v_mfma_f32_16x16x32_bf16 v[8:11], v[202:205], v[226:229], v[8:11]
	v_mfma_f32_16x16x32_bf16 v[20:23], v[186:189], v[234:237], v[20:23]
	v_mfma_f32_16x16x32_bf16 v[16:19], v[202:205], v[234:237], v[16:19]
	v_mfma_f32_16x16x32_bf16 v[52:55], v[198:201], v[214:217], v[52:55]
	v_mfma_f32_16x16x32_bf16 v[48:51], v[206:209], v[214:217], v[48:51]
	v_mfma_f32_16x16x32_bf16 v[36:39], v[198:201], v[222:225], v[36:39]
	v_mfma_f32_16x16x32_bf16 v[32:35], v[206:209], v[222:225], v[32:35]
	v_mfma_f32_16x16x32_bf16 v[12:15], v[198:201], v[230:233], v[12:15]
	v_mfma_f32_16x16x32_bf16 v[8:11], v[206:209], v[230:233], v[8:11]
	v_mfma_f32_16x16x32_bf16 v[20:23], v[198:201], v[238:241], v[20:23]
	v_mfma_f32_16x16x32_bf16 v[16:19], v[206:209], v[238:241], v[16:19]
	s_setprio 0
	s_barrier
	ds_read_b128 v[156:159], v171
	ds_read_b128 v[174:177], v171 offset:1024
	ds_read_b128 v[178:181], v171 offset:2048
	ds_read_b128 v[182:185], v171 offset:3072
	ds_read_b128 v[186:189], v172
	ds_read_b128 v[198:201], v172 offset:1024
	ds_read_b128 v[202:205], v172 offset:2048
	ds_read_b128 v[170:173], v172 offset:3072
	s_mov_b32 m0, s64
	v_lshl_add_u64 v[142:143], v[142:143], 0, s[58:59]
	ds_read_b128 v[206:209], v168 offset:32768
	ds_read_b128 v[210:213], v168 offset:33792
	ds_read_b128 v[214:217], v168 offset:34816
	ds_read_b128 v[218:221], v168 offset:35840
	ds_read_b128 v[222:225], v168 offset:36864
	ds_read_b128 v[226:229], v168 offset:37888
	ds_read_b128 v[230:233], v168 offset:38912
	ds_read_b128 v[234:237], v168 offset:39936
	global_load_lds_dwordx4 v[142:143], off
	v_lshl_add_u64 v[142:143], v[146:147], 0, s[58:59]
	s_mov_b32 m0, s65
	s_nop 0
	global_load_lds_dwordx4 v[142:143], off
	s_waitcnt vmcnt(8)
	s_waitcnt lgkmcnt(0)
	s_barrier
	s_setprio 1
	s_waitcnt lgkmcnt(0)
	v_mfma_f32_16x16x32_bf16 v[136:139], v[156:159], v[206:209], v[136:139]
	v_mfma_f32_16x16x32_bf16 v[132:135], v[178:181], v[206:209], v[132:135]
	v_mfma_f32_16x16x32_bf16 v[116:119], v[156:159], v[214:217], v[116:119]
	v_mfma_f32_16x16x32_bf16 v[112:115], v[178:181], v[214:217], v[112:115]
	v_mfma_f32_16x16x32_bf16 v[96:99], v[156:159], v[222:225], v[96:99]
	v_mfma_f32_16x16x32_bf16 v[92:95], v[178:181], v[222:225], v[92:95]
	v_mfma_f32_16x16x32_bf16 v[76:79], v[156:159], v[230:233], v[76:79]
	v_mfma_f32_16x16x32_bf16 v[72:75], v[178:181], v[230:233], v[72:75]
	v_mfma_f32_16x16x32_bf16 v[136:139], v[174:177], v[210:213], v[136:139]
	v_mfma_f32_16x16x32_bf16 v[132:135], v[182:185], v[210:213], v[132:135]
	v_mfma_f32_16x16x32_bf16 v[116:119], v[174:177], v[218:221], v[116:119]
	v_mfma_f32_16x16x32_bf16 v[112:115], v[182:185], v[218:221], v[112:115]
	v_mfma_f32_16x16x32_bf16 v[96:99], v[174:177], v[226:229], v[96:99]
	v_mfma_f32_16x16x32_bf16 v[92:95], v[182:185], v[226:229], v[92:95]
	v_mfma_f32_16x16x32_bf16 v[76:79], v[174:177], v[234:237], v[76:79]
	v_mfma_f32_16x16x32_bf16 v[72:75], v[182:185], v[234:237], v[72:75]
	s_setprio 0
	s_setprio 1
	v_mfma_f32_16x16x32_bf16 v[124:127], v[186:189], v[206:209], v[124:127]
	v_mfma_f32_16x16x32_bf16 v[120:123], v[202:205], v[206:209], v[120:123]
	v_mfma_f32_16x16x32_bf16 v[104:107], v[186:189], v[214:217], v[104:107]
	v_mfma_f32_16x16x32_bf16 v[100:103], v[202:205], v[214:217], v[100:103]
	v_mfma_f32_16x16x32_bf16 v[84:87], v[186:189], v[222:225], v[84:87]
	v_mfma_f32_16x16x32_bf16 v[80:83], v[202:205], v[222:225], v[80:83]
	v_mfma_f32_16x16x32_bf16 v[68:71], v[186:189], v[230:233], v[68:71]
	v_mfma_f32_16x16x32_bf16 v[64:67], v[202:205], v[230:233], v[64:67]
	v_mfma_f32_16x16x32_bf16 v[124:127], v[198:201], v[210:213], v[124:127]
	v_mfma_f32_16x16x32_bf16 v[120:123], v[170:173], v[210:213], v[120:123]
	v_mfma_f32_16x16x32_bf16 v[104:107], v[198:201], v[218:221], v[104:107]
	v_mfma_f32_16x16x32_bf16 v[100:103], v[170:173], v[218:221], v[100:103]
	v_mfma_f32_16x16x32_bf16 v[84:87], v[198:201], v[226:229], v[84:87]
	v_mfma_f32_16x16x32_bf16 v[80:83], v[170:173], v[226:229], v[80:83]
	v_mfma_f32_16x16x32_bf16 v[68:71], v[198:201], v[234:237], v[68:71]
	v_mfma_f32_16x16x32_bf16 v[64:67], v[170:173], v[234:237], v[64:67]
	s_setprio 0
	s_barrier
	s_add_u32 s8, s6, 0x40000
	s_addc_u32 s9, s7, 0
	s_mov_b32 m0, s54
	v_lshl_add_u64 v[142:143], s[8:9], 0, v[90:91]
	ds_read_b128 v[206:209], v168 offset:49152
	ds_read_b128 v[210:213], v168 offset:50176
	ds_read_b128 v[214:217], v168 offset:51200
	ds_read_b128 v[218:221], v168 offset:52224
	ds_read_b128 v[222:225], v168 offset:53248
	ds_read_b128 v[226:229], v168 offset:54272
	ds_read_b128 v[230:233], v168 offset:55296
	ds_read_b128 v[234:237], v168 offset:56320
	global_load_lds_dwordx4 v[142:143], off
	v_lshl_add_u64 v[142:143], s[8:9], 0, v[108:109]
	s_add_u32 s8, s6, 0x40080
	s_mov_b32 m0, s30
	s_addc_u32 s9, s7, 0
	global_load_lds_dwordx4 v[142:143], off
	v_lshl_add_u64 v[142:143], s[8:9], 0, v[90:91]
	s_mov_b32 m0, s15
	s_add_u32 s6, s6, 0x40100
	global_load_lds_dwordx4 v[142:143], off
	v_lshl_add_u64 v[142:143], s[8:9], 0, v[108:109]
	s_mov_b32 m0, s17
	s_addc_u32 s7, s7, 0
	global_load_lds_dwordx4 v[142:143], off
	v_lshl_add_u64 v[142:143], s[6:7], 0, v[90:91]
	s_mov_b32 m0, s68
	s_nop 0
	global_load_lds_dwordx4 v[142:143], off
	v_lshl_add_u64 v[142:143], s[6:7], 0, v[108:109]
	s_mov_b32 m0, s69
	s_nop 0
	global_load_lds_dwordx4 v[142:143], off
	s_waitcnt vmcnt(8)
	s_waitcnt lgkmcnt(0)
	s_barrier
	s_setprio 1
	s_waitcnt lgkmcnt(0)
	v_mfma_f32_16x16x32_bf16 v[60:63], v[156:159], v[206:209], v[60:63]
	v_mfma_f32_16x16x32_bf16 v[56:59], v[178:181], v[206:209], v[56:59]
	v_mfma_f32_16x16x32_bf16 v[44:47], v[156:159], v[214:217], v[44:47]
	v_mfma_f32_16x16x32_bf16 v[40:43], v[178:181], v[214:217], v[40:43]
	v_mfma_f32_16x16x32_bf16 v[28:31], v[156:159], v[222:225], v[28:31]
	v_mfma_f32_16x16x32_bf16 v[24:27], v[178:181], v[222:225], v[24:27]
	v_mfma_f32_16x16x32_bf16 v[4:7], v[156:159], v[230:233], v[4:7]
	v_mfma_f32_16x16x32_bf16 v[0:3], v[178:181], v[230:233], v[0:3]
	v_mfma_f32_16x16x32_bf16 v[60:63], v[174:177], v[210:213], v[60:63]
	v_mfma_f32_16x16x32_bf16 v[56:59], v[182:185], v[210:213], v[56:59]
	v_mfma_f32_16x16x32_bf16 v[44:47], v[174:177], v[218:221], v[44:47]
	v_mfma_f32_16x16x32_bf16 v[40:43], v[182:185], v[218:221], v[40:43]
	v_mfma_f32_16x16x32_bf16 v[28:31], v[174:177], v[226:229], v[28:31]
	v_mfma_f32_16x16x32_bf16 v[24:27], v[182:185], v[226:229], v[24:27]
	v_mfma_f32_16x16x32_bf16 v[4:7], v[174:177], v[234:237], v[4:7]
	v_mfma_f32_16x16x32_bf16 v[0:3], v[182:185], v[234:237], v[0:3]
	s_setprio 0
	s_setprio 1
	v_mfma_f32_16x16x32_bf16 v[52:55], v[186:189], v[206:209], v[52:55]
	v_mfma_f32_16x16x32_bf16 v[48:51], v[202:205], v[206:209], v[48:51]
	v_mfma_f32_16x16x32_bf16 v[36:39], v[186:189], v[214:217], v[36:39]
	v_mfma_f32_16x16x32_bf16 v[32:35], v[202:205], v[214:217], v[32:35]
	v_mfma_f32_16x16x32_bf16 v[12:15], v[186:189], v[222:225], v[12:15]
	v_mfma_f32_16x16x32_bf16 v[8:11], v[202:205], v[222:225], v[8:11]
	v_mfma_f32_16x16x32_bf16 v[20:23], v[186:189], v[230:233], v[20:23]
	v_mfma_f32_16x16x32_bf16 v[16:19], v[202:205], v[230:233], v[16:19]
	v_mfma_f32_16x16x32_bf16 v[52:55], v[198:201], v[210:213], v[52:55]
	v_mfma_f32_16x16x32_bf16 v[48:51], v[170:173], v[210:213], v[48:51]
	v_mfma_f32_16x16x32_bf16 v[36:39], v[198:201], v[218:221], v[36:39]
	v_mfma_f32_16x16x32_bf16 v[32:35], v[170:173], v[218:221], v[32:35]
	v_mfma_f32_16x16x32_bf16 v[12:15], v[198:201], v[226:229], v[12:15]
	v_mfma_f32_16x16x32_bf16 v[8:11], v[170:173], v[226:229], v[8:11]
	v_mfma_f32_16x16x32_bf16 v[20:23], v[198:201], v[234:237], v[20:23]
	v_mfma_f32_16x16x32_bf16 v[16:19], v[170:173], v[234:237], v[16:19]
	s_setprio 0
	s_barrier
	s_and_b64 vcc, exec, s[38:39]
	s_cbranch_vccz .LBB0_608
	s_ashr_i32 s43, s42, 31
	s_lshl_b64 s[2:3], s[42:43], 19
	s_add_u32 s4, s25, s2
	v_mov_b32_e32 v8, 0
	s_addc_u32 s5, s48, s3
	s_mov_b32 s12, s84
	s_mov_b32 s2, s42
	s_mov_b64 s[40:41], s[44:45]
	s_mov_b32 s43, s10
	v_mov_b32_e32 v9, v8
	v_mov_b32_e32 v10, v8
	v_mov_b32_e32 v11, v8
	v_mov_b32_e32 v12, v8
	v_mov_b32_e32 v13, v8
	v_mov_b32_e32 v14, v8
	v_mov_b32_e32 v15, v8
	v_mov_b32_e32 v32, v8
	v_mov_b32_e32 v33, v8
	v_mov_b32_e32 v34, v8
	v_mov_b32_e32 v35, v8
	v_mov_b32_e32 v36, v8
	v_mov_b32_e32 v37, v8
	v_mov_b32_e32 v38, v8
	v_mov_b32_e32 v39, v8
	v_mov_b32_e32 v48, v8
	v_mov_b32_e32 v49, v8
	v_mov_b32_e32 v50, v8
	v_mov_b32_e32 v51, v8
	v_mov_b32_e32 v52, v8
	v_mov_b32_e32 v53, v8
	v_mov_b32_e32 v54, v8
	v_mov_b32_e32 v55, v8
	v_mov_b32_e32 v0, v8
	v_mov_b32_e32 v1, v8
	v_mov_b32_e32 v2, v8
	v_mov_b32_e32 v3, v8
	v_mov_b32_e32 v4, v8
	v_mov_b32_e32 v5, v8
	v_mov_b32_e32 v6, v8
	v_mov_b32_e32 v7, v8
	v_mov_b32_e32 v24, v8
	v_mov_b32_e32 v25, v8
	v_mov_b32_e32 v26, v8
	v_mov_b32_e32 v27, v8
	v_mov_b32_e32 v28, v8
	v_mov_b32_e32 v29, v8
	v_mov_b32_e32 v30, v8
	v_mov_b32_e32 v31, v8
	v_mov_b32_e32 v40, v8
	v_mov_b32_e32 v41, v8
	v_mov_b32_e32 v42, v8
	v_mov_b32_e32 v43, v8
	v_mov_b32_e32 v44, v8
	v_mov_b32_e32 v45, v8
	v_mov_b32_e32 v46, v8
	v_mov_b32_e32 v47, v8
	v_mov_b32_e32 v56, v8
	v_mov_b32_e32 v57, v8
	v_mov_b32_e32 v58, v8
	v_mov_b32_e32 v59, v8
	v_mov_b32_e32 v60, v8
	v_mov_b32_e32 v61, v8
	v_mov_b32_e32 v62, v8
	v_mov_b32_e32 v63, v8
	v_mov_b32_e32 v64, v8
	v_mov_b32_e32 v65, v8
	v_mov_b32_e32 v66, v8
	v_mov_b32_e32 v67, v8
	v_mov_b32_e32 v68, v8
	v_mov_b32_e32 v69, v8
	v_mov_b32_e32 v70, v8
	v_mov_b32_e32 v71, v8
	v_mov_b32_e32 v80, v8
	v_mov_b32_e32 v81, v8
	v_mov_b32_e32 v82, v8
	v_mov_b32_e32 v83, v8
	v_mov_b32_e32 v84, v8
	v_mov_b32_e32 v85, v8
	v_mov_b32_e32 v86, v8
	v_mov_b32_e32 v87, v8
	v_mov_b32_e32 v100, v8
	v_mov_b32_e32 v101, v8
	v_mov_b32_e32 v102, v8
	v_mov_b32_e32 v103, v8
	v_mov_b32_e32 v104, v8
	v_mov_b32_e32 v105, v8
	v_mov_b32_e32 v106, v8
	v_mov_b32_e32 v107, v8
	v_mov_b32_e32 v120, v8
	v_mov_b32_e32 v121, v8
	v_mov_b32_e32 v122, v8
	v_mov_b32_e32 v123, v8
	v_mov_b32_e32 v124, v8
	v_mov_b32_e32 v125, v8
	v_mov_b32_e32 v126, v8
	v_mov_b32_e32 v127, v8
	v_mov_b32_e32 v72, v8
	v_mov_b32_e32 v73, v8
	v_mov_b32_e32 v74, v8
	v_mov_b32_e32 v75, v8
	v_mov_b32_e32 v76, v8
	v_mov_b32_e32 v77, v8
	v_mov_b32_e32 v78, v8
	v_mov_b32_e32 v79, v8
	v_mov_b32_e32 v92, v8
	v_mov_b32_e32 v93, v8
	v_mov_b32_e32 v94, v8
	v_mov_b32_e32 v95, v8
	v_mov_b32_e32 v96, v8
	v_mov_b32_e32 v97, v8
	v_mov_b32_e32 v98, v8
	v_mov_b32_e32 v99, v8
	v_mov_b32_e32 v112, v8
	v_mov_b32_e32 v113, v8
	v_mov_b32_e32 v114, v8
	v_mov_b32_e32 v115, v8
	v_mov_b32_e32 v116, v8
	v_mov_b32_e32 v117, v8
	v_mov_b32_e32 v118, v8
	v_mov_b32_e32 v119, v8
	v_mov_b32_e32 v132, v8
	v_mov_b32_e32 v133, v8
	v_mov_b32_e32 v134, v8
	v_mov_b32_e32 v135, v8
	v_mov_b32_e32 v136, v8
	v_mov_b32_e32 v137, v8
	v_mov_b32_e32 v138, v8
	v_mov_b32_e32 v139, v8
	v_mov_b32_e32 v20, v8
	v_mov_b32_e32 v21, v8
	v_mov_b32_e32 v22, v8
	v_mov_b32_e32 v23, v8
	v_mov_b32_e32 v16, v8
	v_mov_b32_e32 v17, v8
	v_mov_b32_e32 v18, v8
	v_mov_b32_e32 v19, v8
	s_branch .LBB0_608

.LBB0_741:
	s_add_u32 s6, s2, s40
	s_addc_u32 s7, s3, s41
	s_add_u32 s6, s6, 0x100
	s_addc_u32 s7, s7, 0
	s_add_u32 s8, s13, s40
	s_addc_u32 s9, s14, s41
	s_add_i32 s16, 0, 0x10000
	s_cmpk_eq_i32 s40, 0x700
	s_cselect_b32 s19, s5, s7
	s_cselect_b32 s18, s11, s6
	v_add_u32_e32 v146, s16, v142
	s_cselect_b32 s7, s43, s9
	s_cselect_b32 s6, s42, s8
	s_add_i32 s17, 0, 0x14000
	ds_read_b128 v[156:159], v146
	ds_read_b128 v[160:163], v146 offset:1024
	ds_read_b128 v[164:167], v146 offset:2048
	ds_read_b128 v[168:171], v146 offset:3072
	v_add_u32_e32 v146, s17, v142
	ds_read_b128 v[172:175], v146
	ds_read_b128 v[176:179], v146 offset:1024
	ds_read_b128 v[180:183], v146 offset:2048
	ds_read_b128 v[184:187], v146 offset:3072
	v_lshl_add_u64 v[146:147], v[138:139], 0, s[40:41]
	s_add_i32 m0, s51, 0xc000
	ds_read_b128 v[188:191], v143
	ds_read_b128 v[202:205], v143 offset:1024
	ds_read_b128 v[206:209], v143 offset:2048
	ds_read_b128 v[210:213], v143 offset:3072
	ds_read_b128 v[214:217], v143 offset:4096
	ds_read_b128 v[218:221], v143 offset:5120
	ds_read_b128 v[222:225], v143 offset:6144
	ds_read_b128 v[226:229], v143 offset:7168
	global_load_lds_dwordx4 v[146:147], off
	v_lshl_add_u64 v[146:147], v[140:141], 0, s[40:41]
	s_add_i32 m0, s51, 0xe000
	s_nop 0
	global_load_lds_dwordx4 v[146:147], off
	s_waitcnt vmcnt(8)
	s_waitcnt lgkmcnt(0)
	s_barrier
	s_setprio 1
	s_waitcnt lgkmcnt(0)
	v_mfma_f32_16x16x32_bf16 v[124:127], v[156:159], v[188:191], v[124:127]
	v_mfma_f32_16x16x32_bf16 v[120:123], v[164:167], v[188:191], v[120:123]
	v_mfma_f32_16x16x32_bf16 v[108:111], v[156:159], v[206:209], v[108:111]
	v_mfma_f32_16x16x32_bf16 v[104:107], v[164:167], v[206:209], v[104:107]
	v_mfma_f32_16x16x32_bf16 v[100:103], v[156:159], v[214:217], v[100:103]
	v_mfma_f32_16x16x32_bf16 v[92:95], v[164:167], v[214:217], v[92:95]
	v_mfma_f32_16x16x32_bf16 v[84:87], v[156:159], v[222:225], v[84:87]
	v_mfma_f32_16x16x32_bf16 v[76:79], v[164:167], v[222:225], v[76:79]
	v_mfma_f32_16x16x32_bf16 v[124:127], v[160:163], v[202:205], v[124:127]
	v_mfma_f32_16x16x32_bf16 v[120:123], v[168:171], v[202:205], v[120:123]
	v_mfma_f32_16x16x32_bf16 v[108:111], v[160:163], v[210:213], v[108:111]
	v_mfma_f32_16x16x32_bf16 v[104:107], v[168:171], v[210:213], v[104:107]
	v_mfma_f32_16x16x32_bf16 v[100:103], v[160:163], v[218:221], v[100:103]
	v_mfma_f32_16x16x32_bf16 v[92:95], v[168:171], v[218:221], v[92:95]
	v_mfma_f32_16x16x32_bf16 v[84:87], v[160:163], v[226:229], v[84:87]
	v_mfma_f32_16x16x32_bf16 v[76:79], v[168:171], v[226:229], v[76:79]
	s_setprio 0
	s_setprio 1
	v_mfma_f32_16x16x32_bf16 v[116:119], v[172:175], v[188:191], v[116:119]
	v_mfma_f32_16x16x32_bf16 v[112:115], v[180:183], v[188:191], v[112:115]
	v_mfma_f32_16x16x32_bf16 v[96:99], v[172:175], v[206:209], v[96:99]
	v_mfma_f32_16x16x32_bf16 v[88:91], v[180:183], v[206:209], v[88:91]
	v_mfma_f32_16x16x32_bf16 v[80:83], v[172:175], v[214:217], v[80:83]
	v_mfma_f32_16x16x32_bf16 v[72:75], v[180:183], v[214:217], v[72:75]
	v_mfma_f32_16x16x32_bf16 v[68:71], v[172:175], v[222:225], v[68:71]
	v_mfma_f32_16x16x32_bf16 v[64:67], v[180:183], v[222:225], v[64:67]
	v_mfma_f32_16x16x32_bf16 v[116:119], v[176:179], v[202:205], v[116:119]
	v_mfma_f32_16x16x32_bf16 v[112:115], v[184:187], v[202:205], v[112:115]
	v_mfma_f32_16x16x32_bf16 v[96:99], v[176:179], v[210:213], v[96:99]
	v_mfma_f32_16x16x32_bf16 v[88:91], v[184:187], v[210:213], v[88:91]
	v_mfma_f32_16x16x32_bf16 v[80:83], v[176:179], v[218:221], v[80:83]
	v_mfma_f32_16x16x32_bf16 v[72:75], v[184:187], v[218:221], v[72:75]
	v_mfma_f32_16x16x32_bf16 v[68:71], v[176:179], v[226:229], v[68:71]
	v_mfma_f32_16x16x32_bf16 v[64:67], v[184:187], v[226:229], v[64:67]
	s_setprio 0
	s_barrier
	s_add_i32 s8, s16, s50
	v_lshl_add_u64 v[146:147], s[6:7], 0, v[144:145]
	s_mov_b32 m0, s8
	ds_read_b128 v[188:191], v143 offset:16384
	ds_read_b128 v[202:205], v143 offset:17408
	ds_read_b128 v[206:209], v143 offset:18432
	ds_read_b128 v[210:213], v143 offset:19456
	ds_read_b128 v[214:217], v143 offset:20480
	ds_read_b128 v[218:221], v143 offset:21504
	ds_read_b128 v[222:225], v143 offset:22528
	ds_read_b128 v[226:229], v143 offset:23552
	global_load_lds_dwordx4 v[146:147], off
	s_add_i32 m0, s8, 0x2000
	s_add_u32 s8, s6, 0x40000
	v_lshl_add_u64 v[154:155], s[6:7], 0, v[128:129]
	s_addc_u32 s9, s7, 0
	s_add_i32 s16, s17, s50
	global_load_lds_dwordx4 v[154:155], off
	v_lshl_add_u64 v[230:231], s[8:9], 0, v[144:145]
	s_mov_b32 m0, s16
	v_lshl_add_u64 v[232:233], s[18:19], 0, v[130:131]
	global_load_lds_dwordx4 v[230:231], off
	v_lshl_add_u64 v[230:231], s[8:9], 0, v[128:129]
	s_add_i32 m0, s16, 0x2000
	s_nop 0
	global_load_lds_dwordx4 v[230:231], off
	v_lshl_add_u64 v[230:231], s[18:19], 0, v[132:133]
	s_mov_b32 m0, s51
	s_nop 0
	global_load_lds_dwordx4 v[230:231], off
	s_mov_b32 m0, s64
	s_nop 0
	global_load_lds_dwordx4 v[232:233], off
	s_waitcnt vmcnt(8)
	s_waitcnt lgkmcnt(0)
	s_barrier
	s_setprio 1
	s_waitcnt lgkmcnt(0)
	v_mfma_f32_16x16x32_bf16 v[60:63], v[156:159], v[188:191], v[60:63]
	v_mfma_f32_16x16x32_bf16 v[56:59], v[164:167], v[188:191], v[56:59]
	v_mfma_f32_16x16x32_bf16 v[52:55], v[156:159], v[206:209], v[52:55]
	v_mfma_f32_16x16x32_bf16 v[44:47], v[164:167], v[206:209], v[44:47]
	v_mfma_f32_16x16x32_bf16 v[36:39], v[156:159], v[214:217], v[36:39]
	v_mfma_f32_16x16x32_bf16 v[28:31], v[164:167], v[214:217], v[28:31]
	v_mfma_f32_16x16x32_bf16 v[20:23], v[156:159], v[222:225], v[20:23]
	v_mfma_f32_16x16x32_bf16 v[12:15], v[164:167], v[222:225], v[12:15]
	v_mfma_f32_16x16x32_bf16 v[60:63], v[160:163], v[202:205], v[60:63]
	v_mfma_f32_16x16x32_bf16 v[56:59], v[168:171], v[202:205], v[56:59]
	v_mfma_f32_16x16x32_bf16 v[52:55], v[160:163], v[210:213], v[52:55]
	v_mfma_f32_16x16x32_bf16 v[44:47], v[168:171], v[210:213], v[44:47]
	v_mfma_f32_16x16x32_bf16 v[36:39], v[160:163], v[218:221], v[36:39]
	v_mfma_f32_16x16x32_bf16 v[28:31], v[168:171], v[218:221], v[28:31]
	v_mfma_f32_16x16x32_bf16 v[20:23], v[160:163], v[226:229], v[20:23]
	v_mfma_f32_16x16x32_bf16 v[12:15], v[168:171], v[226:229], v[12:15]
	s_setprio 0
	s_setprio 1
	v_mfma_f32_16x16x32_bf16 v[48:51], v[172:175], v[188:191], v[48:51]
	v_mfma_f32_16x16x32_bf16 v[40:43], v[180:183], v[188:191], v[40:43]
	v_mfma_f32_16x16x32_bf16 v[32:35], v[172:175], v[206:209], v[32:35]
	v_mfma_f32_16x16x32_bf16 v[24:27], v[180:183], v[206:209], v[24:27]
	v_mfma_f32_16x16x32_bf16 v[16:19], v[172:175], v[214:217], v[16:19]
	v_mfma_f32_16x16x32_bf16 v[8:11], v[180:183], v[214:217], v[8:11]
	v_mfma_f32_16x16x32_bf16 v[4:7], v[172:175], v[222:225], v[4:7]
	v_mfma_f32_16x16x32_bf16 v[0:3], v[180:183], v[222:225], v[0:3]
	v_mfma_f32_16x16x32_bf16 v[48:51], v[176:179], v[202:205], v[48:51]
	v_mfma_f32_16x16x32_bf16 v[40:43], v[184:187], v[202:205], v[40:43]
	v_mfma_f32_16x16x32_bf16 v[32:35], v[176:179], v[210:213], v[32:35]
	v_mfma_f32_16x16x32_bf16 v[24:27], v[184:187], v[210:213], v[24:27]
	v_mfma_f32_16x16x32_bf16 v[16:19], v[176:179], v[218:221], v[16:19]
	v_mfma_f32_16x16x32_bf16 v[8:11], v[184:187], v[218:221], v[8:11]
	v_mfma_f32_16x16x32_bf16 v[4:7], v[176:179], v[226:229], v[4:7]
	v_mfma_f32_16x16x32_bf16 v[0:3], v[184:187], v[226:229], v[0:3]
	s_setprio 0
	s_barrier
	s_add_i32 s16, 0, 0x18000
	s_add_i32 s17, 0, 0x1c000
	v_add_u32_e32 v168, s16, v142
	v_add_u32_e32 v184, s17, v142
	ds_read_b128 v[156:159], v168
	ds_read_b128 v[160:163], v168 offset:1024
	ds_read_b128 v[164:167], v168 offset:2048
	ds_read_b128 v[168:171], v168 offset:3072
	ds_read_b128 v[172:175], v184
	ds_read_b128 v[176:179], v184 offset:1024
	ds_read_b128 v[180:183], v184 offset:2048
	ds_read_b128 v[184:187], v184 offset:3072
	s_add_u32 s8, s18, 0x40000
	s_addc_u32 s9, s19, 0
	s_mov_b32 m0, s65
	v_lshl_add_u64 v[234:235], s[8:9], 0, v[132:133]
	ds_read_b128 v[188:191], v143 offset:32768
	ds_read_b128 v[202:205], v143 offset:33792
	ds_read_b128 v[206:209], v143 offset:34816
	ds_read_b128 v[210:213], v143 offset:35840
	ds_read_b128 v[214:217], v143 offset:36864
	ds_read_b128 v[218:221], v143 offset:37888
	ds_read_b128 v[222:225], v143 offset:38912
	ds_read_b128 v[226:229], v143 offset:39936
	global_load_lds_dwordx4 v[234:235], off
	v_lshl_add_u64 v[234:235], s[8:9], 0, v[130:131]
	s_mov_b32 m0, s68
	s_nop 0
	global_load_lds_dwordx4 v[234:235], off
	s_waitcnt vmcnt(8)
	s_waitcnt lgkmcnt(0)
	s_barrier
	s_setprio 1
	s_waitcnt lgkmcnt(0)
	v_mfma_f32_16x16x32_bf16 v[124:127], v[156:159], v[188:191], v[124:127]
	v_mfma_f32_16x16x32_bf16 v[120:123], v[164:167], v[188:191], v[120:123]
	v_mfma_f32_16x16x32_bf16 v[108:111], v[156:159], v[206:209], v[108:111]
	v_mfma_f32_16x16x32_bf16 v[104:107], v[164:167], v[206:209], v[104:107]
	v_mfma_f32_16x16x32_bf16 v[100:103], v[156:159], v[214:217], v[100:103]
	v_mfma_f32_16x16x32_bf16 v[92:95], v[164:167], v[214:217], v[92:95]
	v_mfma_f32_16x16x32_bf16 v[84:87], v[156:159], v[222:225], v[84:87]
	v_mfma_f32_16x16x32_bf16 v[76:79], v[164:167], v[222:225], v[76:79]
	v_mfma_f32_16x16x32_bf16 v[124:127], v[160:163], v[202:205], v[124:127]
	v_mfma_f32_16x16x32_bf16 v[120:123], v[168:171], v[202:205], v[120:123]
	v_mfma_f32_16x16x32_bf16 v[108:111], v[160:163], v[210:213], v[108:111]
	v_mfma_f32_16x16x32_bf16 v[104:107], v[168:171], v[210:213], v[104:107]
	v_mfma_f32_16x16x32_bf16 v[100:103], v[160:163], v[218:221], v[100:103]
	v_mfma_f32_16x16x32_bf16 v[92:95], v[168:171], v[218:221], v[92:95]
	v_mfma_f32_16x16x32_bf16 v[84:87], v[160:163], v[226:229], v[84:87]
	v_mfma_f32_16x16x32_bf16 v[76:79], v[168:171], v[226:229], v[76:79]
	s_setprio 0
	s_setprio 1
	v_mfma_f32_16x16x32_bf16 v[116:119], v[172:175], v[188:191], v[116:119]
	v_mfma_f32_16x16x32_bf16 v[112:115], v[180:183], v[188:191], v[112:115]
	v_mfma_f32_16x16x32_bf16 v[96:99], v[172:175], v[206:209], v[96:99]
	v_mfma_f32_16x16x32_bf16 v[88:91], v[180:183], v[206:209], v[88:91]
	v_mfma_f32_16x16x32_bf16 v[80:83], v[172:175], v[214:217], v[80:83]
	v_mfma_f32_16x16x32_bf16 v[72:75], v[180:183], v[214:217], v[72:75]
	v_mfma_f32_16x16x32_bf16 v[68:71], v[172:175], v[222:225], v[68:71]
	v_mfma_f32_16x16x32_bf16 v[64:67], v[180:183], v[222:225], v[64:67]
	v_mfma_f32_16x16x32_bf16 v[116:119], v[176:179], v[202:205], v[116:119]
	v_mfma_f32_16x16x32_bf16 v[112:115], v[184:187], v[202:205], v[112:115]
	v_mfma_f32_16x16x32_bf16 v[96:99], v[176:179], v[210:213], v[96:99]
	v_mfma_f32_16x16x32_bf16 v[88:91], v[184:187], v[210:213], v[88:91]
	v_mfma_f32_16x16x32_bf16 v[80:83], v[176:179], v[218:221], v[80:83]
	v_mfma_f32_16x16x32_bf16 v[72:75], v[184:187], v[218:221], v[72:75]
	v_mfma_f32_16x16x32_bf16 v[68:71], v[176:179], v[226:229], v[68:71]
	v_mfma_f32_16x16x32_bf16 v[64:67], v[184:187], v[226:229], v[64:67]
	s_setprio 0
	s_barrier
	s_add_i32 s8, s16, s50
	v_lshl_add_u64 v[146:147], v[146:147], 0, s[70:71]
	s_mov_b32 m0, s8
	ds_read_b128 v[188:191], v143 offset:49152
	ds_read_b128 v[202:205], v143 offset:50176
	ds_read_b128 v[206:209], v143 offset:51200
	ds_read_b128 v[210:213], v143 offset:52224
	ds_read_b128 v[214:217], v143 offset:53248
	ds_read_b128 v[218:221], v143 offset:54272
	ds_read_b128 v[222:225], v143 offset:55296
	ds_read_b128 v[226:229], v143 offset:56320
	global_load_lds_dwordx4 v[146:147], off
	s_add_i32 m0, s8, 0x2000
	s_add_u32 s6, s6, 0x40080
	v_lshl_add_u64 v[146:147], v[154:155], 0, s[70:71]
	s_addc_u32 s7, s7, 0
	s_add_i32 s8, s17, s50
	global_load_lds_dwordx4 v[146:147], off
	v_lshl_add_u64 v[146:147], s[6:7], 0, v[144:145]
	s_mov_b32 m0, s8
	s_nop 0
	global_load_lds_dwordx4 v[146:147], off
	v_lshl_add_u64 v[146:147], s[6:7], 0, v[128:129]
	s_add_i32 m0, s8, 0x2000
	s_nop 0
	global_load_lds_dwordx4 v[146:147], off
	v_lshl_add_u64 v[146:147], v[230:231], 0, s[70:71]
	s_mov_b32 m0, s69
	s_nop 0
	global_load_lds_dwordx4 v[146:147], off
	v_lshl_add_u64 v[146:147], v[232:233], 0, s[70:71]
	s_mov_b32 m0, s84
	s_nop 0
	global_load_lds_dwordx4 v[146:147], off
	s_waitcnt vmcnt(8)
	s_waitcnt lgkmcnt(0)
	s_barrier
	s_setprio 1
	s_waitcnt lgkmcnt(0)
	v_mfma_f32_16x16x32_bf16 v[60:63], v[156:159], v[188:191], v[60:63]
	v_mfma_f32_16x16x32_bf16 v[56:59], v[164:167], v[188:191], v[56:59]
	v_mfma_f32_16x16x32_bf16 v[52:55], v[156:159], v[206:209], v[52:55]
	v_mfma_f32_16x16x32_bf16 v[44:47], v[164:167], v[206:209], v[44:47]
	v_mfma_f32_16x16x32_bf16 v[36:39], v[156:159], v[214:217], v[36:39]
	v_mfma_f32_16x16x32_bf16 v[28:31], v[164:167], v[214:217], v[28:31]
	v_mfma_f32_16x16x32_bf16 v[20:23], v[156:159], v[222:225], v[20:23]
	v_mfma_f32_16x16x32_bf16 v[12:15], v[164:167], v[222:225], v[12:15]
	v_mfma_f32_16x16x32_bf16 v[60:63], v[160:163], v[202:205], v[60:63]
	v_mfma_f32_16x16x32_bf16 v[56:59], v[168:171], v[202:205], v[56:59]
	v_mfma_f32_16x16x32_bf16 v[52:55], v[160:163], v[210:213], v[52:55]
	v_mfma_f32_16x16x32_bf16 v[44:47], v[168:171], v[210:213], v[44:47]
	v_mfma_f32_16x16x32_bf16 v[36:39], v[160:163], v[218:221], v[36:39]
	v_mfma_f32_16x16x32_bf16 v[28:31], v[168:171], v[218:221], v[28:31]
	v_mfma_f32_16x16x32_bf16 v[20:23], v[160:163], v[226:229], v[20:23]
	v_mfma_f32_16x16x32_bf16 v[12:15], v[168:171], v[226:229], v[12:15]
	s_setprio 0
	s_setprio 1
	v_mfma_f32_16x16x32_bf16 v[48:51], v[172:175], v[188:191], v[48:51]
	s_add_i32 s15, s15, 2
	s_add_u32 s40, s40, 0x100
	s_addc_u32 s41, s41, 0
	s_cmp_gt_u32 s15, 13
	v_mfma_f32_16x16x32_bf16 v[40:43], v[180:183], v[188:191], v[40:43]
	v_mfma_f32_16x16x32_bf16 v[32:35], v[172:175], v[206:209], v[32:35]
	v_mfma_f32_16x16x32_bf16 v[24:27], v[180:183], v[206:209], v[24:27]
	v_mfma_f32_16x16x32_bf16 v[16:19], v[172:175], v[214:217], v[16:19]
	v_mfma_f32_16x16x32_bf16 v[8:11], v[180:183], v[214:217], v[8:11]
	v_mfma_f32_16x16x32_bf16 v[4:7], v[172:175], v[222:225], v[4:7]
	v_mfma_f32_16x16x32_bf16 v[0:3], v[180:183], v[222:225], v[0:3]
	v_mfma_f32_16x16x32_bf16 v[48:51], v[176:179], v[202:205], v[48:51]
	v_mfma_f32_16x16x32_bf16 v[40:43], v[184:187], v[202:205], v[40:43]
	v_mfma_f32_16x16x32_bf16 v[32:35], v[176:179], v[210:213], v[32:35]
	v_mfma_f32_16x16x32_bf16 v[24:27], v[184:187], v[210:213], v[24:27]
	v_mfma_f32_16x16x32_bf16 v[16:19], v[176:179], v[218:221], v[16:19]
	v_mfma_f32_16x16x32_bf16 v[8:11], v[184:187], v[218:221], v[8:11]
	v_mfma_f32_16x16x32_bf16 v[4:7], v[176:179], v[226:229], v[4:7]
	v_mfma_f32_16x16x32_bf16 v[0:3], v[184:187], v[226:229], v[0:3]
	s_setprio 0
	s_barrier
	s_cbranch_scc0 .LBB0_741
	s_add_u32 s6, s13, 0xffffff00
	s_addc_u32 s7, s14, -1
	s_and_b64 vcc, exec, s[38:39]
	s_cbranch_vccnz .LBB0_730
	v_mov_b32_e32 v0, 0
	s_mov_b32 s25, s4
	s_mov_b32 s24, s12
	s_mov_b64 s[2:3], s[44:45]
	s_mov_b32 s85, s10
	v_mov_b32_e32 v1, v0
	v_mov_b32_e32 v2, v0
	v_mov_b32_e32 v3, v0
	v_mov_b32_e32 v4, v0
	v_mov_b32_e32 v5, v0
	v_mov_b32_e32 v6, v0
	v_mov_b32_e32 v7, v0
	v_mov_b32_e32 v8, v0
	v_mov_b32_e32 v9, v0
	v_mov_b32_e32 v10, v0
	v_mov_b32_e32 v11, v0
	v_mov_b32_e32 v16, v0
	v_mov_b32_e32 v17, v0
	v_mov_b32_e32 v18, v0
	v_mov_b32_e32 v19, v0
	v_mov_b32_e32 v24, v0
	v_mov_b32_e32 v25, v0
	v_mov_b32_e32 v26, v0
	v_mov_b32_e32 v27, v0
	v_mov_b32_e32 v32, v0
	v_mov_b32_e32 v33, v0
	v_mov_b32_e32 v34, v0
	v_mov_b32_e32 v35, v0
	v_mov_b32_e32 v40, v0
	v_mov_b32_e32 v41, v0
	v_mov_b32_e32 v42, v0
	v_mov_b32_e32 v43, v0
	v_mov_b32_e32 v48, v0
	v_mov_b32_e32 v49, v0
	v_mov_b32_e32 v50, v0
	v_mov_b32_e32 v51, v0
	v_mov_b32_e32 v12, v0
	v_mov_b32_e32 v13, v0
	v_mov_b32_e32 v14, v0
	v_mov_b32_e32 v15, v0
	v_mov_b32_e32 v20, v0
	v_mov_b32_e32 v21, v0
	v_mov_b32_e32 v22, v0
	v_mov_b32_e32 v23, v0
	v_mov_b32_e32 v28, v0
	v_mov_b32_e32 v29, v0
	v_mov_b32_e32 v30, v0
	v_mov_b32_e32 v31, v0
	v_mov_b32_e32 v36, v0
	v_mov_b32_e32 v37, v0
	v_mov_b32_e32 v38, v0
	v_mov_b32_e32 v39, v0
	v_mov_b32_e32 v44, v0
	v_mov_b32_e32 v45, v0
	v_mov_b32_e32 v46, v0
	v_mov_b32_e32 v47, v0
	v_mov_b32_e32 v52, v0
	v_mov_b32_e32 v53, v0
	v_mov_b32_e32 v54, v0
	v_mov_b32_e32 v55, v0
	v_mov_b32_e32 v56, v0
	v_mov_b32_e32 v57, v0
	v_mov_b32_e32 v58, v0
	v_mov_b32_e32 v59, v0
	v_mov_b32_e32 v60, v0
	v_mov_b32_e32 v61, v0
	v_mov_b32_e32 v62, v0
	v_mov_b32_e32 v63, v0
	v_mov_b32_e32 v64, v0
	v_mov_b32_e32 v65, v0
	v_mov_b32_e32 v66, v0
	v_mov_b32_e32 v67, v0
	v_mov_b32_e32 v68, v0
	v_mov_b32_e32 v69, v0
	v_mov_b32_e32 v70, v0
	v_mov_b32_e32 v71, v0
	v_mov_b32_e32 v72, v0
	v_mov_b32_e32 v73, v0
	v_mov_b32_e32 v74, v0
	v_mov_b32_e32 v75, v0
	v_mov_b32_e32 v80, v0
	v_mov_b32_e32 v81, v0
	v_mov_b32_e32 v82, v0
	v_mov_b32_e32 v83, v0
	v_mov_b32_e32 v88, v0
	v_mov_b32_e32 v89, v0
	v_mov_b32_e32 v90, v0
	v_mov_b32_e32 v91, v0
	v_mov_b32_e32 v96, v0
	v_mov_b32_e32 v97, v0
	v_mov_b32_e32 v98, v0
	v_mov_b32_e32 v99, v0
	v_mov_b32_e32 v112, v0
	v_mov_b32_e32 v113, v0
	v_mov_b32_e32 v114, v0
	v_mov_b32_e32 v115, v0
	v_mov_b32_e32 v116, v0
	v_mov_b32_e32 v117, v0
	v_mov_b32_e32 v118, v0
	v_mov_b32_e32 v119, v0
	v_mov_b32_e32 v76, v0
	v_mov_b32_e32 v77, v0
	v_mov_b32_e32 v78, v0
	v_mov_b32_e32 v79, v0
	v_mov_b32_e32 v84, v0
	v_mov_b32_e32 v85, v0
	v_mov_b32_e32 v86, v0
	v_mov_b32_e32 v87, v0
	v_mov_b32_e32 v92, v0
	v_mov_b32_e32 v93, v0
	v_mov_b32_e32 v94, v0
	v_mov_b32_e32 v95, v0
	v_mov_b32_e32 v100, v0
	v_mov_b32_e32 v101, v0
	v_mov_b32_e32 v102, v0
	v_mov_b32_e32 v103, v0
	v_mov_b32_e32 v104, v0
	v_mov_b32_e32 v105, v0
	v_mov_b32_e32 v106, v0
	v_mov_b32_e32 v107, v0
	v_mov_b32_e32 v108, v0
	v_mov_b32_e32 v109, v0
	v_mov_b32_e32 v110, v0
	v_mov_b32_e32 v111, v0
	v_mov_b32_e32 v120, v0
	v_mov_b32_e32 v121, v0
	v_mov_b32_e32 v122, v0
	v_mov_b32_e32 v123, v0
	v_mov_b32_e32 v124, v0
	v_mov_b32_e32 v125, v0
	v_mov_b32_e32 v126, v0
	v_mov_b32_e32 v127, v0
	s_andn2_b64 vcc, exec, s[36:37]
	s_cbranch_vccnz .LBB0_731

.LBB0_876:
	s_add_i32 s31, 0, 0x10000
	s_add_i32 s16, 0, 0x14000
	v_add_u32_e32 v169, s31, v166
	v_add_u32_e32 v170, s16, v166
	ds_read_b128 v[172:175], v169
	ds_read_b128 v[176:179], v169 offset:1024
	ds_read_b128 v[180:183], v169 offset:2048
	ds_read_b128 v[184:187], v169 offset:3072
	ds_read_b128 v[188:191], v170
	ds_read_b128 v[198:201], v170 offset:1024
	ds_read_b128 v[202:205], v170 offset:2048
	ds_read_b128 v[206:209], v170 offset:3072
	v_lshl_add_u64 v[146:147], v[142:143], 0, s[48:49]
	s_add_i32 s33, s50, 0xc000
	v_lshl_add_u64 v[154:155], v[146:147], 0, s[28:29]
	s_mov_b32 m0, s33
	ds_read_b128 v[210:213], v168
	ds_read_b128 v[214:217], v168 offset:1024
	ds_read_b128 v[218:221], v168 offset:2048
	ds_read_b128 v[222:225], v168 offset:3072
	ds_read_b128 v[226:229], v168 offset:4096
	ds_read_b128 v[230:233], v168 offset:5120
	ds_read_b128 v[234:237], v168 offset:6144
	ds_read_b128 v[238:241], v168 offset:7168
	global_load_lds_dwordx4 v[154:155], off
	v_lshl_add_u64 v[154:155], v[156:157], 0, s[48:49]
	s_add_i32 s11, s50, 0xe000
	v_lshl_add_u64 v[242:243], v[154:155], 0, s[28:29]
	s_mov_b32 m0, s11
	s_nop 0
	global_load_lds_dwordx4 v[242:243], off
	s_waitcnt vmcnt(8)
	s_waitcnt lgkmcnt(0)
	s_barrier
	s_setprio 1
	s_waitcnt lgkmcnt(0)
	v_mfma_f32_16x16x32_bf16 v[136:139], v[172:175], v[210:213], v[136:139]
	v_mfma_f32_16x16x32_bf16 v[132:135], v[180:183], v[210:213], v[132:135]
	v_mfma_f32_16x16x32_bf16 v[116:119], v[172:175], v[218:221], v[116:119]
	v_mfma_f32_16x16x32_bf16 v[112:115], v[180:183], v[218:221], v[112:115]
	v_mfma_f32_16x16x32_bf16 v[96:99], v[172:175], v[226:229], v[96:99]
	v_mfma_f32_16x16x32_bf16 v[92:95], v[180:183], v[226:229], v[92:95]
	v_mfma_f32_16x16x32_bf16 v[76:79], v[172:175], v[234:237], v[76:79]
	v_mfma_f32_16x16x32_bf16 v[72:75], v[180:183], v[234:237], v[72:75]
	v_mfma_f32_16x16x32_bf16 v[136:139], v[176:179], v[214:217], v[136:139]
	v_mfma_f32_16x16x32_bf16 v[132:135], v[184:187], v[214:217], v[132:135]
	v_mfma_f32_16x16x32_bf16 v[116:119], v[176:179], v[222:225], v[116:119]
	v_mfma_f32_16x16x32_bf16 v[112:115], v[184:187], v[222:225], v[112:115]
	v_mfma_f32_16x16x32_bf16 v[96:99], v[176:179], v[230:233], v[96:99]
	v_mfma_f32_16x16x32_bf16 v[92:95], v[184:187], v[230:233], v[92:95]
	v_mfma_f32_16x16x32_bf16 v[76:79], v[176:179], v[238:241], v[76:79]
	v_mfma_f32_16x16x32_bf16 v[72:75], v[184:187], v[238:241], v[72:75]
	s_setprio 0
	s_setprio 1
	v_mfma_f32_16x16x32_bf16 v[124:127], v[188:191], v[210:213], v[124:127]
	v_mfma_f32_16x16x32_bf16 v[120:123], v[202:205], v[210:213], v[120:123]
	v_mfma_f32_16x16x32_bf16 v[104:107], v[188:191], v[218:221], v[104:107]
	v_mfma_f32_16x16x32_bf16 v[100:103], v[202:205], v[218:221], v[100:103]
	v_mfma_f32_16x16x32_bf16 v[84:87], v[188:191], v[226:229], v[84:87]
	v_mfma_f32_16x16x32_bf16 v[80:83], v[202:205], v[226:229], v[80:83]
	v_mfma_f32_16x16x32_bf16 v[68:71], v[188:191], v[234:237], v[68:71]
	v_mfma_f32_16x16x32_bf16 v[64:67], v[202:205], v[234:237], v[64:67]
	v_mfma_f32_16x16x32_bf16 v[124:127], v[198:201], v[214:217], v[124:127]
	v_mfma_f32_16x16x32_bf16 v[120:123], v[206:209], v[214:217], v[120:123]
	v_mfma_f32_16x16x32_bf16 v[104:107], v[198:201], v[222:225], v[104:107]
	v_mfma_f32_16x16x32_bf16 v[100:103], v[206:209], v[222:225], v[100:103]
	v_mfma_f32_16x16x32_bf16 v[84:87], v[198:201], v[230:233], v[84:87]
	v_mfma_f32_16x16x32_bf16 v[80:83], v[206:209], v[230:233], v[80:83]
	v_mfma_f32_16x16x32_bf16 v[68:71], v[198:201], v[238:241], v[68:71]
	v_mfma_f32_16x16x32_bf16 v[64:67], v[206:209], v[238:241], v[64:67]
	s_setprio 0
	s_barrier
	v_lshl_add_u64 v[246:247], v[158:159], 0, s[48:49]
	s_add_i32 s31, s31, s25
	v_lshl_add_u64 v[242:243], v[246:247], 0, s[96:97]
	s_mov_b32 m0, s31
	v_lshl_add_u64 v[248:249], v[160:161], 0, s[48:49]
	s_add_i32 s14, s31, 0x2000
	ds_read_b128 v[210:213], v168 offset:16384
	ds_read_b128 v[214:217], v168 offset:17408
	ds_read_b128 v[218:221], v168 offset:18432
	ds_read_b128 v[222:225], v168 offset:19456
	ds_read_b128 v[226:229], v168 offset:20480
	ds_read_b128 v[230:233], v168 offset:21504
	ds_read_b128 v[234:237], v168 offset:22528
	ds_read_b128 v[238:241], v168 offset:23552
	global_load_lds_dwordx4 v[242:243], off
	v_lshl_add_u64 v[242:243], v[248:249], 0, s[96:97]
	s_mov_b32 m0, s14
	s_add_i32 s16, s16, s25
	global_load_lds_dwordx4 v[242:243], off
	v_lshl_add_u64 v[242:243], v[246:247], 0, s[74:75]
	s_mov_b32 m0, s16
	s_add_i32 s23, s16, 0x2000
	global_load_lds_dwordx4 v[242:243], off
	v_lshl_add_u64 v[242:243], v[248:249], 0, s[74:75]
	s_mov_b32 m0, s23
	s_nop 0
	global_load_lds_dwordx4 v[242:243], off
	v_lshl_add_u64 v[242:243], v[146:147], 0, s[96:97]
	s_mov_b32 m0, s50
	s_nop 0
	global_load_lds_dwordx4 v[242:243], off
	v_lshl_add_u64 v[242:243], v[154:155], 0, s[96:97]
	s_mov_b32 m0, s51
	s_nop 0
	global_load_lds_dwordx4 v[242:243], off
	s_waitcnt vmcnt(8)
	s_waitcnt lgkmcnt(0)
	s_barrier
	s_setprio 1
	s_waitcnt lgkmcnt(0)
	v_mfma_f32_16x16x32_bf16 v[60:63], v[172:175], v[210:213], v[60:63]
	v_mfma_f32_16x16x32_bf16 v[56:59], v[180:183], v[210:213], v[56:59]
	v_mfma_f32_16x16x32_bf16 v[44:47], v[172:175], v[218:221], v[44:47]
	v_mfma_f32_16x16x32_bf16 v[40:43], v[180:183], v[218:221], v[40:43]
	v_mfma_f32_16x16x32_bf16 v[28:31], v[172:175], v[226:229], v[28:31]
	v_mfma_f32_16x16x32_bf16 v[24:27], v[180:183], v[226:229], v[24:27]
	v_mfma_f32_16x16x32_bf16 v[4:7], v[172:175], v[234:237], v[4:7]
	v_mfma_f32_16x16x32_bf16 v[0:3], v[180:183], v[234:237], v[0:3]
	v_mfma_f32_16x16x32_bf16 v[60:63], v[176:179], v[214:217], v[60:63]
	v_mfma_f32_16x16x32_bf16 v[56:59], v[184:187], v[214:217], v[56:59]
	v_mfma_f32_16x16x32_bf16 v[44:47], v[176:179], v[222:225], v[44:47]
	v_mfma_f32_16x16x32_bf16 v[40:43], v[184:187], v[222:225], v[40:43]
	v_mfma_f32_16x16x32_bf16 v[28:31], v[176:179], v[230:233], v[28:31]
	v_mfma_f32_16x16x32_bf16 v[24:27], v[184:187], v[230:233], v[24:27]
	v_mfma_f32_16x16x32_bf16 v[4:7], v[176:179], v[238:241], v[4:7]
	v_mfma_f32_16x16x32_bf16 v[0:3], v[184:187], v[238:241], v[0:3]
	s_setprio 0
	s_setprio 1
	v_mfma_f32_16x16x32_bf16 v[52:55], v[188:191], v[210:213], v[52:55]
	v_mfma_f32_16x16x32_bf16 v[48:51], v[202:205], v[210:213], v[48:51]
	v_mfma_f32_16x16x32_bf16 v[36:39], v[188:191], v[218:221], v[36:39]
	v_mfma_f32_16x16x32_bf16 v[32:35], v[202:205], v[218:221], v[32:35]
	v_mfma_f32_16x16x32_bf16 v[12:15], v[188:191], v[226:229], v[12:15]
	v_mfma_f32_16x16x32_bf16 v[8:11], v[202:205], v[226:229], v[8:11]
	v_mfma_f32_16x16x32_bf16 v[20:23], v[188:191], v[234:237], v[20:23]
	v_mfma_f32_16x16x32_bf16 v[16:19], v[202:205], v[234:237], v[16:19]
	v_mfma_f32_16x16x32_bf16 v[52:55], v[198:201], v[214:217], v[52:55]
	v_mfma_f32_16x16x32_bf16 v[48:51], v[206:209], v[214:217], v[48:51]
	v_mfma_f32_16x16x32_bf16 v[36:39], v[198:201], v[222:225], v[36:39]
	v_mfma_f32_16x16x32_bf16 v[32:35], v[206:209], v[222:225], v[32:35]
	v_mfma_f32_16x16x32_bf16 v[12:15], v[198:201], v[230:233], v[12:15]
	v_mfma_f32_16x16x32_bf16 v[8:11], v[206:209], v[230:233], v[8:11]
	v_mfma_f32_16x16x32_bf16 v[20:23], v[198:201], v[238:241], v[20:23]
	v_mfma_f32_16x16x32_bf16 v[16:19], v[206:209], v[238:241], v[16:19]
	s_setprio 0
	s_barrier
	s_add_i32 s45, 0, 0x18000
	s_add_i32 s15, 0, 0x1c000
	v_add_u32_e32 v171, s45, v166
	v_add_u32_e32 v172, s15, v166
	ds_read_b128 v[174:177], v171
	ds_read_b128 v[178:181], v171 offset:1024
	ds_read_b128 v[182:185], v171 offset:2048
	ds_read_b128 v[186:189], v171 offset:3072
	ds_read_b128 v[198:201], v172
	ds_read_b128 v[202:205], v172 offset:1024
	ds_read_b128 v[206:209], v172 offset:2048
	ds_read_b128 v[210:213], v172 offset:3072
	s_mov_b32 m0, s64
	v_lshl_add_u64 v[190:191], v[146:147], 0, s[34:35]
	ds_read_b128 v[214:217], v168 offset:32768
	ds_read_b128 v[218:221], v168 offset:33792
	ds_read_b128 v[222:225], v168 offset:34816
	ds_read_b128 v[226:229], v168 offset:35840
	ds_read_b128 v[230:233], v168 offset:36864
	ds_read_b128 v[234:237], v168 offset:37888
	ds_read_b128 v[238:241], v168 offset:38912
	ds_read_b128 v[242:245], v168 offset:39936
	global_load_lds_dwordx4 v[190:191], off
	v_lshl_add_u64 v[190:191], v[154:155], 0, s[34:35]
	s_mov_b32 m0, s65
	s_nop 0
	global_load_lds_dwordx4 v[190:191], off
	s_waitcnt vmcnt(8)
	s_waitcnt lgkmcnt(0)
	s_barrier
	s_setprio 1
	s_waitcnt lgkmcnt(0)
	v_mfma_f32_16x16x32_bf16 v[136:139], v[174:177], v[214:217], v[136:139]
	v_mfma_f32_16x16x32_bf16 v[132:135], v[182:185], v[214:217], v[132:135]
	v_mfma_f32_16x16x32_bf16 v[116:119], v[174:177], v[222:225], v[116:119]
	v_mfma_f32_16x16x32_bf16 v[112:115], v[182:185], v[222:225], v[112:115]
	v_mfma_f32_16x16x32_bf16 v[96:99], v[174:177], v[230:233], v[96:99]
	v_mfma_f32_16x16x32_bf16 v[92:95], v[182:185], v[230:233], v[92:95]
	v_mfma_f32_16x16x32_bf16 v[76:79], v[174:177], v[238:241], v[76:79]
	v_mfma_f32_16x16x32_bf16 v[72:75], v[182:185], v[238:241], v[72:75]
	v_mfma_f32_16x16x32_bf16 v[136:139], v[178:181], v[218:221], v[136:139]
	v_mfma_f32_16x16x32_bf16 v[132:135], v[186:189], v[218:221], v[132:135]
	v_mfma_f32_16x16x32_bf16 v[116:119], v[178:181], v[226:229], v[116:119]
	v_mfma_f32_16x16x32_bf16 v[112:115], v[186:189], v[226:229], v[112:115]
	v_mfma_f32_16x16x32_bf16 v[96:99], v[178:181], v[234:237], v[96:99]
	v_mfma_f32_16x16x32_bf16 v[92:95], v[186:189], v[234:237], v[92:95]
	v_mfma_f32_16x16x32_bf16 v[76:79], v[178:181], v[242:245], v[76:79]
	v_mfma_f32_16x16x32_bf16 v[72:75], v[186:189], v[242:245], v[72:75]
	s_setprio 0
	s_setprio 1
	v_mfma_f32_16x16x32_bf16 v[124:127], v[198:201], v[214:217], v[124:127]
	v_mfma_f32_16x16x32_bf16 v[120:123], v[206:209], v[214:217], v[120:123]
	v_mfma_f32_16x16x32_bf16 v[104:107], v[198:201], v[222:225], v[104:107]
	v_mfma_f32_16x16x32_bf16 v[100:103], v[206:209], v[222:225], v[100:103]
	v_mfma_f32_16x16x32_bf16 v[84:87], v[198:201], v[230:233], v[84:87]
	v_mfma_f32_16x16x32_bf16 v[80:83], v[206:209], v[230:233], v[80:83]
	v_mfma_f32_16x16x32_bf16 v[68:71], v[198:201], v[238:241], v[68:71]
	v_mfma_f32_16x16x32_bf16 v[64:67], v[206:209], v[238:241], v[64:67]
	v_mfma_f32_16x16x32_bf16 v[124:127], v[202:205], v[218:221], v[124:127]
	v_mfma_f32_16x16x32_bf16 v[120:123], v[210:213], v[218:221], v[120:123]
	v_mfma_f32_16x16x32_bf16 v[104:107], v[202:205], v[226:229], v[104:107]
	v_mfma_f32_16x16x32_bf16 v[100:103], v[210:213], v[226:229], v[100:103]
	v_mfma_f32_16x16x32_bf16 v[84:87], v[202:205], v[234:237], v[84:87]
	v_mfma_f32_16x16x32_bf16 v[80:83], v[210:213], v[234:237], v[80:83]
	v_mfma_f32_16x16x32_bf16 v[68:71], v[202:205], v[242:245], v[68:71]
	v_mfma_f32_16x16x32_bf16 v[64:67], v[210:213], v[242:245], v[64:67]
	s_setprio 0
	s_barrier
	s_add_i32 s45, s45, s25
	v_lshl_add_u64 v[190:191], v[246:247], 0, s[58:59]
	s_mov_b32 m0, s45
	s_add_i32 s30, s45, 0x2000
	ds_read_b128 v[214:217], v168 offset:49152
	ds_read_b128 v[218:221], v168 offset:50176
	ds_read_b128 v[222:225], v168 offset:51200
	ds_read_b128 v[226:229], v168 offset:52224
	ds_read_b128 v[230:233], v168 offset:53248
	ds_read_b128 v[234:237], v168 offset:54272
	ds_read_b128 v[238:241], v168 offset:55296
	ds_read_b128 v[242:245], v168 offset:56320
	global_load_lds_dwordx4 v[190:191], off
	v_lshl_add_u64 v[190:191], v[248:249], 0, s[58:59]
	s_mov_b32 m0, s30
	s_add_i32 s15, s15, s25
	global_load_lds_dwordx4 v[190:191], off
	v_lshl_add_u64 v[190:191], v[246:247], 0, s[82:83]
	s_mov_b32 m0, s15
	s_add_i32 s17, s15, 0x2000
	global_load_lds_dwordx4 v[190:191], off
	v_lshl_add_u64 v[190:191], v[248:249], 0, s[82:83]
	s_mov_b32 m0, s17
	v_lshl_add_u64 v[146:147], v[146:147], 0, s[58:59]
	global_load_lds_dwordx4 v[190:191], off
	s_mov_b32 m0, s68
	s_nop 0
	global_load_lds_dwordx4 v[146:147], off
	v_lshl_add_u64 v[146:147], v[154:155], 0, s[58:59]
	s_mov_b32 m0, s69
	s_nop 0
	global_load_lds_dwordx4 v[146:147], off
	s_waitcnt vmcnt(8)
	s_waitcnt lgkmcnt(0)
	s_barrier
	s_setprio 1
	s_waitcnt lgkmcnt(0)
	v_mfma_f32_16x16x32_bf16 v[60:63], v[174:177], v[214:217], v[60:63]
	v_mfma_f32_16x16x32_bf16 v[56:59], v[182:185], v[214:217], v[56:59]
	v_mfma_f32_16x16x32_bf16 v[44:47], v[174:177], v[222:225], v[44:47]
	v_mfma_f32_16x16x32_bf16 v[40:43], v[182:185], v[222:225], v[40:43]
	v_mfma_f32_16x16x32_bf16 v[28:31], v[174:177], v[230:233], v[28:31]
	v_mfma_f32_16x16x32_bf16 v[24:27], v[182:185], v[230:233], v[24:27]
	v_mfma_f32_16x16x32_bf16 v[4:7], v[174:177], v[238:241], v[4:7]
	v_mfma_f32_16x16x32_bf16 v[0:3], v[182:185], v[238:241], v[0:3]
	v_mfma_f32_16x16x32_bf16 v[60:63], v[178:181], v[218:221], v[60:63]
	v_mfma_f32_16x16x32_bf16 v[56:59], v[186:189], v[218:221], v[56:59]
	v_mfma_f32_16x16x32_bf16 v[44:47], v[178:181], v[226:229], v[44:47]
	v_mfma_f32_16x16x32_bf16 v[40:43], v[186:189], v[226:229], v[40:43]
	v_mfma_f32_16x16x32_bf16 v[28:31], v[178:181], v[234:237], v[28:31]
	v_mfma_f32_16x16x32_bf16 v[24:27], v[186:189], v[234:237], v[24:27]
	v_mfma_f32_16x16x32_bf16 v[4:7], v[178:181], v[242:245], v[4:7]
	v_mfma_f32_16x16x32_bf16 v[0:3], v[186:189], v[242:245], v[0:3]
	s_setprio 0
	s_setprio 1
	v_mfma_f32_16x16x32_bf16 v[52:55], v[198:201], v[214:217], v[52:55]
	s_add_i32 s3, s3, 2
	s_add_u32 s48, s48, 0x100
	s_addc_u32 s49, s49, 0
	s_cmp_gt_u32 s3, 11
	v_mfma_f32_16x16x32_bf16 v[48:51], v[206:209], v[214:217], v[48:51]
	v_mfma_f32_16x16x32_bf16 v[36:39], v[198:201], v[222:225], v[36:39]
	v_mfma_f32_16x16x32_bf16 v[32:35], v[206:209], v[222:225], v[32:35]
	v_mfma_f32_16x16x32_bf16 v[12:15], v[198:201], v[230:233], v[12:15]
	v_mfma_f32_16x16x32_bf16 v[8:11], v[206:209], v[230:233], v[8:11]
	v_mfma_f32_16x16x32_bf16 v[20:23], v[198:201], v[238:241], v[20:23]
	v_mfma_f32_16x16x32_bf16 v[16:19], v[206:209], v[238:241], v[16:19]
	v_mfma_f32_16x16x32_bf16 v[52:55], v[202:205], v[218:221], v[52:55]
	v_mfma_f32_16x16x32_bf16 v[48:51], v[210:213], v[218:221], v[48:51]
	v_mfma_f32_16x16x32_bf16 v[36:39], v[202:205], v[226:229], v[36:39]
	v_mfma_f32_16x16x32_bf16 v[32:35], v[210:213], v[226:229], v[32:35]
	v_mfma_f32_16x16x32_bf16 v[12:15], v[202:205], v[234:237], v[12:15]
	v_mfma_f32_16x16x32_bf16 v[8:11], v[210:213], v[234:237], v[8:11]
	v_mfma_f32_16x16x32_bf16 v[20:23], v[202:205], v[242:245], v[20:23]
	v_mfma_f32_16x16x32_bf16 v[16:19], v[210:213], v[242:245], v[16:19]
	s_setprio 0
	s_barrier
	s_cbranch_scc0 .LBB0_876
	ds_read_b128 v[156:159], v169
	ds_read_b128 v[174:177], v169 offset:1024
	ds_read_b128 v[178:181], v169 offset:2048
	ds_read_b128 v[182:185], v169 offset:3072
	ds_read_b128 v[186:189], v170
	ds_read_b128 v[198:201], v170 offset:1024
	ds_read_b128 v[202:205], v170 offset:2048
	ds_read_b128 v[206:209], v170 offset:3072
	s_ashr_i32 s5, s4, 31
	s_ashr_i32 s3, s2, 31
	s_lshl_b64 s[6:7], s[2:3], 9
	s_lshl_b64 s[8:9], s[4:5], 19
	s_add_u32 s3, s60, s8
	s_addc_u32 s5, s61, s9
	s_add_u32 s6, s3, s6
	s_addc_u32 s7, s5, s7
	s_add_u32 s8, s42, 0xc0780
	s_addc_u32 s9, s43, 0
	s_mov_b32 m0, s33
	v_lshl_add_u64 v[142:143], s[8:9], 0, v[144:145]
	ds_read_b128 v[210:213], v168
	ds_read_b128 v[214:217], v168 offset:1024
	ds_read_b128 v[218:221], v168 offset:2048
	ds_read_b128 v[222:225], v168 offset:3072
	ds_read_b128 v[226:229], v168 offset:4096
	ds_read_b128 v[230:233], v168 offset:5120
	ds_read_b128 v[234:237], v168 offset:6144
	ds_read_b128 v[238:241], v168 offset:7168
	global_load_lds_dwordx4 v[142:143], off
	v_lshl_add_u64 v[142:143], s[8:9], 0, v[88:89]
	s_mov_b32 m0, s11
	s_nop 0
	global_load_lds_dwordx4 v[142:143], off
	s_waitcnt vmcnt(8)
	s_waitcnt lgkmcnt(0)
	s_barrier
	s_setprio 1
	s_waitcnt lgkmcnt(0)
	v_mfma_f32_16x16x32_bf16 v[136:139], v[156:159], v[210:213], v[136:139]
	v_mfma_f32_16x16x32_bf16 v[132:135], v[178:181], v[210:213], v[132:135]
	v_mfma_f32_16x16x32_bf16 v[116:119], v[156:159], v[218:221], v[116:119]
	v_mfma_f32_16x16x32_bf16 v[112:115], v[178:181], v[218:221], v[112:115]
	v_mfma_f32_16x16x32_bf16 v[96:99], v[156:159], v[226:229], v[96:99]
	v_mfma_f32_16x16x32_bf16 v[92:95], v[178:181], v[226:229], v[92:95]
	v_mfma_f32_16x16x32_bf16 v[76:79], v[156:159], v[234:237], v[76:79]
	v_mfma_f32_16x16x32_bf16 v[72:75], v[178:181], v[234:237], v[72:75]
	v_mfma_f32_16x16x32_bf16 v[136:139], v[174:177], v[214:217], v[136:139]
	v_mfma_f32_16x16x32_bf16 v[132:135], v[182:185], v[214:217], v[132:135]
	v_mfma_f32_16x16x32_bf16 v[116:119], v[174:177], v[222:225], v[116:119]
	v_mfma_f32_16x16x32_bf16 v[112:115], v[182:185], v[222:225], v[112:115]
	v_mfma_f32_16x16x32_bf16 v[96:99], v[174:177], v[230:233], v[96:99]
	v_mfma_f32_16x16x32_bf16 v[92:95], v[182:185], v[230:233], v[92:95]
	v_mfma_f32_16x16x32_bf16 v[76:79], v[174:177], v[238:241], v[76:79]
	v_mfma_f32_16x16x32_bf16 v[72:75], v[182:185], v[238:241], v[72:75]
	s_setprio 0
	s_setprio 1
	v_mfma_f32_16x16x32_bf16 v[124:127], v[186:189], v[210:213], v[124:127]
	v_mfma_f32_16x16x32_bf16 v[120:123], v[202:205], v[210:213], v[120:123]
	v_mfma_f32_16x16x32_bf16 v[104:107], v[186:189], v[218:221], v[104:107]
	v_mfma_f32_16x16x32_bf16 v[100:103], v[202:205], v[218:221], v[100:103]
	v_mfma_f32_16x16x32_bf16 v[84:87], v[186:189], v[226:229], v[84:87]
	v_mfma_f32_16x16x32_bf16 v[80:83], v[202:205], v[226:229], v[80:83]
	v_mfma_f32_16x16x32_bf16 v[68:71], v[186:189], v[234:237], v[68:71]
	v_mfma_f32_16x16x32_bf16 v[64:67], v[202:205], v[234:237], v[64:67]
	v_mfma_f32_16x16x32_bf16 v[124:127], v[198:201], v[214:217], v[124:127]
	v_mfma_f32_16x16x32_bf16 v[120:123], v[206:209], v[214:217], v[120:123]
	v_mfma_f32_16x16x32_bf16 v[104:107], v[198:201], v[222:225], v[104:107]
	v_mfma_f32_16x16x32_bf16 v[100:103], v[206:209], v[222:225], v[100:103]
	v_mfma_f32_16x16x32_bf16 v[84:87], v[198:201], v[230:233], v[84:87]
	v_mfma_f32_16x16x32_bf16 v[80:83], v[206:209], v[230:233], v[80:83]
	v_mfma_f32_16x16x32_bf16 v[68:71], v[198:201], v[238:241], v[68:71]
	v_mfma_f32_16x16x32_bf16 v[64:67], v[206:209], v[238:241], v[64:67]
	s_setprio 0
	s_barrier
	s_mov_b32 m0, s31
	v_lshl_add_u64 v[142:143], s[6:7], 0, v[90:91]
	ds_read_b128 v[210:213], v168 offset:16384
	ds_read_b128 v[214:217], v168 offset:17408
	ds_read_b128 v[218:221], v168 offset:18432
	ds_read_b128 v[222:225], v168 offset:19456
	ds_read_b128 v[226:229], v168 offset:20480
	ds_read_b128 v[230:233], v168 offset:21504
	ds_read_b128 v[234:237], v168 offset:22528
	ds_read_b128 v[238:241], v168 offset:23552
	global_load_lds_dwordx4 v[142:143], off
	v_lshl_add_u64 v[146:147], s[6:7], 0, v[108:109]
	s_mov_b32 m0, s14
	v_lshl_add_u64 v[154:155], v[142:143], 0, s[70:71]
	global_load_lds_dwordx4 v[146:147], off
	s_mov_b32 m0, s16
	s_nop 0
	global_load_lds_dwordx4 v[154:155], off
	v_lshl_add_u64 v[154:155], v[146:147], 0, s[70:71]
	s_mov_b32 m0, s23
	s_nop 0
	global_load_lds_dwordx4 v[154:155], off
	v_lshl_add_u64 v[154:155], v[142:143], 0, s[96:97]
	s_mov_b32 m0, s50
	s_nop 0
	global_load_lds_dwordx4 v[154:155], off
	v_lshl_add_u64 v[154:155], v[146:147], 0, s[96:97]
	s_mov_b32 m0, s51
	s_nop 0
	global_load_lds_dwordx4 v[154:155], off
	s_waitcnt vmcnt(8)
	s_waitcnt lgkmcnt(0)
	s_barrier
	s_setprio 1
	s_waitcnt lgkmcnt(0)
	v_mfma_f32_16x16x32_bf16 v[60:63], v[156:159], v[210:213], v[60:63]
	v_mfma_f32_16x16x32_bf16 v[56:59], v[178:181], v[210:213], v[56:59]
	v_mfma_f32_16x16x32_bf16 v[44:47], v[156:159], v[218:221], v[44:47]
	v_mfma_f32_16x16x32_bf16 v[40:43], v[178:181], v[218:221], v[40:43]
	v_mfma_f32_16x16x32_bf16 v[28:31], v[156:159], v[226:229], v[28:31]
	v_mfma_f32_16x16x32_bf16 v[24:27], v[178:181], v[226:229], v[24:27]
	v_mfma_f32_16x16x32_bf16 v[4:7], v[156:159], v[234:237], v[4:7]
	v_mfma_f32_16x16x32_bf16 v[0:3], v[178:181], v[234:237], v[0:3]
	v_mfma_f32_16x16x32_bf16 v[60:63], v[174:177], v[214:217], v[60:63]
	v_mfma_f32_16x16x32_bf16 v[56:59], v[182:185], v[214:217], v[56:59]
	v_mfma_f32_16x16x32_bf16 v[44:47], v[174:177], v[222:225], v[44:47]
	v_mfma_f32_16x16x32_bf16 v[40:43], v[182:185], v[222:225], v[40:43]
	v_mfma_f32_16x16x32_bf16 v[28:31], v[174:177], v[230:233], v[28:31]
	v_mfma_f32_16x16x32_bf16 v[24:27], v[182:185], v[230:233], v[24:27]
	v_mfma_f32_16x16x32_bf16 v[4:7], v[174:177], v[238:241], v[4:7]
	v_mfma_f32_16x16x32_bf16 v[0:3], v[182:185], v[238:241], v[0:3]
	s_setprio 0
	s_setprio 1
	v_mfma_f32_16x16x32_bf16 v[52:55], v[186:189], v[210:213], v[52:55]
	v_mfma_f32_16x16x32_bf16 v[48:51], v[202:205], v[210:213], v[48:51]
	v_mfma_f32_16x16x32_bf16 v[36:39], v[186:189], v[218:221], v[36:39]
	v_mfma_f32_16x16x32_bf16 v[32:35], v[202:205], v[218:221], v[32:35]
	v_mfma_f32_16x16x32_bf16 v[12:15], v[186:189], v[226:229], v[12:15]
	v_mfma_f32_16x16x32_bf16 v[8:11], v[202:205], v[226:229], v[8:11]
	v_mfma_f32_16x16x32_bf16 v[20:23], v[186:189], v[234:237], v[20:23]
	v_mfma_f32_16x16x32_bf16 v[16:19], v[202:205], v[234:237], v[16:19]
	v_mfma_f32_16x16x32_bf16 v[52:55], v[198:201], v[214:217], v[52:55]
	v_mfma_f32_16x16x32_bf16 v[48:51], v[206:209], v[214:217], v[48:51]
	v_mfma_f32_16x16x32_bf16 v[36:39], v[198:201], v[222:225], v[36:39]
	v_mfma_f32_16x16x32_bf16 v[32:35], v[206:209], v[222:225], v[32:35]
	v_mfma_f32_16x16x32_bf16 v[12:15], v[198:201], v[230:233], v[12:15]
	v_mfma_f32_16x16x32_bf16 v[8:11], v[206:209], v[230:233], v[8:11]
	v_mfma_f32_16x16x32_bf16 v[20:23], v[198:201], v[238:241], v[20:23]
	v_mfma_f32_16x16x32_bf16 v[16:19], v[206:209], v[238:241], v[16:19]
	s_setprio 0
	s_barrier
	ds_read_b128 v[156:159], v171
	ds_read_b128 v[174:177], v171 offset:1024
	ds_read_b128 v[178:181], v171 offset:2048
	ds_read_b128 v[182:185], v171 offset:3072
	ds_read_b128 v[186:189], v172
	ds_read_b128 v[198:201], v172 offset:1024
	ds_read_b128 v[202:205], v172 offset:2048
	ds_read_b128 v[170:173], v172 offset:3072
	s_mov_b32 m0, s64
	v_lshl_add_u64 v[142:143], v[142:143], 0, s[58:59]
	ds_read_b128 v[206:209], v168 offset:32768
	ds_read_b128 v[210:213], v168 offset:33792
	ds_read_b128 v[214:217], v168 offset:34816
	ds_read_b128 v[218:221], v168 offset:35840
	ds_read_b128 v[222:225], v168 offset:36864
	ds_read_b128 v[226:229], v168 offset:37888
	ds_read_b128 v[230:233], v168 offset:38912
	ds_read_b128 v[234:237], v168 offset:39936
	global_load_lds_dwordx4 v[142:143], off
	v_lshl_add_u64 v[142:143], v[146:147], 0, s[58:59]
	s_mov_b32 m0, s65
	s_nop 0
	global_load_lds_dwordx4 v[142:143], off
	s_waitcnt vmcnt(8)
	s_waitcnt lgkmcnt(0)
	s_barrier
	s_setprio 1
	s_waitcnt lgkmcnt(0)
	v_mfma_f32_16x16x32_bf16 v[136:139], v[156:159], v[206:209], v[136:139]
	v_mfma_f32_16x16x32_bf16 v[132:135], v[178:181], v[206:209], v[132:135]
	v_mfma_f32_16x16x32_bf16 v[116:119], v[156:159], v[214:217], v[116:119]
	v_mfma_f32_16x16x32_bf16 v[112:115], v[178:181], v[214:217], v[112:115]
	v_mfma_f32_16x16x32_bf16 v[96:99], v[156:159], v[222:225], v[96:99]
	v_mfma_f32_16x16x32_bf16 v[92:95], v[178:181], v[222:225], v[92:95]
	v_mfma_f32_16x16x32_bf16 v[76:79], v[156:159], v[230:233], v[76:79]
	v_mfma_f32_16x16x32_bf16 v[72:75], v[178:181], v[230:233], v[72:75]
	v_mfma_f32_16x16x32_bf16 v[136:139], v[174:177], v[210:213], v[136:139]
	v_mfma_f32_16x16x32_bf16 v[132:135], v[182:185], v[210:213], v[132:135]
	v_mfma_f32_16x16x32_bf16 v[116:119], v[174:177], v[218:221], v[116:119]
	v_mfma_f32_16x16x32_bf16 v[112:115], v[182:185], v[218:221], v[112:115]
	v_mfma_f32_16x16x32_bf16 v[96:99], v[174:177], v[226:229], v[96:99]
	v_mfma_f32_16x16x32_bf16 v[92:95], v[182:185], v[226:229], v[92:95]
	v_mfma_f32_16x16x32_bf16 v[76:79], v[174:177], v[234:237], v[76:79]
	v_mfma_f32_16x16x32_bf16 v[72:75], v[182:185], v[234:237], v[72:75]
	s_setprio 0
	s_setprio 1
	v_mfma_f32_16x16x32_bf16 v[124:127], v[186:189], v[206:209], v[124:127]
	v_mfma_f32_16x16x32_bf16 v[120:123], v[202:205], v[206:209], v[120:123]
	v_mfma_f32_16x16x32_bf16 v[104:107], v[186:189], v[214:217], v[104:107]
	v_mfma_f32_16x16x32_bf16 v[100:103], v[202:205], v[214:217], v[100:103]
	v_mfma_f32_16x16x32_bf16 v[84:87], v[186:189], v[222:225], v[84:87]
	v_mfma_f32_16x16x32_bf16 v[80:83], v[202:205], v[222:225], v[80:83]
	v_mfma_f32_16x16x32_bf16 v[68:71], v[186:189], v[230:233], v[68:71]
	v_mfma_f32_16x16x32_bf16 v[64:67], v[202:205], v[230:233], v[64:67]
	v_mfma_f32_16x16x32_bf16 v[124:127], v[198:201], v[210:213], v[124:127]
	v_mfma_f32_16x16x32_bf16 v[120:123], v[170:173], v[210:213], v[120:123]
	v_mfma_f32_16x16x32_bf16 v[104:107], v[198:201], v[218:221], v[104:107]
	v_mfma_f32_16x16x32_bf16 v[100:103], v[170:173], v[218:221], v[100:103]
	v_mfma_f32_16x16x32_bf16 v[84:87], v[198:201], v[226:229], v[84:87]
	v_mfma_f32_16x16x32_bf16 v[80:83], v[170:173], v[226:229], v[80:83]
	v_mfma_f32_16x16x32_bf16 v[68:71], v[198:201], v[234:237], v[68:71]
	v_mfma_f32_16x16x32_bf16 v[64:67], v[170:173], v[234:237], v[64:67]
	s_setprio 0
	s_barrier
	s_add_u32 s8, s6, 0x40000
	s_addc_u32 s9, s7, 0
	s_mov_b32 m0, s45
	v_lshl_add_u64 v[142:143], s[8:9], 0, v[90:91]
	ds_read_b128 v[206:209], v168 offset:49152
	ds_read_b128 v[210:213], v168 offset:50176
	ds_read_b128 v[214:217], v168 offset:51200
	ds_read_b128 v[218:221], v168 offset:52224
	ds_read_b128 v[222:225], v168 offset:53248
	ds_read_b128 v[226:229], v168 offset:54272
	ds_read_b128 v[230:233], v168 offset:55296
	ds_read_b128 v[234:237], v168 offset:56320
	global_load_lds_dwordx4 v[142:143], off
	v_lshl_add_u64 v[142:143], s[8:9], 0, v[108:109]
	s_add_u32 s8, s6, 0x40080
	s_mov_b32 m0, s30
	s_addc_u32 s9, s7, 0
	global_load_lds_dwordx4 v[142:143], off
	v_lshl_add_u64 v[142:143], s[8:9], 0, v[90:91]
	s_mov_b32 m0, s15
	s_add_u32 s6, s6, 0x40100
	global_load_lds_dwordx4 v[142:143], off
	v_lshl_add_u64 v[142:143], s[8:9], 0, v[108:109]
	s_mov_b32 m0, s17
	s_addc_u32 s7, s7, 0
	global_load_lds_dwordx4 v[142:143], off
	v_lshl_add_u64 v[142:143], s[6:7], 0, v[90:91]
	s_mov_b32 m0, s68
	s_nop 0
	global_load_lds_dwordx4 v[142:143], off
	v_lshl_add_u64 v[142:143], s[6:7], 0, v[108:109]
	s_mov_b32 m0, s69
	s_nop 0
	global_load_lds_dwordx4 v[142:143], off
	s_waitcnt vmcnt(8)
	s_waitcnt lgkmcnt(0)
	s_barrier
	s_setprio 1
	s_waitcnt lgkmcnt(0)
	v_mfma_f32_16x16x32_bf16 v[60:63], v[156:159], v[206:209], v[60:63]
	v_mfma_f32_16x16x32_bf16 v[56:59], v[178:181], v[206:209], v[56:59]
	v_mfma_f32_16x16x32_bf16 v[44:47], v[156:159], v[214:217], v[44:47]
	v_mfma_f32_16x16x32_bf16 v[40:43], v[178:181], v[214:217], v[40:43]
	v_mfma_f32_16x16x32_bf16 v[28:31], v[156:159], v[222:225], v[28:31]
	v_mfma_f32_16x16x32_bf16 v[24:27], v[178:181], v[222:225], v[24:27]
	v_mfma_f32_16x16x32_bf16 v[4:7], v[156:159], v[230:233], v[4:7]
	v_mfma_f32_16x16x32_bf16 v[0:3], v[178:181], v[230:233], v[0:3]
	v_mfma_f32_16x16x32_bf16 v[60:63], v[174:177], v[210:213], v[60:63]
	v_mfma_f32_16x16x32_bf16 v[56:59], v[182:185], v[210:213], v[56:59]
	v_mfma_f32_16x16x32_bf16 v[44:47], v[174:177], v[218:221], v[44:47]
	v_mfma_f32_16x16x32_bf16 v[40:43], v[182:185], v[218:221], v[40:43]
	v_mfma_f32_16x16x32_bf16 v[28:31], v[174:177], v[226:229], v[28:31]
	v_mfma_f32_16x16x32_bf16 v[24:27], v[182:185], v[226:229], v[24:27]
	v_mfma_f32_16x16x32_bf16 v[4:7], v[174:177], v[234:237], v[4:7]
	v_mfma_f32_16x16x32_bf16 v[0:3], v[182:185], v[234:237], v[0:3]
	s_setprio 0
	s_setprio 1
	v_mfma_f32_16x16x32_bf16 v[52:55], v[186:189], v[206:209], v[52:55]
	v_mfma_f32_16x16x32_bf16 v[48:51], v[202:205], v[206:209], v[48:51]
	v_mfma_f32_16x16x32_bf16 v[36:39], v[186:189], v[214:217], v[36:39]
	v_mfma_f32_16x16x32_bf16 v[32:35], v[202:205], v[214:217], v[32:35]
	v_mfma_f32_16x16x32_bf16 v[12:15], v[186:189], v[222:225], v[12:15]
	v_mfma_f32_16x16x32_bf16 v[8:11], v[202:205], v[222:225], v[8:11]
	v_mfma_f32_16x16x32_bf16 v[20:23], v[186:189], v[230:233], v[20:23]
	v_mfma_f32_16x16x32_bf16 v[16:19], v[202:205], v[230:233], v[16:19]
	v_mfma_f32_16x16x32_bf16 v[52:55], v[198:201], v[210:213], v[52:55]
	v_mfma_f32_16x16x32_bf16 v[48:51], v[170:173], v[210:213], v[48:51]
	v_mfma_f32_16x16x32_bf16 v[36:39], v[198:201], v[218:221], v[36:39]
	v_mfma_f32_16x16x32_bf16 v[32:35], v[170:173], v[218:221], v[32:35]
	v_mfma_f32_16x16x32_bf16 v[12:15], v[198:201], v[226:229], v[12:15]
	v_mfma_f32_16x16x32_bf16 v[8:11], v[170:173], v[226:229], v[8:11]
	v_mfma_f32_16x16x32_bf16 v[20:23], v[198:201], v[234:237], v[20:23]
	v_mfma_f32_16x16x32_bf16 v[16:19], v[170:173], v[234:237], v[16:19]
	s_setprio 0
	s_barrier
	s_and_b64 vcc, exec, s[38:39]
	s_cbranch_vccz .LBB0_864
	s_nop 1
	v_mov_b32_e32 v8, 0
	s_mov_b32 s4, s85
	s_mov_b32 s2, s44
	s_mov_b64 s[12:13], s[40:41]
	s_mov_b64 s[42:43], s[46:47]
	s_mov_b32 s84, s10
	v_mov_b32_e32 v9, v8
	v_mov_b32_e32 v10, v8
	v_mov_b32_e32 v11, v8
	v_mov_b32_e32 v12, v8
	v_mov_b32_e32 v13, v8
	v_mov_b32_e32 v14, v8
	v_mov_b32_e32 v15, v8
	v_mov_b32_e32 v32, v8
	v_mov_b32_e32 v33, v8
	v_mov_b32_e32 v34, v8
	v_mov_b32_e32 v35, v8
	v_mov_b32_e32 v36, v8
	v_mov_b32_e32 v37, v8
	v_mov_b32_e32 v38, v8
	v_mov_b32_e32 v39, v8
	v_mov_b32_e32 v48, v8
	v_mov_b32_e32 v49, v8
	v_mov_b32_e32 v50, v8
	v_mov_b32_e32 v51, v8
	v_mov_b32_e32 v52, v8
	v_mov_b32_e32 v53, v8
	v_mov_b32_e32 v54, v8
	v_mov_b32_e32 v55, v8
	v_mov_b32_e32 v0, v8
	v_mov_b32_e32 v1, v8
	v_mov_b32_e32 v2, v8
	v_mov_b32_e32 v3, v8
	v_mov_b32_e32 v4, v8
	v_mov_b32_e32 v5, v8
	v_mov_b32_e32 v6, v8
	v_mov_b32_e32 v7, v8
	v_mov_b32_e32 v24, v8
	v_mov_b32_e32 v25, v8
	v_mov_b32_e32 v26, v8
	v_mov_b32_e32 v27, v8
	v_mov_b32_e32 v28, v8
	v_mov_b32_e32 v29, v8
	v_mov_b32_e32 v30, v8
	v_mov_b32_e32 v31, v8
	v_mov_b32_e32 v40, v8
	v_mov_b32_e32 v41, v8
	v_mov_b32_e32 v42, v8
	v_mov_b32_e32 v43, v8
	v_mov_b32_e32 v44, v8
	v_mov_b32_e32 v45, v8
	v_mov_b32_e32 v46, v8
	v_mov_b32_e32 v47, v8
	v_mov_b32_e32 v56, v8
	v_mov_b32_e32 v57, v8
	v_mov_b32_e32 v58, v8
	v_mov_b32_e32 v59, v8
	v_mov_b32_e32 v60, v8
	v_mov_b32_e32 v61, v8
	v_mov_b32_e32 v62, v8
	v_mov_b32_e32 v63, v8
	v_mov_b32_e32 v64, v8
	v_mov_b32_e32 v65, v8
	v_mov_b32_e32 v66, v8
	v_mov_b32_e32 v67, v8
	v_mov_b32_e32 v68, v8
	v_mov_b32_e32 v69, v8
	v_mov_b32_e32 v70, v8
	v_mov_b32_e32 v71, v8
	v_mov_b32_e32 v80, v8
	v_mov_b32_e32 v81, v8
	v_mov_b32_e32 v82, v8
	v_mov_b32_e32 v83, v8
	v_mov_b32_e32 v84, v8
	v_mov_b32_e32 v85, v8
	v_mov_b32_e32 v86, v8
	v_mov_b32_e32 v87, v8
	v_mov_b32_e32 v100, v8
	v_mov_b32_e32 v101, v8
	v_mov_b32_e32 v102, v8
	v_mov_b32_e32 v103, v8
	v_mov_b32_e32 v104, v8
	v_mov_b32_e32 v105, v8
	v_mov_b32_e32 v106, v8
	v_mov_b32_e32 v107, v8
	v_mov_b32_e32 v120, v8
	v_mov_b32_e32 v121, v8
	v_mov_b32_e32 v122, v8
	v_mov_b32_e32 v123, v8
	v_mov_b32_e32 v124, v8
	v_mov_b32_e32 v125, v8
	v_mov_b32_e32 v126, v8
	v_mov_b32_e32 v127, v8
	v_mov_b32_e32 v72, v8
	v_mov_b32_e32 v73, v8
	v_mov_b32_e32 v74, v8
	v_mov_b32_e32 v75, v8
	v_mov_b32_e32 v76, v8
	v_mov_b32_e32 v77, v8
	v_mov_b32_e32 v78, v8
	v_mov_b32_e32 v79, v8
	v_mov_b32_e32 v92, v8
	v_mov_b32_e32 v93, v8
	v_mov_b32_e32 v94, v8
	v_mov_b32_e32 v95, v8
	v_mov_b32_e32 v96, v8
	v_mov_b32_e32 v97, v8
	v_mov_b32_e32 v98, v8
	v_mov_b32_e32 v99, v8
	v_mov_b32_e32 v112, v8
	v_mov_b32_e32 v113, v8
	v_mov_b32_e32 v114, v8
	v_mov_b32_e32 v115, v8
	v_mov_b32_e32 v116, v8
	v_mov_b32_e32 v117, v8
	v_mov_b32_e32 v118, v8
	v_mov_b32_e32 v119, v8
	v_mov_b32_e32 v132, v8
	v_mov_b32_e32 v133, v8
	v_mov_b32_e32 v134, v8
	v_mov_b32_e32 v135, v8
	v_mov_b32_e32 v136, v8
	v_mov_b32_e32 v137, v8
	v_mov_b32_e32 v138, v8
	v_mov_b32_e32 v139, v8
	v_mov_b32_e32 v20, v8
	v_mov_b32_e32 v21, v8
	v_mov_b32_e32 v22, v8
	v_mov_b32_e32 v23, v8
	v_mov_b32_e32 v16, v8
	v_mov_b32_e32 v17, v8
	v_mov_b32_e32 v18, v8
	v_mov_b32_e32 v19, v8
	s_branch .LBB0_864

.LBB0_993:
	s_add_u32 s6, s48, 0xfffc0080
	s_addc_u32 s7, s49, -1
	s_add_i32 s8, 0, 0x10000
	s_cmp_eq_u32 s31, 12
	s_cselect_b32 s19, s14, s7
	s_cselect_b32 s18, s15, s6
	v_add_u32_e32 v143, s8, v139
	s_cselect_b32 s7, s16, s30
	s_cselect_b32 s6, s17, s23
	s_add_i32 s27, 0, 0x14000
	ds_read_b128 v[156:159], v143
	ds_read_b128 v[160:163], v143 offset:1024
	ds_read_b128 v[164:167], v143 offset:2048
	ds_read_b128 v[168:171], v143 offset:3072
	v_add_u32_e32 v143, s27, v139
	ds_read_b128 v[172:175], v143
	ds_read_b128 v[176:179], v143 offset:1024
	ds_read_b128 v[180:183], v143 offset:2048
	ds_read_b128 v[184:187], v143 offset:3072
	v_lshl_add_u64 v[146:147], s[48:49], 0, v[134:135]
	s_add_i32 m0, s64, 0xc000
	ds_read_b128 v[188:191], v142
	ds_read_b128 v[198:201], v142 offset:1024
	ds_read_b128 v[202:205], v142 offset:2048
	ds_read_b128 v[206:209], v142 offset:3072
	ds_read_b128 v[210:213], v142 offset:4096
	ds_read_b128 v[214:217], v142 offset:5120
	ds_read_b128 v[218:221], v142 offset:6144
	ds_read_b128 v[222:225], v142 offset:7168
	global_load_lds_dwordx4 v[146:147], off
	v_lshl_add_u64 v[146:147], s[48:49], 0, v[136:137]
	s_add_i32 m0, s64, 0xe000
	s_nop 0
	global_load_lds_dwordx4 v[146:147], off
	s_waitcnt vmcnt(8)
	s_waitcnt lgkmcnt(0)
	s_barrier
	s_setprio 1
	s_waitcnt lgkmcnt(0)
	v_mfma_f32_16x16x32_bf16 v[124:127], v[156:159], v[188:191], v[124:127]
	v_mfma_f32_16x16x32_bf16 v[120:123], v[164:167], v[188:191], v[120:123]
	v_mfma_f32_16x16x32_bf16 v[108:111], v[156:159], v[202:205], v[108:111]
	v_mfma_f32_16x16x32_bf16 v[104:107], v[164:167], v[202:205], v[104:107]
	v_mfma_f32_16x16x32_bf16 v[92:95], v[156:159], v[210:213], v[92:95]
	v_mfma_f32_16x16x32_bf16 v[88:91], v[164:167], v[210:213], v[88:91]
	v_mfma_f32_16x16x32_bf16 v[76:79], v[156:159], v[218:221], v[76:79]
	v_mfma_f32_16x16x32_bf16 v[72:75], v[164:167], v[218:221], v[72:75]
	v_mfma_f32_16x16x32_bf16 v[124:127], v[160:163], v[198:201], v[124:127]
	v_mfma_f32_16x16x32_bf16 v[120:123], v[168:171], v[198:201], v[120:123]
	v_mfma_f32_16x16x32_bf16 v[108:111], v[160:163], v[206:209], v[108:111]
	v_mfma_f32_16x16x32_bf16 v[104:107], v[168:171], v[206:209], v[104:107]
	v_mfma_f32_16x16x32_bf16 v[92:95], v[160:163], v[214:217], v[92:95]
	v_mfma_f32_16x16x32_bf16 v[88:91], v[168:171], v[214:217], v[88:91]
	v_mfma_f32_16x16x32_bf16 v[76:79], v[160:163], v[222:225], v[76:79]
	v_mfma_f32_16x16x32_bf16 v[72:75], v[168:171], v[222:225], v[72:75]
	s_setprio 0
	s_setprio 1
	v_mfma_f32_16x16x32_bf16 v[116:119], v[172:175], v[188:191], v[116:119]
	v_mfma_f32_16x16x32_bf16 v[112:115], v[180:183], v[188:191], v[112:115]
	v_mfma_f32_16x16x32_bf16 v[100:103], v[172:175], v[202:205], v[100:103]
	v_mfma_f32_16x16x32_bf16 v[96:99], v[180:183], v[202:205], v[96:99]
	v_mfma_f32_16x16x32_bf16 v[84:87], v[172:175], v[210:213], v[84:87]
	v_mfma_f32_16x16x32_bf16 v[80:83], v[180:183], v[210:213], v[80:83]
	v_mfma_f32_16x16x32_bf16 v[68:71], v[172:175], v[218:221], v[68:71]
	v_mfma_f32_16x16x32_bf16 v[64:67], v[180:183], v[218:221], v[64:67]
	v_mfma_f32_16x16x32_bf16 v[116:119], v[176:179], v[198:201], v[116:119]
	v_mfma_f32_16x16x32_bf16 v[112:115], v[184:187], v[198:201], v[112:115]
	v_mfma_f32_16x16x32_bf16 v[100:103], v[176:179], v[206:209], v[100:103]
	v_mfma_f32_16x16x32_bf16 v[96:99], v[184:187], v[206:209], v[96:99]
	v_mfma_f32_16x16x32_bf16 v[84:87], v[176:179], v[214:217], v[84:87]
	v_mfma_f32_16x16x32_bf16 v[80:83], v[184:187], v[214:217], v[80:83]
	v_mfma_f32_16x16x32_bf16 v[68:71], v[176:179], v[222:225], v[68:71]
	v_mfma_f32_16x16x32_bf16 v[64:67], v[184:187], v[222:225], v[64:67]
	s_setprio 0
	s_barrier
	s_add_i32 s8, s8, s0
	v_lshl_add_u64 v[146:147], s[6:7], 0, v[144:145]
	s_mov_b32 m0, s8
	ds_read_b128 v[188:191], v142 offset:16384
	ds_read_b128 v[198:201], v142 offset:17408
	ds_read_b128 v[202:205], v142 offset:18432
	ds_read_b128 v[206:209], v142 offset:19456
	ds_read_b128 v[210:213], v142 offset:20480
	ds_read_b128 v[214:217], v142 offset:21504
	ds_read_b128 v[218:221], v142 offset:22528
	ds_read_b128 v[222:225], v142 offset:23552
	global_load_lds_dwordx4 v[146:147], off
	s_add_i32 m0, s8, 0x2000
	s_add_u32 s8, s6, 0x40000
	v_lshl_add_u64 v[154:155], s[6:7], 0, v[128:129]
	s_addc_u32 s9, s7, 0
	s_add_i32 s27, s27, s0
	global_load_lds_dwordx4 v[154:155], off
	v_lshl_add_u64 v[226:227], s[8:9], 0, v[144:145]
	s_mov_b32 m0, s27
	v_lshl_add_u64 v[228:229], s[18:19], 0, v[130:131]
	global_load_lds_dwordx4 v[226:227], off
	v_lshl_add_u64 v[226:227], s[8:9], 0, v[128:129]
	s_add_i32 m0, s27, 0x2000
	s_nop 0
	global_load_lds_dwordx4 v[226:227], off
	v_lshl_add_u64 v[226:227], s[18:19], 0, v[132:133]
	s_mov_b32 m0, s64
	s_nop 0
	global_load_lds_dwordx4 v[226:227], off
	s_mov_b32 m0, s65
	s_nop 0
	global_load_lds_dwordx4 v[228:229], off
	s_waitcnt vmcnt(8)
	s_waitcnt lgkmcnt(0)
	s_barrier
	s_setprio 1
	s_waitcnt lgkmcnt(0)
	v_mfma_f32_16x16x32_bf16 v[60:63], v[156:159], v[188:191], v[60:63]
	v_mfma_f32_16x16x32_bf16 v[56:59], v[164:167], v[188:191], v[56:59]
	v_mfma_f32_16x16x32_bf16 v[44:47], v[156:159], v[202:205], v[44:47]
	v_mfma_f32_16x16x32_bf16 v[40:43], v[164:167], v[202:205], v[40:43]
	v_mfma_f32_16x16x32_bf16 v[28:31], v[156:159], v[210:213], v[28:31]
	v_mfma_f32_16x16x32_bf16 v[24:27], v[164:167], v[210:213], v[24:27]
	v_mfma_f32_16x16x32_bf16 v[12:15], v[156:159], v[218:221], v[12:15]
	v_mfma_f32_16x16x32_bf16 v[8:11], v[164:167], v[218:221], v[8:11]
	v_mfma_f32_16x16x32_bf16 v[60:63], v[160:163], v[198:201], v[60:63]
	v_mfma_f32_16x16x32_bf16 v[56:59], v[168:171], v[198:201], v[56:59]
	v_mfma_f32_16x16x32_bf16 v[44:47], v[160:163], v[206:209], v[44:47]
	v_mfma_f32_16x16x32_bf16 v[40:43], v[168:171], v[206:209], v[40:43]
	v_mfma_f32_16x16x32_bf16 v[28:31], v[160:163], v[214:217], v[28:31]
	v_mfma_f32_16x16x32_bf16 v[24:27], v[168:171], v[214:217], v[24:27]
	v_mfma_f32_16x16x32_bf16 v[12:15], v[160:163], v[222:225], v[12:15]
	v_mfma_f32_16x16x32_bf16 v[8:11], v[168:171], v[222:225], v[8:11]
	s_setprio 0
	s_setprio 1
	v_mfma_f32_16x16x32_bf16 v[52:55], v[172:175], v[188:191], v[52:55]
	v_mfma_f32_16x16x32_bf16 v[48:51], v[180:183], v[188:191], v[48:51]
	v_mfma_f32_16x16x32_bf16 v[36:39], v[172:175], v[202:205], v[36:39]
	v_mfma_f32_16x16x32_bf16 v[32:35], v[180:183], v[202:205], v[32:35]
	v_mfma_f32_16x16x32_bf16 v[20:23], v[172:175], v[210:213], v[20:23]
	v_mfma_f32_16x16x32_bf16 v[16:19], v[180:183], v[210:213], v[16:19]
	v_mfma_f32_16x16x32_bf16 v[4:7], v[172:175], v[218:221], v[4:7]
	v_mfma_f32_16x16x32_bf16 v[0:3], v[180:183], v[218:221], v[0:3]
	v_mfma_f32_16x16x32_bf16 v[52:55], v[176:179], v[198:201], v[52:55]
	v_mfma_f32_16x16x32_bf16 v[48:51], v[184:187], v[198:201], v[48:51]
	v_mfma_f32_16x16x32_bf16 v[36:39], v[176:179], v[206:209], v[36:39]
	v_mfma_f32_16x16x32_bf16 v[32:35], v[184:187], v[206:209], v[32:35]
	v_mfma_f32_16x16x32_bf16 v[20:23], v[176:179], v[214:217], v[20:23]
	v_mfma_f32_16x16x32_bf16 v[16:19], v[184:187], v[214:217], v[16:19]
	v_mfma_f32_16x16x32_bf16 v[4:7], v[176:179], v[222:225], v[4:7]
	v_mfma_f32_16x16x32_bf16 v[0:3], v[184:187], v[222:225], v[0:3]
	s_setprio 0
	s_barrier
	s_add_i32 s27, 0, 0x18000
	v_add_u32_e32 v143, s27, v139
	s_add_i32 s33, 0, 0x1c000
	ds_read_b128 v[156:159], v143
	ds_read_b128 v[160:163], v143 offset:1024
	ds_read_b128 v[164:167], v143 offset:2048
	ds_read_b128 v[168:171], v143 offset:3072
	v_add_u32_e32 v143, s33, v139
	ds_read_b128 v[172:175], v143
	ds_read_b128 v[176:179], v143 offset:1024
	ds_read_b128 v[180:183], v143 offset:2048
	ds_read_b128 v[184:187], v143 offset:3072
	s_add_u32 s8, s18, 0x40000
	s_addc_u32 s9, s19, 0
	s_mov_b32 m0, s68
	v_lshl_add_u64 v[230:231], s[8:9], 0, v[132:133]
	ds_read_b128 v[188:191], v142 offset:32768
	ds_read_b128 v[198:201], v142 offset:33792
	ds_read_b128 v[202:205], v142 offset:34816
	ds_read_b128 v[206:209], v142 offset:35840
	ds_read_b128 v[210:213], v142 offset:36864
	ds_read_b128 v[214:217], v142 offset:37888
	ds_read_b128 v[218:221], v142 offset:38912
	ds_read_b128 v[222:225], v142 offset:39936
	global_load_lds_dwordx4 v[230:231], off
	v_lshl_add_u64 v[230:231], s[8:9], 0, v[130:131]
	s_mov_b32 m0, s69
	s_nop 0
	global_load_lds_dwordx4 v[230:231], off
	s_waitcnt vmcnt(8)
	s_waitcnt lgkmcnt(0)
	s_barrier
	s_setprio 1
	s_waitcnt lgkmcnt(0)
	v_mfma_f32_16x16x32_bf16 v[124:127], v[156:159], v[188:191], v[124:127]
	v_mfma_f32_16x16x32_bf16 v[120:123], v[164:167], v[188:191], v[120:123]
	v_mfma_f32_16x16x32_bf16 v[108:111], v[156:159], v[202:205], v[108:111]
	v_mfma_f32_16x16x32_bf16 v[104:107], v[164:167], v[202:205], v[104:107]
	v_mfma_f32_16x16x32_bf16 v[92:95], v[156:159], v[210:213], v[92:95]
	v_mfma_f32_16x16x32_bf16 v[88:91], v[164:167], v[210:213], v[88:91]
	v_mfma_f32_16x16x32_bf16 v[76:79], v[156:159], v[218:221], v[76:79]
	v_mfma_f32_16x16x32_bf16 v[72:75], v[164:167], v[218:221], v[72:75]
	v_mfma_f32_16x16x32_bf16 v[124:127], v[160:163], v[198:201], v[124:127]
	v_mfma_f32_16x16x32_bf16 v[120:123], v[168:171], v[198:201], v[120:123]
	v_mfma_f32_16x16x32_bf16 v[108:111], v[160:163], v[206:209], v[108:111]
	v_mfma_f32_16x16x32_bf16 v[104:107], v[168:171], v[206:209], v[104:107]
	v_mfma_f32_16x16x32_bf16 v[92:95], v[160:163], v[214:217], v[92:95]
	v_mfma_f32_16x16x32_bf16 v[88:91], v[168:171], v[214:217], v[88:91]
	v_mfma_f32_16x16x32_bf16 v[76:79], v[160:163], v[222:225], v[76:79]
	v_mfma_f32_16x16x32_bf16 v[72:75], v[168:171], v[222:225], v[72:75]
	s_setprio 0
	s_setprio 1
	v_mfma_f32_16x16x32_bf16 v[116:119], v[172:175], v[188:191], v[116:119]
	v_mfma_f32_16x16x32_bf16 v[112:115], v[180:183], v[188:191], v[112:115]
	v_mfma_f32_16x16x32_bf16 v[100:103], v[172:175], v[202:205], v[100:103]
	v_mfma_f32_16x16x32_bf16 v[96:99], v[180:183], v[202:205], v[96:99]
	v_mfma_f32_16x16x32_bf16 v[84:87], v[172:175], v[210:213], v[84:87]
	v_mfma_f32_16x16x32_bf16 v[80:83], v[180:183], v[210:213], v[80:83]
	v_mfma_f32_16x16x32_bf16 v[68:71], v[172:175], v[218:221], v[68:71]
	v_mfma_f32_16x16x32_bf16 v[64:67], v[180:183], v[218:221], v[64:67]
	v_mfma_f32_16x16x32_bf16 v[116:119], v[176:179], v[198:201], v[116:119]
	v_mfma_f32_16x16x32_bf16 v[112:115], v[184:187], v[198:201], v[112:115]
	v_mfma_f32_16x16x32_bf16 v[100:103], v[176:179], v[206:209], v[100:103]
	v_mfma_f32_16x16x32_bf16 v[96:99], v[184:187], v[206:209], v[96:99]
	v_mfma_f32_16x16x32_bf16 v[84:87], v[176:179], v[214:217], v[84:87]
	v_mfma_f32_16x16x32_bf16 v[80:83], v[184:187], v[214:217], v[80:83]
	v_mfma_f32_16x16x32_bf16 v[68:71], v[176:179], v[222:225], v[68:71]
	v_mfma_f32_16x16x32_bf16 v[64:67], v[184:187], v[222:225], v[64:67]
	s_setprio 0
	s_barrier
	s_add_i32 s8, s27, s0
	v_lshl_add_u64 v[146:147], v[146:147], 0, s[70:71]
	s_mov_b32 m0, s8
	ds_read_b128 v[188:191], v142 offset:49152
	ds_read_b128 v[198:201], v142 offset:50176
	ds_read_b128 v[202:205], v142 offset:51200
	ds_read_b128 v[206:209], v142 offset:52224
	ds_read_b128 v[210:213], v142 offset:53248
	ds_read_b128 v[214:217], v142 offset:54272
	ds_read_b128 v[218:221], v142 offset:55296
	ds_read_b128 v[222:225], v142 offset:56320
	global_load_lds_dwordx4 v[146:147], off
	s_add_i32 m0, s8, 0x2000
	s_add_u32 s6, s6, 0x40080
	v_lshl_add_u64 v[146:147], v[154:155], 0, s[70:71]
	s_addc_u32 s7, s7, 0
	s_add_i32 s8, s33, s0
	global_load_lds_dwordx4 v[146:147], off
	v_lshl_add_u64 v[146:147], s[6:7], 0, v[144:145]
	s_mov_b32 m0, s8
	s_nop 0
	global_load_lds_dwordx4 v[146:147], off
	v_lshl_add_u64 v[146:147], s[6:7], 0, v[128:129]
	s_add_i32 m0, s8, 0x2000
	s_nop 0
	global_load_lds_dwordx4 v[146:147], off
	v_lshl_add_u64 v[146:147], v[226:227], 0, s[70:71]
	s_mov_b32 m0, s84
	s_nop 0
	global_load_lds_dwordx4 v[146:147], off
	v_lshl_add_u64 v[146:147], v[228:229], 0, s[70:71]
	s_mov_b32 m0, s85
	s_nop 0
	global_load_lds_dwordx4 v[146:147], off
	s_waitcnt vmcnt(8)
	s_waitcnt lgkmcnt(0)
	s_barrier
	s_setprio 1
	s_waitcnt lgkmcnt(0)
	v_mfma_f32_16x16x32_bf16 v[60:63], v[156:159], v[188:191], v[60:63]
	v_mfma_f32_16x16x32_bf16 v[56:59], v[164:167], v[188:191], v[56:59]
	v_mfma_f32_16x16x32_bf16 v[44:47], v[156:159], v[202:205], v[44:47]
	v_mfma_f32_16x16x32_bf16 v[40:43], v[164:167], v[202:205], v[40:43]
	v_mfma_f32_16x16x32_bf16 v[28:31], v[156:159], v[210:213], v[28:31]
	v_mfma_f32_16x16x32_bf16 v[24:27], v[164:167], v[210:213], v[24:27]
	v_mfma_f32_16x16x32_bf16 v[12:15], v[156:159], v[218:221], v[12:15]
	v_mfma_f32_16x16x32_bf16 v[8:11], v[164:167], v[218:221], v[8:11]
	v_mfma_f32_16x16x32_bf16 v[60:63], v[160:163], v[198:201], v[60:63]
	v_mfma_f32_16x16x32_bf16 v[56:59], v[168:171], v[198:201], v[56:59]
	v_mfma_f32_16x16x32_bf16 v[44:47], v[160:163], v[206:209], v[44:47]
	v_mfma_f32_16x16x32_bf16 v[40:43], v[168:171], v[206:209], v[40:43]
	v_mfma_f32_16x16x32_bf16 v[28:31], v[160:163], v[214:217], v[28:31]
	v_mfma_f32_16x16x32_bf16 v[24:27], v[168:171], v[214:217], v[24:27]
	v_mfma_f32_16x16x32_bf16 v[12:15], v[160:163], v[222:225], v[12:15]
	v_mfma_f32_16x16x32_bf16 v[8:11], v[168:171], v[222:225], v[8:11]
	s_setprio 0
	s_setprio 1
	v_mfma_f32_16x16x32_bf16 v[52:55], v[172:175], v[188:191], v[52:55]
	s_add_i32 s31, s31, 2
	s_add_u32 s48, s48, 0x100
	s_addc_u32 s49, s49, 0
	s_add_u32 s23, s23, 0x100
	s_addc_u32 s30, s30, 0
	s_cmp_gt_u32 s31, 13
	v_mfma_f32_16x16x32_bf16 v[48:51], v[180:183], v[188:191], v[48:51]
	v_mfma_f32_16x16x32_bf16 v[36:39], v[172:175], v[202:205], v[36:39]
	v_mfma_f32_16x16x32_bf16 v[32:35], v[180:183], v[202:205], v[32:35]
	v_mfma_f32_16x16x32_bf16 v[20:23], v[172:175], v[210:213], v[20:23]
	v_mfma_f32_16x16x32_bf16 v[16:19], v[180:183], v[210:213], v[16:19]
	v_mfma_f32_16x16x32_bf16 v[4:7], v[172:175], v[218:221], v[4:7]
	v_mfma_f32_16x16x32_bf16 v[0:3], v[180:183], v[218:221], v[0:3]
	v_mfma_f32_16x16x32_bf16 v[52:55], v[176:179], v[198:201], v[52:55]
	v_mfma_f32_16x16x32_bf16 v[48:51], v[184:187], v[198:201], v[48:51]
	v_mfma_f32_16x16x32_bf16 v[36:39], v[176:179], v[206:209], v[36:39]
	v_mfma_f32_16x16x32_bf16 v[32:35], v[184:187], v[206:209], v[32:35]
	v_mfma_f32_16x16x32_bf16 v[20:23], v[176:179], v[214:217], v[20:23]
	v_mfma_f32_16x16x32_bf16 v[16:19], v[184:187], v[214:217], v[16:19]
	v_mfma_f32_16x16x32_bf16 v[4:7], v[176:179], v[222:225], v[4:7]
	v_mfma_f32_16x16x32_bf16 v[0:3], v[184:187], v[222:225], v[0:3]
	s_setprio 0
	s_barrier
	s_cbranch_scc0 .LBB0_993
	s_and_b64 vcc, exec, s[38:39]
	s_cbranch_vccz .LBB0_996
	s_barrier

.LBB0_1018:
	s_add_u32 s8, s48, 0xfffc0080
	s_addc_u32 s9, s49, -1
	s_add_i32 s27, 0, 0x10000
	s_cmp_eq_u32 s51, 12
	s_cselect_b32 s19, s31, s9
	s_cselect_b32 s18, s33, s8
	v_add_u32_e32 v142, s27, v139
	s_cselect_b32 s25, s37, s50
	s_cselect_b32 s24, s41, s43
	s_add_i32 s52, 0, 0x14000
	ds_read_b128 v[156:159], v142
	ds_read_b128 v[160:163], v142 offset:1024
	ds_read_b128 v[164:167], v142 offset:2048
	ds_read_b128 v[168:171], v142 offset:3072
	v_add_u32_e32 v142, s52, v139
	ds_read_b128 v[172:175], v142
	ds_read_b128 v[176:179], v142 offset:1024
	ds_read_b128 v[180:183], v142 offset:2048
	ds_read_b128 v[184:187], v142 offset:3072
	v_lshl_add_u64 v[142:143], s[48:49], 0, v[134:135]
	s_add_i32 m0, s17, 0xc000
	ds_read_b128 v[188:191], v141
	ds_read_b128 v[198:201], v141 offset:1024
	ds_read_b128 v[202:205], v141 offset:2048
	ds_read_b128 v[206:209], v141 offset:3072
	ds_read_b128 v[210:213], v141 offset:4096
	ds_read_b128 v[214:217], v141 offset:5120
	ds_read_b128 v[218:221], v141 offset:6144
	ds_read_b128 v[222:225], v141 offset:7168
	global_load_lds_dwordx4 v[142:143], off
	v_lshl_add_u64 v[142:143], s[48:49], 0, v[136:137]
	s_add_i32 m0, s17, 0xe000
	s_nop 0
	global_load_lds_dwordx4 v[142:143], off
	s_waitcnt vmcnt(8)
	s_waitcnt lgkmcnt(0)
	s_barrier
	s_setprio 1
	s_waitcnt lgkmcnt(0)
	v_mfma_f32_16x16x32_bf16 v[124:127], v[156:159], v[188:191], v[124:127]
	v_mfma_f32_16x16x32_bf16 v[120:123], v[164:167], v[188:191], v[120:123]
	v_mfma_f32_16x16x32_bf16 v[116:119], v[156:159], v[202:205], v[116:119]
	v_mfma_f32_16x16x32_bf16 v[112:115], v[164:167], v[202:205], v[112:115]
	v_mfma_f32_16x16x32_bf16 v[100:103], v[156:159], v[210:213], v[100:103]
	v_mfma_f32_16x16x32_bf16 v[96:99], v[164:167], v[210:213], v[96:99]
	v_mfma_f32_16x16x32_bf16 v[84:87], v[156:159], v[218:221], v[84:87]
	v_mfma_f32_16x16x32_bf16 v[80:83], v[164:167], v[218:221], v[80:83]
	v_mfma_f32_16x16x32_bf16 v[124:127], v[160:163], v[198:201], v[124:127]
	v_mfma_f32_16x16x32_bf16 v[120:123], v[168:171], v[198:201], v[120:123]
	v_mfma_f32_16x16x32_bf16 v[116:119], v[160:163], v[206:209], v[116:119]
	v_mfma_f32_16x16x32_bf16 v[112:115], v[168:171], v[206:209], v[112:115]
	v_mfma_f32_16x16x32_bf16 v[100:103], v[160:163], v[214:217], v[100:103]
	v_mfma_f32_16x16x32_bf16 v[96:99], v[168:171], v[214:217], v[96:99]
	v_mfma_f32_16x16x32_bf16 v[84:87], v[160:163], v[222:225], v[84:87]
	v_mfma_f32_16x16x32_bf16 v[80:83], v[168:171], v[222:225], v[80:83]
	s_setprio 0
	s_setprio 1
	v_mfma_f32_16x16x32_bf16 v[108:111], v[172:175], v[188:191], v[108:111]
	v_mfma_f32_16x16x32_bf16 v[104:107], v[180:183], v[188:191], v[104:107]
	v_mfma_f32_16x16x32_bf16 v[92:95], v[172:175], v[202:205], v[92:95]
	v_mfma_f32_16x16x32_bf16 v[88:91], v[180:183], v[202:205], v[88:91]
	v_mfma_f32_16x16x32_bf16 v[76:79], v[172:175], v[210:213], v[76:79]
	v_mfma_f32_16x16x32_bf16 v[72:75], v[180:183], v[210:213], v[72:75]
	v_mfma_f32_16x16x32_bf16 v[68:71], v[172:175], v[218:221], v[68:71]
	v_mfma_f32_16x16x32_bf16 v[64:67], v[180:183], v[218:221], v[64:67]
	v_mfma_f32_16x16x32_bf16 v[108:111], v[176:179], v[198:201], v[108:111]
	v_mfma_f32_16x16x32_bf16 v[104:107], v[184:187], v[198:201], v[104:107]
	v_mfma_f32_16x16x32_bf16 v[92:95], v[176:179], v[206:209], v[92:95]
	v_mfma_f32_16x16x32_bf16 v[88:91], v[184:187], v[206:209], v[88:91]
	v_mfma_f32_16x16x32_bf16 v[76:79], v[176:179], v[214:217], v[76:79]
	v_mfma_f32_16x16x32_bf16 v[72:75], v[184:187], v[214:217], v[72:75]
	v_mfma_f32_16x16x32_bf16 v[68:71], v[176:179], v[222:225], v[68:71]
	v_mfma_f32_16x16x32_bf16 v[64:67], v[184:187], v[222:225], v[64:67]
	s_setprio 0
	s_barrier
	s_add_i32 s8, s27, s16
	v_lshl_add_u64 v[142:143], s[24:25], 0, v[144:145]
	s_mov_b32 m0, s8
	ds_read_b128 v[188:191], v141 offset:16384
	ds_read_b128 v[198:201], v141 offset:17408
	ds_read_b128 v[202:205], v141 offset:18432
	ds_read_b128 v[206:209], v141 offset:19456
	ds_read_b128 v[210:213], v141 offset:20480
	ds_read_b128 v[214:217], v141 offset:21504
	ds_read_b128 v[218:221], v141 offset:22528
	ds_read_b128 v[222:225], v141 offset:23552
	global_load_lds_dwordx4 v[142:143], off
	s_add_i32 m0, s8, 0x2000
	s_add_u32 s8, s24, 0x40000
	v_lshl_add_u64 v[146:147], s[24:25], 0, v[132:133]
	s_addc_u32 s9, s25, 0
	s_add_i32 s27, s52, s16
	global_load_lds_dwordx4 v[146:147], off
	v_lshl_add_u64 v[154:155], s[8:9], 0, v[144:145]
	s_mov_b32 m0, s27
	v_lshl_add_u64 v[226:227], s[18:19], 0, v[130:131]
	global_load_lds_dwordx4 v[154:155], off
	v_lshl_add_u64 v[154:155], s[8:9], 0, v[132:133]
	s_add_i32 m0, s27, 0x2000
	s_nop 0
	global_load_lds_dwordx4 v[154:155], off
	v_lshl_add_u64 v[154:155], s[18:19], 0, v[128:129]
	s_mov_b32 m0, s17
	s_nop 0
	global_load_lds_dwordx4 v[154:155], off
	s_mov_b32 m0, s14
	s_nop 0
	global_load_lds_dwordx4 v[226:227], off
	s_waitcnt vmcnt(8)
	s_waitcnt lgkmcnt(0)
	s_barrier
	s_setprio 1
	s_waitcnt lgkmcnt(0)
	v_mfma_f32_16x16x32_bf16 v[60:63], v[156:159], v[188:191], v[60:63]
	v_mfma_f32_16x16x32_bf16 v[56:59], v[164:167], v[188:191], v[56:59]
	v_mfma_f32_16x16x32_bf16 v[52:55], v[156:159], v[202:205], v[52:55]
	v_mfma_f32_16x16x32_bf16 v[48:51], v[164:167], v[202:205], v[48:51]
	v_mfma_f32_16x16x32_bf16 v[36:39], v[156:159], v[210:213], v[36:39]
	v_mfma_f32_16x16x32_bf16 v[32:35], v[164:167], v[210:213], v[32:35]
	v_mfma_f32_16x16x32_bf16 v[20:23], v[156:159], v[218:221], v[20:23]
	v_mfma_f32_16x16x32_bf16 v[16:19], v[164:167], v[218:221], v[16:19]
	v_mfma_f32_16x16x32_bf16 v[60:63], v[160:163], v[198:201], v[60:63]
	v_mfma_f32_16x16x32_bf16 v[56:59], v[168:171], v[198:201], v[56:59]
	v_mfma_f32_16x16x32_bf16 v[52:55], v[160:163], v[206:209], v[52:55]
	v_mfma_f32_16x16x32_bf16 v[48:51], v[168:171], v[206:209], v[48:51]
	v_mfma_f32_16x16x32_bf16 v[36:39], v[160:163], v[214:217], v[36:39]
	v_mfma_f32_16x16x32_bf16 v[32:35], v[168:171], v[214:217], v[32:35]
	v_mfma_f32_16x16x32_bf16 v[20:23], v[160:163], v[222:225], v[20:23]
	v_mfma_f32_16x16x32_bf16 v[16:19], v[168:171], v[222:225], v[16:19]
	s_setprio 0
	s_setprio 1
	v_mfma_f32_16x16x32_bf16 v[44:47], v[172:175], v[188:191], v[44:47]
	v_mfma_f32_16x16x32_bf16 v[40:43], v[180:183], v[188:191], v[40:43]
	v_mfma_f32_16x16x32_bf16 v[28:31], v[172:175], v[202:205], v[28:31]
	v_mfma_f32_16x16x32_bf16 v[24:27], v[180:183], v[202:205], v[24:27]
	v_mfma_f32_16x16x32_bf16 v[12:15], v[172:175], v[210:213], v[12:15]
	v_mfma_f32_16x16x32_bf16 v[8:11], v[180:183], v[210:213], v[8:11]
	v_mfma_f32_16x16x32_bf16 v[4:7], v[172:175], v[218:221], v[4:7]
	v_mfma_f32_16x16x32_bf16 v[0:3], v[180:183], v[218:221], v[0:3]
	v_mfma_f32_16x16x32_bf16 v[44:47], v[176:179], v[198:201], v[44:47]
	v_mfma_f32_16x16x32_bf16 v[40:43], v[184:187], v[198:201], v[40:43]
	v_mfma_f32_16x16x32_bf16 v[28:31], v[176:179], v[206:209], v[28:31]
	v_mfma_f32_16x16x32_bf16 v[24:27], v[184:187], v[206:209], v[24:27]
	v_mfma_f32_16x16x32_bf16 v[12:15], v[176:179], v[214:217], v[12:15]
	v_mfma_f32_16x16x32_bf16 v[8:11], v[184:187], v[214:217], v[8:11]
	v_mfma_f32_16x16x32_bf16 v[4:7], v[176:179], v[222:225], v[4:7]
	v_mfma_f32_16x16x32_bf16 v[0:3], v[184:187], v[222:225], v[0:3]
	s_setprio 0
	s_barrier
	s_add_i32 s27, 0, 0x18000
	s_add_i32 s52, 0, 0x1c000
	v_add_u32_e32 v168, s27, v139
	v_add_u32_e32 v184, s52, v139
	ds_read_b128 v[156:159], v168
	ds_read_b128 v[160:163], v168 offset:1024
	ds_read_b128 v[164:167], v168 offset:2048
	ds_read_b128 v[168:171], v168 offset:3072
	ds_read_b128 v[172:175], v184
	ds_read_b128 v[176:179], v184 offset:1024
	ds_read_b128 v[180:183], v184 offset:2048
	ds_read_b128 v[184:187], v184 offset:3072
	s_add_u32 s8, s18, 0x40000
	s_addc_u32 s9, s19, 0
	s_mov_b32 m0, s15
	v_lshl_add_u64 v[228:229], s[8:9], 0, v[128:129]
	ds_read_b128 v[188:191], v141 offset:32768
	ds_read_b128 v[198:201], v141 offset:33792
	ds_read_b128 v[202:205], v141 offset:34816
	ds_read_b128 v[206:209], v141 offset:35840
	ds_read_b128 v[210:213], v141 offset:36864
	ds_read_b128 v[214:217], v141 offset:37888
	ds_read_b128 v[218:221], v141 offset:38912
	ds_read_b128 v[222:225], v141 offset:39936
	global_load_lds_dwordx4 v[228:229], off
	v_lshl_add_u64 v[228:229], s[8:9], 0, v[130:131]
	s_mov_b32 m0, s23
	s_nop 0
	global_load_lds_dwordx4 v[228:229], off
	s_waitcnt vmcnt(8)
	s_waitcnt lgkmcnt(0)
	s_barrier
	s_setprio 1
	s_waitcnt lgkmcnt(0)
	v_mfma_f32_16x16x32_bf16 v[124:127], v[156:159], v[188:191], v[124:127]
	v_mfma_f32_16x16x32_bf16 v[120:123], v[164:167], v[188:191], v[120:123]
	v_mfma_f32_16x16x32_bf16 v[116:119], v[156:159], v[202:205], v[116:119]
	v_mfma_f32_16x16x32_bf16 v[112:115], v[164:167], v[202:205], v[112:115]
	v_mfma_f32_16x16x32_bf16 v[100:103], v[156:159], v[210:213], v[100:103]
	v_mfma_f32_16x16x32_bf16 v[96:99], v[164:167], v[210:213], v[96:99]
	v_mfma_f32_16x16x32_bf16 v[84:87], v[156:159], v[218:221], v[84:87]
	v_mfma_f32_16x16x32_bf16 v[80:83], v[164:167], v[218:221], v[80:83]
	v_mfma_f32_16x16x32_bf16 v[124:127], v[160:163], v[198:201], v[124:127]
	v_mfma_f32_16x16x32_bf16 v[120:123], v[168:171], v[198:201], v[120:123]
	v_mfma_f32_16x16x32_bf16 v[116:119], v[160:163], v[206:209], v[116:119]
	v_mfma_f32_16x16x32_bf16 v[112:115], v[168:171], v[206:209], v[112:115]
	v_mfma_f32_16x16x32_bf16 v[100:103], v[160:163], v[214:217], v[100:103]
	v_mfma_f32_16x16x32_bf16 v[96:99], v[168:171], v[214:217], v[96:99]
	v_mfma_f32_16x16x32_bf16 v[84:87], v[160:163], v[222:225], v[84:87]
	v_mfma_f32_16x16x32_bf16 v[80:83], v[168:171], v[222:225], v[80:83]
	s_setprio 0
	s_setprio 1
	v_mfma_f32_16x16x32_bf16 v[108:111], v[172:175], v[188:191], v[108:111]
	v_mfma_f32_16x16x32_bf16 v[104:107], v[180:183], v[188:191], v[104:107]
	v_mfma_f32_16x16x32_bf16 v[92:95], v[172:175], v[202:205], v[92:95]
	v_mfma_f32_16x16x32_bf16 v[88:91], v[180:183], v[202:205], v[88:91]
	v_mfma_f32_16x16x32_bf16 v[76:79], v[172:175], v[210:213], v[76:79]
	v_mfma_f32_16x16x32_bf16 v[72:75], v[180:183], v[210:213], v[72:75]
	v_mfma_f32_16x16x32_bf16 v[68:71], v[172:175], v[218:221], v[68:71]
	v_mfma_f32_16x16x32_bf16 v[64:67], v[180:183], v[218:221], v[64:67]
	v_mfma_f32_16x16x32_bf16 v[108:111], v[176:179], v[198:201], v[108:111]
	v_mfma_f32_16x16x32_bf16 v[104:107], v[184:187], v[198:201], v[104:107]
	v_mfma_f32_16x16x32_bf16 v[92:95], v[176:179], v[206:209], v[92:95]
	v_mfma_f32_16x16x32_bf16 v[88:91], v[184:187], v[206:209], v[88:91]
	v_mfma_f32_16x16x32_bf16 v[76:79], v[176:179], v[214:217], v[76:79]
	v_mfma_f32_16x16x32_bf16 v[72:75], v[184:187], v[214:217], v[72:75]
	v_mfma_f32_16x16x32_bf16 v[68:71], v[176:179], v[222:225], v[68:71]
	v_mfma_f32_16x16x32_bf16 v[64:67], v[184:187], v[222:225], v[64:67]
	s_setprio 0
	s_barrier
	s_add_i32 s8, s27, s16
	v_lshl_add_u64 v[142:143], v[142:143], 0, s[70:71]
	s_mov_b32 m0, s8
	ds_read_b128 v[188:191], v141 offset:49152
	ds_read_b128 v[198:201], v141 offset:50176
	ds_read_b128 v[202:205], v141 offset:51200
	ds_read_b128 v[206:209], v141 offset:52224
	ds_read_b128 v[210:213], v141 offset:53248
	ds_read_b128 v[214:217], v141 offset:54272
	ds_read_b128 v[218:221], v141 offset:55296
	ds_read_b128 v[222:225], v141 offset:56320
	global_load_lds_dwordx4 v[142:143], off
	s_add_i32 m0, s8, 0x2000
	s_add_u32 s8, s24, 0x40080
	v_lshl_add_u64 v[142:143], v[146:147], 0, s[70:71]
	s_addc_u32 s9, s25, 0
	s_add_i32 s18, s52, s16
	global_load_lds_dwordx4 v[142:143], off
	v_lshl_add_u64 v[142:143], s[8:9], 0, v[144:145]
	s_mov_b32 m0, s18
	s_nop 0
	global_load_lds_dwordx4 v[142:143], off
	v_lshl_add_u64 v[142:143], s[8:9], 0, v[132:133]
	s_add_i32 m0, s18, 0x2000
	s_nop 0
	global_load_lds_dwordx4 v[142:143], off
	v_lshl_add_u64 v[142:143], v[154:155], 0, s[70:71]
	s_mov_b32 m0, s0
	s_nop 0
	global_load_lds_dwordx4 v[142:143], off
	v_lshl_add_u64 v[142:143], v[226:227], 0, s[70:71]
	s_mov_b32 m0, s30
	s_nop 0
	global_load_lds_dwordx4 v[142:143], off
	s_waitcnt vmcnt(8)
	s_waitcnt lgkmcnt(0)
	s_barrier
	s_setprio 1
	s_waitcnt lgkmcnt(0)
	v_mfma_f32_16x16x32_bf16 v[60:63], v[156:159], v[188:191], v[60:63]
	v_mfma_f32_16x16x32_bf16 v[56:59], v[164:167], v[188:191], v[56:59]
	v_mfma_f32_16x16x32_bf16 v[52:55], v[156:159], v[202:205], v[52:55]
	v_mfma_f32_16x16x32_bf16 v[48:51], v[164:167], v[202:205], v[48:51]
	v_mfma_f32_16x16x32_bf16 v[36:39], v[156:159], v[210:213], v[36:39]
	v_mfma_f32_16x16x32_bf16 v[32:35], v[164:167], v[210:213], v[32:35]
	v_mfma_f32_16x16x32_bf16 v[20:23], v[156:159], v[218:221], v[20:23]
	v_mfma_f32_16x16x32_bf16 v[16:19], v[164:167], v[218:221], v[16:19]
	v_mfma_f32_16x16x32_bf16 v[60:63], v[160:163], v[198:201], v[60:63]
	v_mfma_f32_16x16x32_bf16 v[56:59], v[168:171], v[198:201], v[56:59]
	v_mfma_f32_16x16x32_bf16 v[52:55], v[160:163], v[206:209], v[52:55]
	v_mfma_f32_16x16x32_bf16 v[48:51], v[168:171], v[206:209], v[48:51]
	v_mfma_f32_16x16x32_bf16 v[36:39], v[160:163], v[214:217], v[36:39]
	v_mfma_f32_16x16x32_bf16 v[32:35], v[168:171], v[214:217], v[32:35]
	v_mfma_f32_16x16x32_bf16 v[20:23], v[160:163], v[222:225], v[20:23]
	v_mfma_f32_16x16x32_bf16 v[16:19], v[168:171], v[222:225], v[16:19]
	s_setprio 0
	s_setprio 1
	v_mfma_f32_16x16x32_bf16 v[44:47], v[172:175], v[188:191], v[44:47]
	s_add_i32 s51, s51, 2
	s_add_u32 s48, s48, 0x100
	s_addc_u32 s49, s49, 0
	s_add_u32 s43, s43, 0x100
	s_addc_u32 s50, s50, 0
	s_cmp_gt_u32 s51, 13
	v_mfma_f32_16x16x32_bf16 v[40:43], v[180:183], v[188:191], v[40:43]
	v_mfma_f32_16x16x32_bf16 v[28:31], v[172:175], v[202:205], v[28:31]
	v_mfma_f32_16x16x32_bf16 v[24:27], v[180:183], v[202:205], v[24:27]
	v_mfma_f32_16x16x32_bf16 v[12:15], v[172:175], v[210:213], v[12:15]
	v_mfma_f32_16x16x32_bf16 v[8:11], v[180:183], v[210:213], v[8:11]
	v_mfma_f32_16x16x32_bf16 v[4:7], v[172:175], v[218:221], v[4:7]
	v_mfma_f32_16x16x32_bf16 v[0:3], v[180:183], v[218:221], v[0:3]
	v_mfma_f32_16x16x32_bf16 v[44:47], v[176:179], v[198:201], v[44:47]
	v_mfma_f32_16x16x32_bf16 v[40:43], v[184:187], v[198:201], v[40:43]
	v_mfma_f32_16x16x32_bf16 v[28:31], v[176:179], v[206:209], v[28:31]
	v_mfma_f32_16x16x32_bf16 v[24:27], v[184:187], v[206:209], v[24:27]
	v_mfma_f32_16x16x32_bf16 v[12:15], v[176:179], v[214:217], v[12:15]
	v_mfma_f32_16x16x32_bf16 v[8:11], v[184:187], v[214:217], v[8:11]
	v_mfma_f32_16x16x32_bf16 v[4:7], v[176:179], v[222:225], v[4:7]
	v_mfma_f32_16x16x32_bf16 v[0:3], v[184:187], v[222:225], v[0:3]
	s_setprio 0
	s_barrier
	s_cbranch_scc0 .LBB0_1018
	s_and_b64 vcc, exec, s[12:13]
	s_movk_i32 s33, 0xe000
	s_cbranch_vccz .LBB0_1021
	s_barrier

.LBB0_1193:
	s_add_i32 s31, 0, 0x10000
	s_add_i32 s18, 0, 0x14000
	v_add_u32_e32 v169, s31, v166
	v_add_u32_e32 v170, s18, v166
	ds_read_b128 v[172:175], v169
	ds_read_b128 v[176:179], v169 offset:1024
	ds_read_b128 v[180:183], v169 offset:2048
	ds_read_b128 v[184:187], v169 offset:3072
	ds_read_b128 v[188:191], v170
	ds_read_b128 v[198:201], v170 offset:1024
	ds_read_b128 v[202:205], v170 offset:2048
	ds_read_b128 v[206:209], v170 offset:3072
	v_lshl_add_u64 v[146:147], v[142:143], 0, s[50:51]
	s_add_i32 s33, s85, 0xc000
	v_lshl_add_u64 v[154:155], v[146:147], 0, s[28:29]
	s_mov_b32 m0, s33
	ds_read_b128 v[210:213], v168
	ds_read_b128 v[214:217], v168 offset:1024
	ds_read_b128 v[218:221], v168 offset:2048
	ds_read_b128 v[222:225], v168 offset:3072
	ds_read_b128 v[226:229], v168 offset:4096
	ds_read_b128 v[230:233], v168 offset:5120
	ds_read_b128 v[234:237], v168 offset:6144
	ds_read_b128 v[238:241], v168 offset:7168
	global_load_lds_dwordx4 v[154:155], off
	v_lshl_add_u64 v[154:155], v[156:157], 0, s[50:51]
	s_add_i32 s14, s85, 0xe000
	v_lshl_add_u64 v[242:243], v[154:155], 0, s[28:29]
	s_mov_b32 m0, s14
	s_nop 0
	global_load_lds_dwordx4 v[242:243], off
	s_waitcnt vmcnt(8)
	s_waitcnt lgkmcnt(0)
	s_barrier
	s_setprio 1
	s_waitcnt lgkmcnt(0)
	v_mfma_f32_16x16x32_bf16 v[136:139], v[172:175], v[210:213], v[136:139]
	v_mfma_f32_16x16x32_bf16 v[132:135], v[180:183], v[210:213], v[132:135]
	v_mfma_f32_16x16x32_bf16 v[116:119], v[172:175], v[218:221], v[116:119]
	v_mfma_f32_16x16x32_bf16 v[112:115], v[180:183], v[218:221], v[112:115]
	v_mfma_f32_16x16x32_bf16 v[96:99], v[172:175], v[226:229], v[96:99]
	v_mfma_f32_16x16x32_bf16 v[92:95], v[180:183], v[226:229], v[92:95]
	v_mfma_f32_16x16x32_bf16 v[76:79], v[172:175], v[234:237], v[76:79]
	v_mfma_f32_16x16x32_bf16 v[72:75], v[180:183], v[234:237], v[72:75]
	v_mfma_f32_16x16x32_bf16 v[136:139], v[176:179], v[214:217], v[136:139]
	v_mfma_f32_16x16x32_bf16 v[132:135], v[184:187], v[214:217], v[132:135]
	v_mfma_f32_16x16x32_bf16 v[116:119], v[176:179], v[222:225], v[116:119]
	v_mfma_f32_16x16x32_bf16 v[112:115], v[184:187], v[222:225], v[112:115]
	v_mfma_f32_16x16x32_bf16 v[96:99], v[176:179], v[230:233], v[96:99]
	v_mfma_f32_16x16x32_bf16 v[92:95], v[184:187], v[230:233], v[92:95]
	v_mfma_f32_16x16x32_bf16 v[76:79], v[176:179], v[238:241], v[76:79]
	v_mfma_f32_16x16x32_bf16 v[72:75], v[184:187], v[238:241], v[72:75]
	s_setprio 0
	s_setprio 1
	v_mfma_f32_16x16x32_bf16 v[124:127], v[188:191], v[210:213], v[124:127]
	v_mfma_f32_16x16x32_bf16 v[120:123], v[202:205], v[210:213], v[120:123]
	v_mfma_f32_16x16x32_bf16 v[104:107], v[188:191], v[218:221], v[104:107]
	v_mfma_f32_16x16x32_bf16 v[100:103], v[202:205], v[218:221], v[100:103]
	v_mfma_f32_16x16x32_bf16 v[84:87], v[188:191], v[226:229], v[84:87]
	v_mfma_f32_16x16x32_bf16 v[80:83], v[202:205], v[226:229], v[80:83]
	v_mfma_f32_16x16x32_bf16 v[68:71], v[188:191], v[234:237], v[68:71]
	v_mfma_f32_16x16x32_bf16 v[64:67], v[202:205], v[234:237], v[64:67]
	v_mfma_f32_16x16x32_bf16 v[124:127], v[198:201], v[214:217], v[124:127]
	v_mfma_f32_16x16x32_bf16 v[120:123], v[206:209], v[214:217], v[120:123]
	v_mfma_f32_16x16x32_bf16 v[104:107], v[198:201], v[222:225], v[104:107]
	v_mfma_f32_16x16x32_bf16 v[100:103], v[206:209], v[222:225], v[100:103]
	v_mfma_f32_16x16x32_bf16 v[84:87], v[198:201], v[230:233], v[84:87]
	v_mfma_f32_16x16x32_bf16 v[80:83], v[206:209], v[230:233], v[80:83]
	v_mfma_f32_16x16x32_bf16 v[68:71], v[198:201], v[238:241], v[68:71]
	v_mfma_f32_16x16x32_bf16 v[64:67], v[206:209], v[238:241], v[64:67]
	s_setprio 0
	s_barrier
	v_lshl_add_u64 v[246:247], v[158:159], 0, s[50:51]
	s_add_i32 s31, s31, s84
	v_lshl_add_u64 v[242:243], v[246:247], 0, s[96:97]
	s_mov_b32 m0, s31
	v_lshl_add_u64 v[248:249], v[160:161], 0, s[50:51]
	s_add_i32 s15, s31, 0x2000
	ds_read_b128 v[210:213], v168 offset:16384
	ds_read_b128 v[214:217], v168 offset:17408
	ds_read_b128 v[218:221], v168 offset:18432
	ds_read_b128 v[222:225], v168 offset:19456
	ds_read_b128 v[226:229], v168 offset:20480
	ds_read_b128 v[230:233], v168 offset:21504
	ds_read_b128 v[234:237], v168 offset:22528
	ds_read_b128 v[238:241], v168 offset:23552
	global_load_lds_dwordx4 v[242:243], off
	v_lshl_add_u64 v[242:243], v[248:249], 0, s[96:97]
	s_mov_b32 m0, s15
	s_add_i32 s18, s18, s84
	global_load_lds_dwordx4 v[242:243], off
	v_lshl_add_u64 v[242:243], v[246:247], 0, s[56:57]
	s_mov_b32 m0, s18
	s_add_i32 s23, s18, 0x2000
	global_load_lds_dwordx4 v[242:243], off
	v_lshl_add_u64 v[242:243], v[248:249], 0, s[56:57]
	s_mov_b32 m0, s23
	s_nop 0
	global_load_lds_dwordx4 v[242:243], off
	v_lshl_add_u64 v[242:243], v[146:147], 0, s[96:97]
	s_mov_b32 m0, s85
	s_nop 0
	global_load_lds_dwordx4 v[242:243], off
	v_lshl_add_u64 v[242:243], v[154:155], 0, s[96:97]
	s_mov_b32 m0, s86
	s_nop 0
	global_load_lds_dwordx4 v[242:243], off
	s_waitcnt vmcnt(8)
	s_waitcnt lgkmcnt(0)
	s_barrier
	s_setprio 1
	s_waitcnt lgkmcnt(0)
	v_mfma_f32_16x16x32_bf16 v[60:63], v[172:175], v[210:213], v[60:63]
	v_mfma_f32_16x16x32_bf16 v[56:59], v[180:183], v[210:213], v[56:59]
	v_mfma_f32_16x16x32_bf16 v[44:47], v[172:175], v[218:221], v[44:47]
	v_mfma_f32_16x16x32_bf16 v[40:43], v[180:183], v[218:221], v[40:43]
	v_mfma_f32_16x16x32_bf16 v[28:31], v[172:175], v[226:229], v[28:31]
	v_mfma_f32_16x16x32_bf16 v[24:27], v[180:183], v[226:229], v[24:27]
	v_mfma_f32_16x16x32_bf16 v[4:7], v[172:175], v[234:237], v[4:7]
	v_mfma_f32_16x16x32_bf16 v[0:3], v[180:183], v[234:237], v[0:3]
	v_mfma_f32_16x16x32_bf16 v[60:63], v[176:179], v[214:217], v[60:63]
	v_mfma_f32_16x16x32_bf16 v[56:59], v[184:187], v[214:217], v[56:59]
	v_mfma_f32_16x16x32_bf16 v[44:47], v[176:179], v[222:225], v[44:47]
	v_mfma_f32_16x16x32_bf16 v[40:43], v[184:187], v[222:225], v[40:43]
	v_mfma_f32_16x16x32_bf16 v[28:31], v[176:179], v[230:233], v[28:31]
	v_mfma_f32_16x16x32_bf16 v[24:27], v[184:187], v[230:233], v[24:27]
	v_mfma_f32_16x16x32_bf16 v[4:7], v[176:179], v[238:241], v[4:7]
	v_mfma_f32_16x16x32_bf16 v[0:3], v[184:187], v[238:241], v[0:3]
	s_setprio 0
	s_setprio 1
	v_mfma_f32_16x16x32_bf16 v[52:55], v[188:191], v[210:213], v[52:55]
	v_mfma_f32_16x16x32_bf16 v[48:51], v[202:205], v[210:213], v[48:51]
	v_mfma_f32_16x16x32_bf16 v[36:39], v[188:191], v[218:221], v[36:39]
	v_mfma_f32_16x16x32_bf16 v[32:35], v[202:205], v[218:221], v[32:35]
	v_mfma_f32_16x16x32_bf16 v[12:15], v[188:191], v[226:229], v[12:15]
	v_mfma_f32_16x16x32_bf16 v[8:11], v[202:205], v[226:229], v[8:11]
	v_mfma_f32_16x16x32_bf16 v[20:23], v[188:191], v[234:237], v[20:23]
	v_mfma_f32_16x16x32_bf16 v[16:19], v[202:205], v[234:237], v[16:19]
	v_mfma_f32_16x16x32_bf16 v[52:55], v[198:201], v[214:217], v[52:55]
	v_mfma_f32_16x16x32_bf16 v[48:51], v[206:209], v[214:217], v[48:51]
	v_mfma_f32_16x16x32_bf16 v[36:39], v[198:201], v[222:225], v[36:39]
	v_mfma_f32_16x16x32_bf16 v[32:35], v[206:209], v[222:225], v[32:35]
	v_mfma_f32_16x16x32_bf16 v[12:15], v[198:201], v[230:233], v[12:15]
	v_mfma_f32_16x16x32_bf16 v[8:11], v[206:209], v[230:233], v[8:11]
	v_mfma_f32_16x16x32_bf16 v[20:23], v[198:201], v[238:241], v[20:23]
	v_mfma_f32_16x16x32_bf16 v[16:19], v[206:209], v[238:241], v[16:19]
	s_setprio 0
	s_barrier
	s_add_i32 s54, 0, 0x18000
	s_add_i32 s16, 0, 0x1c000
	v_add_u32_e32 v171, s54, v166
	v_add_u32_e32 v172, s16, v166
	ds_read_b128 v[174:177], v171
	ds_read_b128 v[178:181], v171 offset:1024
	ds_read_b128 v[182:185], v171 offset:2048
	ds_read_b128 v[186:189], v171 offset:3072
	ds_read_b128 v[198:201], v172
	ds_read_b128 v[202:205], v172 offset:1024
	ds_read_b128 v[206:209], v172 offset:2048
	ds_read_b128 v[210:213], v172 offset:3072
	s_mov_b32 m0, s87
	v_lshl_add_u64 v[190:191], v[146:147], 0, s[34:35]
	ds_read_b128 v[214:217], v168 offset:32768
	ds_read_b128 v[218:221], v168 offset:33792
	ds_read_b128 v[222:225], v168 offset:34816
	ds_read_b128 v[226:229], v168 offset:35840
	ds_read_b128 v[230:233], v168 offset:36864
	ds_read_b128 v[234:237], v168 offset:37888
	ds_read_b128 v[238:241], v168 offset:38912
	ds_read_b128 v[242:245], v168 offset:39936
	global_load_lds_dwordx4 v[190:191], off
	v_lshl_add_u64 v[190:191], v[154:155], 0, s[34:35]
	s_mov_b32 m0, s4
	s_nop 0
	global_load_lds_dwordx4 v[190:191], off
	s_waitcnt vmcnt(8)
	s_waitcnt lgkmcnt(0)
	s_barrier
	s_setprio 1
	s_waitcnt lgkmcnt(0)
	v_mfma_f32_16x16x32_bf16 v[136:139], v[174:177], v[214:217], v[136:139]
	v_mfma_f32_16x16x32_bf16 v[132:135], v[182:185], v[214:217], v[132:135]
	v_mfma_f32_16x16x32_bf16 v[116:119], v[174:177], v[222:225], v[116:119]
	v_mfma_f32_16x16x32_bf16 v[112:115], v[182:185], v[222:225], v[112:115]
	v_mfma_f32_16x16x32_bf16 v[96:99], v[174:177], v[230:233], v[96:99]
	v_mfma_f32_16x16x32_bf16 v[92:95], v[182:185], v[230:233], v[92:95]
	v_mfma_f32_16x16x32_bf16 v[76:79], v[174:177], v[238:241], v[76:79]
	v_mfma_f32_16x16x32_bf16 v[72:75], v[182:185], v[238:241], v[72:75]
	v_mfma_f32_16x16x32_bf16 v[136:139], v[178:181], v[218:221], v[136:139]
	v_mfma_f32_16x16x32_bf16 v[132:135], v[186:189], v[218:221], v[132:135]
	v_mfma_f32_16x16x32_bf16 v[116:119], v[178:181], v[226:229], v[116:119]
	v_mfma_f32_16x16x32_bf16 v[112:115], v[186:189], v[226:229], v[112:115]
	v_mfma_f32_16x16x32_bf16 v[96:99], v[178:181], v[234:237], v[96:99]
	v_mfma_f32_16x16x32_bf16 v[92:95], v[186:189], v[234:237], v[92:95]
	v_mfma_f32_16x16x32_bf16 v[76:79], v[178:181], v[242:245], v[76:79]
	v_mfma_f32_16x16x32_bf16 v[72:75], v[186:189], v[242:245], v[72:75]
	s_setprio 0
	s_setprio 1
	v_mfma_f32_16x16x32_bf16 v[124:127], v[198:201], v[214:217], v[124:127]
	v_mfma_f32_16x16x32_bf16 v[120:123], v[206:209], v[214:217], v[120:123]
	v_mfma_f32_16x16x32_bf16 v[104:107], v[198:201], v[222:225], v[104:107]
	v_mfma_f32_16x16x32_bf16 v[100:103], v[206:209], v[222:225], v[100:103]
	v_mfma_f32_16x16x32_bf16 v[84:87], v[198:201], v[230:233], v[84:87]
	v_mfma_f32_16x16x32_bf16 v[80:83], v[206:209], v[230:233], v[80:83]
	v_mfma_f32_16x16x32_bf16 v[68:71], v[198:201], v[238:241], v[68:71]
	v_mfma_f32_16x16x32_bf16 v[64:67], v[206:209], v[238:241], v[64:67]
	v_mfma_f32_16x16x32_bf16 v[124:127], v[202:205], v[218:221], v[124:127]
	v_mfma_f32_16x16x32_bf16 v[120:123], v[210:213], v[218:221], v[120:123]
	v_mfma_f32_16x16x32_bf16 v[104:107], v[202:205], v[226:229], v[104:107]
	v_mfma_f32_16x16x32_bf16 v[100:103], v[210:213], v[226:229], v[100:103]
	v_mfma_f32_16x16x32_bf16 v[84:87], v[202:205], v[234:237], v[84:87]
	v_mfma_f32_16x16x32_bf16 v[80:83], v[210:213], v[234:237], v[80:83]
	v_mfma_f32_16x16x32_bf16 v[68:71], v[202:205], v[242:245], v[68:71]
	v_mfma_f32_16x16x32_bf16 v[64:67], v[210:213], v[242:245], v[64:67]
	s_setprio 0
	s_barrier
	s_add_i32 s54, s54, s84
	v_lshl_add_u64 v[190:191], v[246:247], 0, s[58:59]
	s_mov_b32 m0, s54
	s_add_i32 s30, s54, 0x2000
	ds_read_b128 v[214:217], v168 offset:49152
	ds_read_b128 v[218:221], v168 offset:50176
	ds_read_b128 v[222:225], v168 offset:51200
	ds_read_b128 v[226:229], v168 offset:52224
	ds_read_b128 v[230:233], v168 offset:53248
	ds_read_b128 v[234:237], v168 offset:54272
	ds_read_b128 v[238:241], v168 offset:55296
	ds_read_b128 v[242:245], v168 offset:56320
	global_load_lds_dwordx4 v[190:191], off
	v_lshl_add_u64 v[190:191], v[248:249], 0, s[58:59]
	s_mov_b32 m0, s30
	s_add_i32 s16, s16, s84
	global_load_lds_dwordx4 v[190:191], off
	v_lshl_add_u64 v[190:191], v[246:247], 0, s[72:73]
	s_mov_b32 m0, s16
	s_add_i32 s19, s16, 0x2000
	global_load_lds_dwordx4 v[190:191], off
	v_lshl_add_u64 v[190:191], v[248:249], 0, s[72:73]
	s_mov_b32 m0, s19
	v_lshl_add_u64 v[146:147], v[146:147], 0, s[58:59]
	global_load_lds_dwordx4 v[190:191], off
	s_mov_b32 m0, s5
	s_nop 0
	global_load_lds_dwordx4 v[146:147], off
	v_lshl_add_u64 v[146:147], v[154:155], 0, s[58:59]
	s_mov_b32 m0, s69
	s_nop 0
	global_load_lds_dwordx4 v[146:147], off
	s_waitcnt vmcnt(8)
	s_waitcnt lgkmcnt(0)
	s_barrier
	s_setprio 1
	s_waitcnt lgkmcnt(0)
	v_mfma_f32_16x16x32_bf16 v[60:63], v[174:177], v[214:217], v[60:63]
	v_mfma_f32_16x16x32_bf16 v[56:59], v[182:185], v[214:217], v[56:59]
	v_mfma_f32_16x16x32_bf16 v[44:47], v[174:177], v[222:225], v[44:47]
	v_mfma_f32_16x16x32_bf16 v[40:43], v[182:185], v[222:225], v[40:43]
	v_mfma_f32_16x16x32_bf16 v[28:31], v[174:177], v[230:233], v[28:31]
	v_mfma_f32_16x16x32_bf16 v[24:27], v[182:185], v[230:233], v[24:27]
	v_mfma_f32_16x16x32_bf16 v[4:7], v[174:177], v[238:241], v[4:7]
	v_mfma_f32_16x16x32_bf16 v[0:3], v[182:185], v[238:241], v[0:3]
	v_mfma_f32_16x16x32_bf16 v[60:63], v[178:181], v[218:221], v[60:63]
	v_mfma_f32_16x16x32_bf16 v[56:59], v[186:189], v[218:221], v[56:59]
	v_mfma_f32_16x16x32_bf16 v[44:47], v[178:181], v[226:229], v[44:47]
	v_mfma_f32_16x16x32_bf16 v[40:43], v[186:189], v[226:229], v[40:43]
	v_mfma_f32_16x16x32_bf16 v[28:31], v[178:181], v[234:237], v[28:31]
	v_mfma_f32_16x16x32_bf16 v[24:27], v[186:189], v[234:237], v[24:27]
	v_mfma_f32_16x16x32_bf16 v[4:7], v[178:181], v[242:245], v[4:7]
	v_mfma_f32_16x16x32_bf16 v[0:3], v[186:189], v[242:245], v[0:3]
	s_setprio 0
	s_setprio 1
	v_mfma_f32_16x16x32_bf16 v[52:55], v[198:201], v[214:217], v[52:55]
	s_add_i32 s11, s11, 2
	s_add_u32 s50, s50, 0x100
	s_addc_u32 s51, s51, 0
	s_cmp_gt_u32 s11, 39
	v_mfma_f32_16x16x32_bf16 v[48:51], v[206:209], v[214:217], v[48:51]
	v_mfma_f32_16x16x32_bf16 v[36:39], v[198:201], v[222:225], v[36:39]
	v_mfma_f32_16x16x32_bf16 v[32:35], v[206:209], v[222:225], v[32:35]
	v_mfma_f32_16x16x32_bf16 v[12:15], v[198:201], v[230:233], v[12:15]
	v_mfma_f32_16x16x32_bf16 v[8:11], v[206:209], v[230:233], v[8:11]
	v_mfma_f32_16x16x32_bf16 v[20:23], v[198:201], v[238:241], v[20:23]
	v_mfma_f32_16x16x32_bf16 v[16:19], v[206:209], v[238:241], v[16:19]
	v_mfma_f32_16x16x32_bf16 v[52:55], v[202:205], v[218:221], v[52:55]
	v_mfma_f32_16x16x32_bf16 v[48:51], v[210:213], v[218:221], v[48:51]
	v_mfma_f32_16x16x32_bf16 v[36:39], v[202:205], v[226:229], v[36:39]
	v_mfma_f32_16x16x32_bf16 v[32:35], v[210:213], v[226:229], v[32:35]
	v_mfma_f32_16x16x32_bf16 v[12:15], v[202:205], v[234:237], v[12:15]
	v_mfma_f32_16x16x32_bf16 v[8:11], v[210:213], v[234:237], v[8:11]
	v_mfma_f32_16x16x32_bf16 v[20:23], v[202:205], v[242:245], v[20:23]
	v_mfma_f32_16x16x32_bf16 v[16:19], v[210:213], v[242:245], v[16:19]
	s_setprio 0
	s_barrier
	s_cbranch_scc0 .LBB0_1193
	ds_read_b128 v[156:159], v169
	ds_read_b128 v[174:177], v169 offset:1024
	ds_read_b128 v[178:181], v169 offset:2048
	ds_read_b128 v[182:185], v169 offset:3072
	ds_read_b128 v[186:189], v170
	ds_read_b128 v[198:201], v170 offset:1024
	ds_read_b128 v[202:205], v170 offset:2048
	ds_read_b128 v[206:209], v170 offset:3072
	s_ashr_i32 s45, s44, 31
	s_ashr_i32 s13, s12, 31
	s_lshl_b64 s[8:9], s[12:13], 9
	s_lshl_b64 s[24:25], s[44:45], 19
	s_add_u32 s11, s60, s24
	s_addc_u32 s13, s61, s25
	s_add_u32 s24, s11, s8
	s_addc_u32 s25, s13, s9
	s_add_u32 s8, s46, 0xc1580
	s_addc_u32 s9, s47, 0
	s_mov_b32 m0, s33
	v_lshl_add_u64 v[142:143], s[8:9], 0, v[144:145]
	ds_read_b128 v[210:213], v168
	ds_read_b128 v[214:217], v168 offset:1024
	ds_read_b128 v[218:221], v168 offset:2048
	ds_read_b128 v[222:225], v168 offset:3072
	ds_read_b128 v[226:229], v168 offset:4096
	ds_read_b128 v[230:233], v168 offset:5120
	ds_read_b128 v[234:237], v168 offset:6144
	ds_read_b128 v[238:241], v168 offset:7168
	global_load_lds_dwordx4 v[142:143], off
	v_lshl_add_u64 v[142:143], s[8:9], 0, v[88:89]
	s_mov_b32 m0, s14
	s_nop 0
	global_load_lds_dwordx4 v[142:143], off
	s_waitcnt vmcnt(8)
	s_waitcnt lgkmcnt(0)
	s_barrier
	s_setprio 1
	s_waitcnt lgkmcnt(0)
	v_mfma_f32_16x16x32_bf16 v[136:139], v[156:159], v[210:213], v[136:139]
	v_mfma_f32_16x16x32_bf16 v[132:135], v[178:181], v[210:213], v[132:135]
	v_mfma_f32_16x16x32_bf16 v[116:119], v[156:159], v[218:221], v[116:119]
	v_mfma_f32_16x16x32_bf16 v[112:115], v[178:181], v[218:221], v[112:115]
	v_mfma_f32_16x16x32_bf16 v[96:99], v[156:159], v[226:229], v[96:99]
	v_mfma_f32_16x16x32_bf16 v[92:95], v[178:181], v[226:229], v[92:95]
	v_mfma_f32_16x16x32_bf16 v[76:79], v[156:159], v[234:237], v[76:79]
	v_mfma_f32_16x16x32_bf16 v[72:75], v[178:181], v[234:237], v[72:75]
	v_mfma_f32_16x16x32_bf16 v[136:139], v[174:177], v[214:217], v[136:139]
	v_mfma_f32_16x16x32_bf16 v[132:135], v[182:185], v[214:217], v[132:135]
	v_mfma_f32_16x16x32_bf16 v[116:119], v[174:177], v[222:225], v[116:119]
	v_mfma_f32_16x16x32_bf16 v[112:115], v[182:185], v[222:225], v[112:115]
	v_mfma_f32_16x16x32_bf16 v[96:99], v[174:177], v[230:233], v[96:99]
	v_mfma_f32_16x16x32_bf16 v[92:95], v[182:185], v[230:233], v[92:95]
	v_mfma_f32_16x16x32_bf16 v[76:79], v[174:177], v[238:241], v[76:79]
	v_mfma_f32_16x16x32_bf16 v[72:75], v[182:185], v[238:241], v[72:75]
	s_setprio 0
	s_setprio 1
	v_mfma_f32_16x16x32_bf16 v[124:127], v[186:189], v[210:213], v[124:127]
	v_mfma_f32_16x16x32_bf16 v[120:123], v[202:205], v[210:213], v[120:123]
	v_mfma_f32_16x16x32_bf16 v[104:107], v[186:189], v[218:221], v[104:107]
	v_mfma_f32_16x16x32_bf16 v[100:103], v[202:205], v[218:221], v[100:103]
	v_mfma_f32_16x16x32_bf16 v[84:87], v[186:189], v[226:229], v[84:87]
	v_mfma_f32_16x16x32_bf16 v[80:83], v[202:205], v[226:229], v[80:83]
	v_mfma_f32_16x16x32_bf16 v[68:71], v[186:189], v[234:237], v[68:71]
	v_mfma_f32_16x16x32_bf16 v[64:67], v[202:205], v[234:237], v[64:67]
	v_mfma_f32_16x16x32_bf16 v[124:127], v[198:201], v[214:217], v[124:127]
	v_mfma_f32_16x16x32_bf16 v[120:123], v[206:209], v[214:217], v[120:123]
	v_mfma_f32_16x16x32_bf16 v[104:107], v[198:201], v[222:225], v[104:107]
	v_mfma_f32_16x16x32_bf16 v[100:103], v[206:209], v[222:225], v[100:103]
	v_mfma_f32_16x16x32_bf16 v[84:87], v[198:201], v[230:233], v[84:87]
	v_mfma_f32_16x16x32_bf16 v[80:83], v[206:209], v[230:233], v[80:83]
	v_mfma_f32_16x16x32_bf16 v[68:71], v[198:201], v[238:241], v[68:71]
	v_mfma_f32_16x16x32_bf16 v[64:67], v[206:209], v[238:241], v[64:67]
	s_setprio 0
	s_barrier
	s_mov_b32 m0, s31
	v_lshl_add_u64 v[142:143], s[24:25], 0, v[90:91]
	ds_read_b128 v[210:213], v168 offset:16384
	ds_read_b128 v[214:217], v168 offset:17408
	ds_read_b128 v[218:221], v168 offset:18432
	ds_read_b128 v[222:225], v168 offset:19456
	ds_read_b128 v[226:229], v168 offset:20480
	ds_read_b128 v[230:233], v168 offset:21504
	ds_read_b128 v[234:237], v168 offset:22528
	ds_read_b128 v[238:241], v168 offset:23552
	global_load_lds_dwordx4 v[142:143], off
	v_lshl_add_u64 v[146:147], s[24:25], 0, v[108:109]
	s_mov_b32 m0, s15
	v_lshl_add_u64 v[154:155], v[142:143], 0, s[70:71]
	global_load_lds_dwordx4 v[146:147], off
	s_mov_b32 m0, s18
	s_nop 0
	global_load_lds_dwordx4 v[154:155], off
	v_lshl_add_u64 v[154:155], v[146:147], 0, s[70:71]
	s_mov_b32 m0, s23
	s_nop 0
	global_load_lds_dwordx4 v[154:155], off
	v_lshl_add_u64 v[154:155], v[142:143], 0, s[96:97]
	s_mov_b32 m0, s85
	s_nop 0
	global_load_lds_dwordx4 v[154:155], off
	v_lshl_add_u64 v[154:155], v[146:147], 0, s[96:97]
	s_mov_b32 m0, s86
	s_nop 0
	global_load_lds_dwordx4 v[154:155], off
	s_waitcnt vmcnt(8)
	s_waitcnt lgkmcnt(0)
	s_barrier
	s_setprio 1
	s_waitcnt lgkmcnt(0)
	v_mfma_f32_16x16x32_bf16 v[60:63], v[156:159], v[210:213], v[60:63]
	v_mfma_f32_16x16x32_bf16 v[56:59], v[178:181], v[210:213], v[56:59]
	v_mfma_f32_16x16x32_bf16 v[44:47], v[156:159], v[218:221], v[44:47]
	v_mfma_f32_16x16x32_bf16 v[40:43], v[178:181], v[218:221], v[40:43]
	v_mfma_f32_16x16x32_bf16 v[28:31], v[156:159], v[226:229], v[28:31]
	v_mfma_f32_16x16x32_bf16 v[24:27], v[178:181], v[226:229], v[24:27]
	v_mfma_f32_16x16x32_bf16 v[4:7], v[156:159], v[234:237], v[4:7]
	v_mfma_f32_16x16x32_bf16 v[0:3], v[178:181], v[234:237], v[0:3]
	v_mfma_f32_16x16x32_bf16 v[60:63], v[174:177], v[214:217], v[60:63]
	v_mfma_f32_16x16x32_bf16 v[56:59], v[182:185], v[214:217], v[56:59]
	v_mfma_f32_16x16x32_bf16 v[44:47], v[174:177], v[222:225], v[44:47]
	v_mfma_f32_16x16x32_bf16 v[40:43], v[182:185], v[222:225], v[40:43]
	v_mfma_f32_16x16x32_bf16 v[28:31], v[174:177], v[230:233], v[28:31]
	v_mfma_f32_16x16x32_bf16 v[24:27], v[182:185], v[230:233], v[24:27]
	v_mfma_f32_16x16x32_bf16 v[4:7], v[174:177], v[238:241], v[4:7]
	v_mfma_f32_16x16x32_bf16 v[0:3], v[182:185], v[238:241], v[0:3]
	s_setprio 0
	s_setprio 1
	v_mfma_f32_16x16x32_bf16 v[52:55], v[186:189], v[210:213], v[52:55]
	v_mfma_f32_16x16x32_bf16 v[48:51], v[202:205], v[210:213], v[48:51]
	v_mfma_f32_16x16x32_bf16 v[36:39], v[186:189], v[218:221], v[36:39]
	v_mfma_f32_16x16x32_bf16 v[32:35], v[202:205], v[218:221], v[32:35]
	v_mfma_f32_16x16x32_bf16 v[12:15], v[186:189], v[226:229], v[12:15]
	v_mfma_f32_16x16x32_bf16 v[8:11], v[202:205], v[226:229], v[8:11]
	v_mfma_f32_16x16x32_bf16 v[20:23], v[186:189], v[234:237], v[20:23]
	v_mfma_f32_16x16x32_bf16 v[16:19], v[202:205], v[234:237], v[16:19]
	v_mfma_f32_16x16x32_bf16 v[52:55], v[198:201], v[214:217], v[52:55]
	v_mfma_f32_16x16x32_bf16 v[48:51], v[206:209], v[214:217], v[48:51]
	v_mfma_f32_16x16x32_bf16 v[36:39], v[198:201], v[222:225], v[36:39]
	v_mfma_f32_16x16x32_bf16 v[32:35], v[206:209], v[222:225], v[32:35]
	v_mfma_f32_16x16x32_bf16 v[12:15], v[198:201], v[230:233], v[12:15]
	v_mfma_f32_16x16x32_bf16 v[8:11], v[206:209], v[230:233], v[8:11]
	v_mfma_f32_16x16x32_bf16 v[20:23], v[198:201], v[238:241], v[20:23]
	v_mfma_f32_16x16x32_bf16 v[16:19], v[206:209], v[238:241], v[16:19]
	s_setprio 0
	s_barrier
	ds_read_b128 v[156:159], v171
	ds_read_b128 v[174:177], v171 offset:1024
	ds_read_b128 v[178:181], v171 offset:2048
	ds_read_b128 v[182:185], v171 offset:3072
	ds_read_b128 v[186:189], v172
	ds_read_b128 v[198:201], v172 offset:1024
	ds_read_b128 v[202:205], v172 offset:2048
	ds_read_b128 v[170:173], v172 offset:3072
	s_mov_b32 m0, s87
	v_lshl_add_u64 v[142:143], v[142:143], 0, s[58:59]
	ds_read_b128 v[206:209], v168 offset:32768
	ds_read_b128 v[210:213], v168 offset:33792
	ds_read_b128 v[214:217], v168 offset:34816
	ds_read_b128 v[218:221], v168 offset:35840
	ds_read_b128 v[222:225], v168 offset:36864
	ds_read_b128 v[226:229], v168 offset:37888
	ds_read_b128 v[230:233], v168 offset:38912
	ds_read_b128 v[234:237], v168 offset:39936
	global_load_lds_dwordx4 v[142:143], off
	v_lshl_add_u64 v[142:143], v[146:147], 0, s[58:59]
	s_mov_b32 m0, s4
	s_nop 0
	global_load_lds_dwordx4 v[142:143], off
	s_waitcnt vmcnt(8)
	s_waitcnt lgkmcnt(0)
	s_barrier
	s_setprio 1
	s_waitcnt lgkmcnt(0)
	v_mfma_f32_16x16x32_bf16 v[136:139], v[156:159], v[206:209], v[136:139]
	v_mfma_f32_16x16x32_bf16 v[132:135], v[178:181], v[206:209], v[132:135]
	v_mfma_f32_16x16x32_bf16 v[116:119], v[156:159], v[214:217], v[116:119]
	v_mfma_f32_16x16x32_bf16 v[112:115], v[178:181], v[214:217], v[112:115]
	v_mfma_f32_16x16x32_bf16 v[96:99], v[156:159], v[222:225], v[96:99]
	v_mfma_f32_16x16x32_bf16 v[92:95], v[178:181], v[222:225], v[92:95]
	v_mfma_f32_16x16x32_bf16 v[76:79], v[156:159], v[230:233], v[76:79]
	v_mfma_f32_16x16x32_bf16 v[72:75], v[178:181], v[230:233], v[72:75]
	v_mfma_f32_16x16x32_bf16 v[136:139], v[174:177], v[210:213], v[136:139]
	v_mfma_f32_16x16x32_bf16 v[132:135], v[182:185], v[210:213], v[132:135]
	v_mfma_f32_16x16x32_bf16 v[116:119], v[174:177], v[218:221], v[116:119]
	v_mfma_f32_16x16x32_bf16 v[112:115], v[182:185], v[218:221], v[112:115]
	v_mfma_f32_16x16x32_bf16 v[96:99], v[174:177], v[226:229], v[96:99]
	v_mfma_f32_16x16x32_bf16 v[92:95], v[182:185], v[226:229], v[92:95]
	v_mfma_f32_16x16x32_bf16 v[76:79], v[174:177], v[234:237], v[76:79]
	v_mfma_f32_16x16x32_bf16 v[72:75], v[182:185], v[234:237], v[72:75]
	s_setprio 0
	s_setprio 1
	v_mfma_f32_16x16x32_bf16 v[124:127], v[186:189], v[206:209], v[124:127]
	v_mfma_f32_16x16x32_bf16 v[120:123], v[202:205], v[206:209], v[120:123]
	v_mfma_f32_16x16x32_bf16 v[104:107], v[186:189], v[214:217], v[104:107]
	v_mfma_f32_16x16x32_bf16 v[100:103], v[202:205], v[214:217], v[100:103]
	v_mfma_f32_16x16x32_bf16 v[84:87], v[186:189], v[222:225], v[84:87]
	v_mfma_f32_16x16x32_bf16 v[80:83], v[202:205], v[222:225], v[80:83]
	v_mfma_f32_16x16x32_bf16 v[68:71], v[186:189], v[230:233], v[68:71]
	v_mfma_f32_16x16x32_bf16 v[64:67], v[202:205], v[230:233], v[64:67]
	v_mfma_f32_16x16x32_bf16 v[124:127], v[198:201], v[210:213], v[124:127]
	v_mfma_f32_16x16x32_bf16 v[120:123], v[170:173], v[210:213], v[120:123]
	v_mfma_f32_16x16x32_bf16 v[104:107], v[198:201], v[218:221], v[104:107]
	v_mfma_f32_16x16x32_bf16 v[100:103], v[170:173], v[218:221], v[100:103]
	v_mfma_f32_16x16x32_bf16 v[84:87], v[198:201], v[226:229], v[84:87]
	v_mfma_f32_16x16x32_bf16 v[80:83], v[170:173], v[226:229], v[80:83]
	v_mfma_f32_16x16x32_bf16 v[68:71], v[198:201], v[234:237], v[68:71]
	v_mfma_f32_16x16x32_bf16 v[64:67], v[170:173], v[234:237], v[64:67]
	s_setprio 0
	s_barrier
	s_add_u32 s8, s24, 0x40000
	s_addc_u32 s9, s25, 0
	s_mov_b32 m0, s54
	v_lshl_add_u64 v[142:143], s[8:9], 0, v[90:91]
	ds_read_b128 v[206:209], v168 offset:49152
	ds_read_b128 v[210:213], v168 offset:50176
	ds_read_b128 v[214:217], v168 offset:51200
	ds_read_b128 v[218:221], v168 offset:52224
	ds_read_b128 v[222:225], v168 offset:53248
	ds_read_b128 v[226:229], v168 offset:54272
	ds_read_b128 v[230:233], v168 offset:55296
	ds_read_b128 v[234:237], v168 offset:56320
	global_load_lds_dwordx4 v[142:143], off
	v_lshl_add_u64 v[142:143], s[8:9], 0, v[108:109]
	s_add_u32 s8, s24, 0x40080
	s_mov_b32 m0, s30
	s_addc_u32 s9, s25, 0
	global_load_lds_dwordx4 v[142:143], off
	v_lshl_add_u64 v[142:143], s[8:9], 0, v[90:91]
	s_mov_b32 m0, s16
	s_nop 0
	global_load_lds_dwordx4 v[142:143], off
	v_lshl_add_u64 v[142:143], s[8:9], 0, v[108:109]
	s_add_u32 s8, s24, 0x40100
	s_mov_b32 m0, s19
	s_addc_u32 s9, s25, 0
	global_load_lds_dwordx4 v[142:143], off
	v_lshl_add_u64 v[142:143], s[8:9], 0, v[90:91]
	s_mov_b32 m0, s5
	s_nop 0
	global_load_lds_dwordx4 v[142:143], off
	v_lshl_add_u64 v[142:143], s[8:9], 0, v[108:109]
	s_mov_b32 m0, s69
	s_nop 0
	global_load_lds_dwordx4 v[142:143], off
	s_waitcnt vmcnt(8)
	s_waitcnt lgkmcnt(0)
	s_barrier
	s_setprio 1
	s_waitcnt lgkmcnt(0)
	v_mfma_f32_16x16x32_bf16 v[60:63], v[156:159], v[206:209], v[60:63]
	v_mfma_f32_16x16x32_bf16 v[56:59], v[178:181], v[206:209], v[56:59]
	v_mfma_f32_16x16x32_bf16 v[44:47], v[156:159], v[214:217], v[44:47]
	v_mfma_f32_16x16x32_bf16 v[40:43], v[178:181], v[214:217], v[40:43]
	v_mfma_f32_16x16x32_bf16 v[28:31], v[156:159], v[222:225], v[28:31]
	v_mfma_f32_16x16x32_bf16 v[24:27], v[178:181], v[222:225], v[24:27]
	v_mfma_f32_16x16x32_bf16 v[4:7], v[156:159], v[230:233], v[4:7]
	v_mfma_f32_16x16x32_bf16 v[0:3], v[178:181], v[230:233], v[0:3]
	v_mfma_f32_16x16x32_bf16 v[60:63], v[174:177], v[210:213], v[60:63]
	v_mfma_f32_16x16x32_bf16 v[56:59], v[182:185], v[210:213], v[56:59]
	v_mfma_f32_16x16x32_bf16 v[44:47], v[174:177], v[218:221], v[44:47]
	v_mfma_f32_16x16x32_bf16 v[40:43], v[182:185], v[218:221], v[40:43]
	v_mfma_f32_16x16x32_bf16 v[28:31], v[174:177], v[226:229], v[28:31]
	v_mfma_f32_16x16x32_bf16 v[24:27], v[182:185], v[226:229], v[24:27]
	v_mfma_f32_16x16x32_bf16 v[4:7], v[174:177], v[234:237], v[4:7]
	v_mfma_f32_16x16x32_bf16 v[0:3], v[182:185], v[234:237], v[0:3]
	s_setprio 0
	s_setprio 1
	v_mfma_f32_16x16x32_bf16 v[52:55], v[186:189], v[206:209], v[52:55]
	v_mfma_f32_16x16x32_bf16 v[48:51], v[202:205], v[206:209], v[48:51]
	v_mfma_f32_16x16x32_bf16 v[36:39], v[186:189], v[214:217], v[36:39]
	v_mfma_f32_16x16x32_bf16 v[32:35], v[202:205], v[214:217], v[32:35]
	v_mfma_f32_16x16x32_bf16 v[12:15], v[186:189], v[222:225], v[12:15]
	v_mfma_f32_16x16x32_bf16 v[8:11], v[202:205], v[222:225], v[8:11]
	v_mfma_f32_16x16x32_bf16 v[20:23], v[186:189], v[230:233], v[20:23]
	v_mfma_f32_16x16x32_bf16 v[16:19], v[202:205], v[230:233], v[16:19]
	v_mfma_f32_16x16x32_bf16 v[52:55], v[198:201], v[210:213], v[52:55]
	v_mfma_f32_16x16x32_bf16 v[48:51], v[170:173], v[210:213], v[48:51]
	v_mfma_f32_16x16x32_bf16 v[36:39], v[198:201], v[218:221], v[36:39]
	v_mfma_f32_16x16x32_bf16 v[32:35], v[170:173], v[218:221], v[32:35]
	v_mfma_f32_16x16x32_bf16 v[12:15], v[198:201], v[226:229], v[12:15]
	v_mfma_f32_16x16x32_bf16 v[8:11], v[170:173], v[226:229], v[8:11]
	v_mfma_f32_16x16x32_bf16 v[20:23], v[198:201], v[234:237], v[20:23]
	v_mfma_f32_16x16x32_bf16 v[16:19], v[170:173], v[234:237], v[16:19]
	s_setprio 0
	s_barrier
	s_and_b64 vcc, exec, s[38:39]
	s_cbranch_vccz .LBB0_1181
	s_nop 1
	v_mov_b32_e32 v8, 0
	s_mov_b32 s44, s3
	s_mov_b32 s12, s2
	s_mov_b64 s[42:43], s[40:41]
	s_mov_b64 s[46:47], s[48:49]
	s_mov_b32 s64, s10
	v_mov_b32_e32 v9, v8
	v_mov_b32_e32 v10, v8
	v_mov_b32_e32 v11, v8
	v_mov_b32_e32 v12, v8
	v_mov_b32_e32 v13, v8
	v_mov_b32_e32 v14, v8
	v_mov_b32_e32 v15, v8
	v_mov_b32_e32 v32, v8
	v_mov_b32_e32 v33, v8
	v_mov_b32_e32 v34, v8
	v_mov_b32_e32 v35, v8
	v_mov_b32_e32 v36, v8
	v_mov_b32_e32 v37, v8
	v_mov_b32_e32 v38, v8
	v_mov_b32_e32 v39, v8
	v_mov_b32_e32 v48, v8
	v_mov_b32_e32 v49, v8
	v_mov_b32_e32 v50, v8
	v_mov_b32_e32 v51, v8
	v_mov_b32_e32 v52, v8
	v_mov_b32_e32 v53, v8
	v_mov_b32_e32 v54, v8
	v_mov_b32_e32 v55, v8
	v_mov_b32_e32 v0, v8
	v_mov_b32_e32 v1, v8
	v_mov_b32_e32 v2, v8
	v_mov_b32_e32 v3, v8
	v_mov_b32_e32 v4, v8
	v_mov_b32_e32 v5, v8
	v_mov_b32_e32 v6, v8
	v_mov_b32_e32 v7, v8
	v_mov_b32_e32 v24, v8
	v_mov_b32_e32 v25, v8
	v_mov_b32_e32 v26, v8
	v_mov_b32_e32 v27, v8
	v_mov_b32_e32 v28, v8
	v_mov_b32_e32 v29, v8
	v_mov_b32_e32 v30, v8
	v_mov_b32_e32 v31, v8
	v_mov_b32_e32 v40, v8
	v_mov_b32_e32 v41, v8
	v_mov_b32_e32 v42, v8
	v_mov_b32_e32 v43, v8
	v_mov_b32_e32 v44, v8
	v_mov_b32_e32 v45, v8
	v_mov_b32_e32 v46, v8
	v_mov_b32_e32 v47, v8
	v_mov_b32_e32 v56, v8
	v_mov_b32_e32 v57, v8
	v_mov_b32_e32 v58, v8
	v_mov_b32_e32 v59, v8
	v_mov_b32_e32 v60, v8
	v_mov_b32_e32 v61, v8
	v_mov_b32_e32 v62, v8
	v_mov_b32_e32 v63, v8
	v_mov_b32_e32 v64, v8
	v_mov_b32_e32 v65, v8
	v_mov_b32_e32 v66, v8
	v_mov_b32_e32 v67, v8
	v_mov_b32_e32 v68, v8
	v_mov_b32_e32 v69, v8
	v_mov_b32_e32 v70, v8
	v_mov_b32_e32 v71, v8
	v_mov_b32_e32 v80, v8
	v_mov_b32_e32 v81, v8
	v_mov_b32_e32 v82, v8
	v_mov_b32_e32 v83, v8
	v_mov_b32_e32 v84, v8
	v_mov_b32_e32 v85, v8
	v_mov_b32_e32 v86, v8
	v_mov_b32_e32 v87, v8
	v_mov_b32_e32 v100, v8
	v_mov_b32_e32 v101, v8
	v_mov_b32_e32 v102, v8
	v_mov_b32_e32 v103, v8
	v_mov_b32_e32 v104, v8
	v_mov_b32_e32 v105, v8
	v_mov_b32_e32 v106, v8
	v_mov_b32_e32 v107, v8
	v_mov_b32_e32 v120, v8
	v_mov_b32_e32 v121, v8
	v_mov_b32_e32 v122, v8
	v_mov_b32_e32 v123, v8
	v_mov_b32_e32 v124, v8
	v_mov_b32_e32 v125, v8
	v_mov_b32_e32 v126, v8
	v_mov_b32_e32 v127, v8
	v_mov_b32_e32 v72, v8
	v_mov_b32_e32 v73, v8
	v_mov_b32_e32 v74, v8
	v_mov_b32_e32 v75, v8
	v_mov_b32_e32 v76, v8
	v_mov_b32_e32 v77, v8
	v_mov_b32_e32 v78, v8
	v_mov_b32_e32 v79, v8
	v_mov_b32_e32 v92, v8
	v_mov_b32_e32 v93, v8
	v_mov_b32_e32 v94, v8
	v_mov_b32_e32 v95, v8
	v_mov_b32_e32 v96, v8
	v_mov_b32_e32 v97, v8
	v_mov_b32_e32 v98, v8
	v_mov_b32_e32 v99, v8
	v_mov_b32_e32 v112, v8
	v_mov_b32_e32 v113, v8
	v_mov_b32_e32 v114, v8
	v_mov_b32_e32 v115, v8
	v_mov_b32_e32 v116, v8
	v_mov_b32_e32 v117, v8
	v_mov_b32_e32 v118, v8
	v_mov_b32_e32 v119, v8
	v_mov_b32_e32 v132, v8
	v_mov_b32_e32 v133, v8
	v_mov_b32_e32 v134, v8
	v_mov_b32_e32 v135, v8
	v_mov_b32_e32 v136, v8
	v_mov_b32_e32 v137, v8
	v_mov_b32_e32 v138, v8
	v_mov_b32_e32 v139, v8
	v_mov_b32_e32 v20, v8
	v_mov_b32_e32 v21, v8
	v_mov_b32_e32 v22, v8
	v_mov_b32_e32 v23, v8
	v_mov_b32_e32 v16, v8
	v_mov_b32_e32 v17, v8
	v_mov_b32_e32 v18, v8
	v_mov_b32_e32 v19, v8
	s_branch .LBB0_1181

.LBB0_1238:
	s_add_u32 s8, s42, s46
	s_addc_u32 s9, s43, s47
	s_add_u32 s8, s8, 0x100
	s_addc_u32 s9, s9, 0
	s_add_u32 s24, s48, s46
	s_addc_u32 s25, s49, s47
	s_add_i32 s27, 0, 0x10000
	s_cmpk_eq_i32 s46, 0x1500
	s_cselect_b32 s19, s45, s9
	s_cselect_b32 s18, s44, s8
	v_add_u32_e32 v146, s27, v143
	s_cselect_b32 s25, s41, s25
	s_cselect_b32 s24, s40, s24
	s_add_i32 s51, 0, 0x14000
	ds_read_b128 v[158:161], v146
	ds_read_b128 v[166:169], v146 offset:1024
	ds_read_b128 v[170:173], v146 offset:2048
	ds_read_b128 v[174:177], v146 offset:3072
	v_add_u32_e32 v146, s51, v143
	ds_read_b128 v[178:181], v146
	ds_read_b128 v[182:185], v146 offset:1024
	ds_read_b128 v[186:189], v146 offset:2048
	ds_read_b128 v[198:201], v146 offset:3072
	v_lshl_add_u64 v[146:147], v[138:139], 0, s[46:47]
	s_add_i32 m0, s3, 0xc000
	ds_read_b128 v[202:205], v156
	ds_read_b128 v[206:209], v156 offset:1024
	ds_read_b128 v[210:213], v156 offset:2048
	ds_read_b128 v[214:217], v156 offset:3072
	ds_read_b128 v[218:221], v156 offset:4096
	ds_read_b128 v[222:225], v156 offset:5120
	ds_read_b128 v[226:229], v156 offset:6144
	ds_read_b128 v[230:233], v156 offset:7168
	global_load_lds_dwordx4 v[146:147], off
	v_lshl_add_u64 v[146:147], v[140:141], 0, s[46:47]
	s_add_i32 m0, s3, 0xe000
	s_nop 0
	global_load_lds_dwordx4 v[146:147], off
	s_waitcnt vmcnt(8)
	s_waitcnt lgkmcnt(0)
	s_barrier
	s_setprio 1
	s_waitcnt lgkmcnt(0)
	v_mfma_f32_16x16x32_bf16 v[124:127], v[158:161], v[202:205], v[124:127]
	v_mfma_f32_16x16x32_bf16 v[120:123], v[170:173], v[202:205], v[120:123]
	v_mfma_f32_16x16x32_bf16 v[108:111], v[158:161], v[210:213], v[108:111]
	v_mfma_f32_16x16x32_bf16 v[104:107], v[170:173], v[210:213], v[104:107]
	v_mfma_f32_16x16x32_bf16 v[92:95], v[158:161], v[218:221], v[92:95]
	v_mfma_f32_16x16x32_bf16 v[88:91], v[170:173], v[218:221], v[88:91]
	v_mfma_f32_16x16x32_bf16 v[76:79], v[158:161], v[226:229], v[76:79]
	v_mfma_f32_16x16x32_bf16 v[72:75], v[170:173], v[226:229], v[72:75]
	v_mfma_f32_16x16x32_bf16 v[124:127], v[166:169], v[206:209], v[124:127]
	v_mfma_f32_16x16x32_bf16 v[120:123], v[174:177], v[206:209], v[120:123]
	v_mfma_f32_16x16x32_bf16 v[108:111], v[166:169], v[214:217], v[108:111]
	v_mfma_f32_16x16x32_bf16 v[104:107], v[174:177], v[214:217], v[104:107]
	v_mfma_f32_16x16x32_bf16 v[92:95], v[166:169], v[222:225], v[92:95]
	v_mfma_f32_16x16x32_bf16 v[88:91], v[174:177], v[222:225], v[88:91]
	v_mfma_f32_16x16x32_bf16 v[76:79], v[166:169], v[230:233], v[76:79]
	v_mfma_f32_16x16x32_bf16 v[72:75], v[174:177], v[230:233], v[72:75]
	s_setprio 0
	s_setprio 1
	v_mfma_f32_16x16x32_bf16 v[116:119], v[178:181], v[202:205], v[116:119]
	v_mfma_f32_16x16x32_bf16 v[112:115], v[186:189], v[202:205], v[112:115]
	v_mfma_f32_16x16x32_bf16 v[100:103], v[178:181], v[210:213], v[100:103]
	v_mfma_f32_16x16x32_bf16 v[96:99], v[186:189], v[210:213], v[96:99]
	v_mfma_f32_16x16x32_bf16 v[84:87], v[178:181], v[218:221], v[84:87]
	v_mfma_f32_16x16x32_bf16 v[80:83], v[186:189], v[218:221], v[80:83]
	v_mfma_f32_16x16x32_bf16 v[68:71], v[178:181], v[226:229], v[68:71]
	v_mfma_f32_16x16x32_bf16 v[64:67], v[186:189], v[226:229], v[64:67]
	v_mfma_f32_16x16x32_bf16 v[116:119], v[182:185], v[206:209], v[116:119]
	v_mfma_f32_16x16x32_bf16 v[112:115], v[198:201], v[206:209], v[112:115]
	v_mfma_f32_16x16x32_bf16 v[100:103], v[182:185], v[214:217], v[100:103]
	v_mfma_f32_16x16x32_bf16 v[96:99], v[198:201], v[214:217], v[96:99]
	v_mfma_f32_16x16x32_bf16 v[84:87], v[182:185], v[222:225], v[84:87]
	v_mfma_f32_16x16x32_bf16 v[80:83], v[198:201], v[222:225], v[80:83]
	v_mfma_f32_16x16x32_bf16 v[68:71], v[182:185], v[230:233], v[68:71]
	v_mfma_f32_16x16x32_bf16 v[64:67], v[198:201], v[230:233], v[64:67]
	s_setprio 0
	s_barrier
	s_add_i32 s8, s27, s2
	v_lshl_add_u64 v[146:147], s[24:25], 0, v[144:145]
	s_mov_b32 m0, s8
	ds_read_b128 v[202:205], v156 offset:16384
	ds_read_b128 v[206:209], v156 offset:17408
	ds_read_b128 v[210:213], v156 offset:18432
	ds_read_b128 v[214:217], v156 offset:19456
	ds_read_b128 v[218:221], v156 offset:20480
	ds_read_b128 v[222:225], v156 offset:21504
	ds_read_b128 v[226:229], v156 offset:22528
	ds_read_b128 v[230:233], v156 offset:23552
	global_load_lds_dwordx4 v[146:147], off
	s_add_i32 m0, s8, 0x2000
	s_add_u32 s8, s24, 0xb0000
	v_lshl_add_u64 v[154:155], s[24:25], 0, v[128:129]
	s_addc_u32 s9, s25, 0
	s_add_i32 s27, s51, s2
	global_load_lds_dwordx4 v[154:155], off
	v_lshl_add_u64 v[190:191], s[8:9], 0, v[144:145]
	s_mov_b32 m0, s27
	v_lshl_add_u64 v[234:235], s[18:19], 0, v[130:131]
	global_load_lds_dwordx4 v[190:191], off
	v_lshl_add_u64 v[190:191], s[8:9], 0, v[128:129]
	s_add_i32 m0, s27, 0x2000
	s_nop 0
	global_load_lds_dwordx4 v[190:191], off
	v_lshl_add_u64 v[190:191], s[18:19], 0, v[132:133]
	s_mov_b32 m0, s3
	s_nop 0
	global_load_lds_dwordx4 v[190:191], off
	s_mov_b32 m0, s4
	s_nop 0
	global_load_lds_dwordx4 v[234:235], off
	s_waitcnt vmcnt(8)
	s_waitcnt lgkmcnt(0)
	s_barrier
	s_setprio 1
	s_waitcnt lgkmcnt(0)
	v_mfma_f32_16x16x32_bf16 v[60:63], v[158:161], v[202:205], v[60:63]
	v_mfma_f32_16x16x32_bf16 v[56:59], v[170:173], v[202:205], v[56:59]
	v_mfma_f32_16x16x32_bf16 v[44:47], v[158:161], v[210:213], v[44:47]
	v_mfma_f32_16x16x32_bf16 v[40:43], v[170:173], v[210:213], v[40:43]
	v_mfma_f32_16x16x32_bf16 v[28:31], v[158:161], v[218:221], v[28:31]
	v_mfma_f32_16x16x32_bf16 v[24:27], v[170:173], v[218:221], v[24:27]
	v_mfma_f32_16x16x32_bf16 v[12:15], v[158:161], v[226:229], v[12:15]
	v_mfma_f32_16x16x32_bf16 v[8:11], v[170:173], v[226:229], v[8:11]
	v_mfma_f32_16x16x32_bf16 v[60:63], v[166:169], v[206:209], v[60:63]
	v_mfma_f32_16x16x32_bf16 v[56:59], v[174:177], v[206:209], v[56:59]
	v_mfma_f32_16x16x32_bf16 v[44:47], v[166:169], v[214:217], v[44:47]
	v_mfma_f32_16x16x32_bf16 v[40:43], v[174:177], v[214:217], v[40:43]
	v_mfma_f32_16x16x32_bf16 v[28:31], v[166:169], v[222:225], v[28:31]
	v_mfma_f32_16x16x32_bf16 v[24:27], v[174:177], v[222:225], v[24:27]
	v_mfma_f32_16x16x32_bf16 v[12:15], v[166:169], v[230:233], v[12:15]
	v_mfma_f32_16x16x32_bf16 v[8:11], v[174:177], v[230:233], v[8:11]
	s_setprio 0
	s_setprio 1
	v_mfma_f32_16x16x32_bf16 v[52:55], v[178:181], v[202:205], v[52:55]
	v_mfma_f32_16x16x32_bf16 v[48:51], v[186:189], v[202:205], v[48:51]
	v_mfma_f32_16x16x32_bf16 v[36:39], v[178:181], v[210:213], v[36:39]
	v_mfma_f32_16x16x32_bf16 v[32:35], v[186:189], v[210:213], v[32:35]
	v_mfma_f32_16x16x32_bf16 v[20:23], v[178:181], v[218:221], v[20:23]
	v_mfma_f32_16x16x32_bf16 v[16:19], v[186:189], v[218:221], v[16:19]
	v_mfma_f32_16x16x32_bf16 v[4:7], v[178:181], v[226:229], v[4:7]
	v_mfma_f32_16x16x32_bf16 v[0:3], v[186:189], v[226:229], v[0:3]
	v_mfma_f32_16x16x32_bf16 v[52:55], v[182:185], v[206:209], v[52:55]
	v_mfma_f32_16x16x32_bf16 v[48:51], v[198:201], v[206:209], v[48:51]
	v_mfma_f32_16x16x32_bf16 v[36:39], v[182:185], v[214:217], v[36:39]
	v_mfma_f32_16x16x32_bf16 v[32:35], v[198:201], v[214:217], v[32:35]
	v_mfma_f32_16x16x32_bf16 v[20:23], v[182:185], v[222:225], v[20:23]
	v_mfma_f32_16x16x32_bf16 v[16:19], v[198:201], v[222:225], v[16:19]
	v_mfma_f32_16x16x32_bf16 v[4:7], v[182:185], v[230:233], v[4:7]
	v_mfma_f32_16x16x32_bf16 v[0:3], v[198:201], v[230:233], v[0:3]
	s_setprio 0
	s_barrier
	s_add_i32 s27, 0, 0x18000
	v_add_u32_e32 v157, s27, v143
	s_add_i32 s51, 0, 0x1c000
	ds_read_b128 v[158:161], v157
	ds_read_b128 v[166:169], v157 offset:1024
	ds_read_b128 v[170:173], v157 offset:2048
	ds_read_b128 v[174:177], v157 offset:3072
	v_add_u32_e32 v157, s51, v143
	ds_read_b128 v[178:181], v157
	ds_read_b128 v[182:185], v157 offset:1024
	ds_read_b128 v[186:189], v157 offset:2048
	ds_read_b128 v[198:201], v157 offset:3072
	s_add_u32 s8, s18, 0xc0000
	s_addc_u32 s9, s19, 0
	s_mov_b32 m0, s5
	v_lshl_add_u64 v[236:237], s[8:9], 0, v[132:133]
	ds_read_b128 v[202:205], v156 offset:32768
	ds_read_b128 v[206:209], v156 offset:33792
	ds_read_b128 v[210:213], v156 offset:34816
	ds_read_b128 v[214:217], v156 offset:35840
	ds_read_b128 v[218:221], v156 offset:36864
	ds_read_b128 v[222:225], v156 offset:37888
	ds_read_b128 v[226:229], v156 offset:38912
	ds_read_b128 v[230:233], v156 offset:39936
	global_load_lds_dwordx4 v[236:237], off
	v_lshl_add_u64 v[236:237], s[8:9], 0, v[130:131]
	s_mov_b32 m0, s14
	s_nop 0
	global_load_lds_dwordx4 v[236:237], off
	s_waitcnt vmcnt(8)
	s_waitcnt lgkmcnt(0)
	s_barrier
	s_setprio 1
	s_waitcnt lgkmcnt(0)
	v_mfma_f32_16x16x32_bf16 v[124:127], v[158:161], v[202:205], v[124:127]
	v_mfma_f32_16x16x32_bf16 v[120:123], v[170:173], v[202:205], v[120:123]
	v_mfma_f32_16x16x32_bf16 v[108:111], v[158:161], v[210:213], v[108:111]
	v_mfma_f32_16x16x32_bf16 v[104:107], v[170:173], v[210:213], v[104:107]
	v_mfma_f32_16x16x32_bf16 v[92:95], v[158:161], v[218:221], v[92:95]
	v_mfma_f32_16x16x32_bf16 v[88:91], v[170:173], v[218:221], v[88:91]
	v_mfma_f32_16x16x32_bf16 v[76:79], v[158:161], v[226:229], v[76:79]
	v_mfma_f32_16x16x32_bf16 v[72:75], v[170:173], v[226:229], v[72:75]
	v_mfma_f32_16x16x32_bf16 v[124:127], v[166:169], v[206:209], v[124:127]
	v_mfma_f32_16x16x32_bf16 v[120:123], v[174:177], v[206:209], v[120:123]
	v_mfma_f32_16x16x32_bf16 v[108:111], v[166:169], v[214:217], v[108:111]
	v_mfma_f32_16x16x32_bf16 v[104:107], v[174:177], v[214:217], v[104:107]
	v_mfma_f32_16x16x32_bf16 v[92:95], v[166:169], v[222:225], v[92:95]
	v_mfma_f32_16x16x32_bf16 v[88:91], v[174:177], v[222:225], v[88:91]
	v_mfma_f32_16x16x32_bf16 v[76:79], v[166:169], v[230:233], v[76:79]
	v_mfma_f32_16x16x32_bf16 v[72:75], v[174:177], v[230:233], v[72:75]
	s_setprio 0
	s_setprio 1
	v_mfma_f32_16x16x32_bf16 v[116:119], v[178:181], v[202:205], v[116:119]
	v_mfma_f32_16x16x32_bf16 v[112:115], v[186:189], v[202:205], v[112:115]
	v_mfma_f32_16x16x32_bf16 v[100:103], v[178:181], v[210:213], v[100:103]
	v_mfma_f32_16x16x32_bf16 v[96:99], v[186:189], v[210:213], v[96:99]
	v_mfma_f32_16x16x32_bf16 v[84:87], v[178:181], v[218:221], v[84:87]
	v_mfma_f32_16x16x32_bf16 v[80:83], v[186:189], v[218:221], v[80:83]
	v_mfma_f32_16x16x32_bf16 v[68:71], v[178:181], v[226:229], v[68:71]
	v_mfma_f32_16x16x32_bf16 v[64:67], v[186:189], v[226:229], v[64:67]
	v_mfma_f32_16x16x32_bf16 v[116:119], v[182:185], v[206:209], v[116:119]
	v_mfma_f32_16x16x32_bf16 v[112:115], v[198:201], v[206:209], v[112:115]
	v_mfma_f32_16x16x32_bf16 v[100:103], v[182:185], v[214:217], v[100:103]
	v_mfma_f32_16x16x32_bf16 v[96:99], v[198:201], v[214:217], v[96:99]
	v_mfma_f32_16x16x32_bf16 v[84:87], v[182:185], v[222:225], v[84:87]
	v_mfma_f32_16x16x32_bf16 v[80:83], v[198:201], v[222:225], v[80:83]
	v_mfma_f32_16x16x32_bf16 v[68:71], v[182:185], v[230:233], v[68:71]
	v_mfma_f32_16x16x32_bf16 v[64:67], v[198:201], v[230:233], v[64:67]
	s_setprio 0
	s_barrier
	s_add_i32 s8, s27, s2
	v_lshl_add_u64 v[146:147], v[146:147], 0, s[70:71]
	s_mov_b32 m0, s8
	ds_read_b128 v[202:205], v156 offset:49152
	ds_read_b128 v[206:209], v156 offset:50176
	ds_read_b128 v[210:213], v156 offset:51200
	ds_read_b128 v[214:217], v156 offset:52224
	ds_read_b128 v[218:221], v156 offset:53248
	ds_read_b128 v[222:225], v156 offset:54272
	ds_read_b128 v[226:229], v156 offset:55296
	ds_read_b128 v[230:233], v156 offset:56320
	global_load_lds_dwordx4 v[146:147], off
	s_add_i32 m0, s8, 0x2000
	s_add_u32 s8, s24, 0xb0080
	v_lshl_add_u64 v[146:147], v[154:155], 0, s[70:71]
	s_addc_u32 s9, s25, 0
	s_add_i32 s18, s51, s2
	global_load_lds_dwordx4 v[146:147], off
	v_lshl_add_u64 v[146:147], s[8:9], 0, v[144:145]
	s_mov_b32 m0, s18
	s_nop 0
	global_load_lds_dwordx4 v[146:147], off
	v_lshl_add_u64 v[146:147], s[8:9], 0, v[128:129]
	s_add_i32 m0, s18, 0x2000
	s_nop 0
	global_load_lds_dwordx4 v[146:147], off
	v_lshl_add_u64 v[146:147], v[190:191], 0, s[70:71]
	s_mov_b32 m0, s10
	s_nop 0
	global_load_lds_dwordx4 v[146:147], off
	v_lshl_add_u64 v[146:147], v[234:235], 0, s[70:71]
	s_mov_b32 m0, s11
	s_nop 0
	global_load_lds_dwordx4 v[146:147], off
	s_waitcnt vmcnt(8)
	s_waitcnt lgkmcnt(0)
	s_barrier
	s_setprio 1
	s_waitcnt lgkmcnt(0)
	v_mfma_f32_16x16x32_bf16 v[60:63], v[158:161], v[202:205], v[60:63]
	v_mfma_f32_16x16x32_bf16 v[56:59], v[170:173], v[202:205], v[56:59]
	v_mfma_f32_16x16x32_bf16 v[44:47], v[158:161], v[210:213], v[44:47]
	v_mfma_f32_16x16x32_bf16 v[40:43], v[170:173], v[210:213], v[40:43]
	v_mfma_f32_16x16x32_bf16 v[28:31], v[158:161], v[218:221], v[28:31]
	v_mfma_f32_16x16x32_bf16 v[24:27], v[170:173], v[218:221], v[24:27]
	v_mfma_f32_16x16x32_bf16 v[12:15], v[158:161], v[226:229], v[12:15]
	v_mfma_f32_16x16x32_bf16 v[8:11], v[170:173], v[226:229], v[8:11]
	v_mfma_f32_16x16x32_bf16 v[60:63], v[166:169], v[206:209], v[60:63]
	v_mfma_f32_16x16x32_bf16 v[56:59], v[174:177], v[206:209], v[56:59]
	v_mfma_f32_16x16x32_bf16 v[44:47], v[166:169], v[214:217], v[44:47]
	v_mfma_f32_16x16x32_bf16 v[40:43], v[174:177], v[214:217], v[40:43]
	v_mfma_f32_16x16x32_bf16 v[28:31], v[166:169], v[222:225], v[28:31]
	v_mfma_f32_16x16x32_bf16 v[24:27], v[174:177], v[222:225], v[24:27]
	v_mfma_f32_16x16x32_bf16 v[12:15], v[166:169], v[230:233], v[12:15]
	v_mfma_f32_16x16x32_bf16 v[8:11], v[174:177], v[230:233], v[8:11]
	s_setprio 0
	s_setprio 1
	v_mfma_f32_16x16x32_bf16 v[52:55], v[178:181], v[202:205], v[52:55]
	s_add_i32 s50, s50, 2
	s_add_u32 s46, s46, 0x100
	s_addc_u32 s47, s47, 0
	s_cmp_gt_u32 s50, 41
	v_mfma_f32_16x16x32_bf16 v[48:51], v[186:189], v[202:205], v[48:51]
	v_mfma_f32_16x16x32_bf16 v[36:39], v[178:181], v[210:213], v[36:39]
	v_mfma_f32_16x16x32_bf16 v[32:35], v[186:189], v[210:213], v[32:35]
	v_mfma_f32_16x16x32_bf16 v[20:23], v[178:181], v[218:221], v[20:23]
	v_mfma_f32_16x16x32_bf16 v[16:19], v[186:189], v[218:221], v[16:19]
	v_mfma_f32_16x16x32_bf16 v[4:7], v[178:181], v[226:229], v[4:7]
	v_mfma_f32_16x16x32_bf16 v[0:3], v[186:189], v[226:229], v[0:3]
	v_mfma_f32_16x16x32_bf16 v[52:55], v[182:185], v[206:209], v[52:55]
	v_mfma_f32_16x16x32_bf16 v[48:51], v[198:201], v[206:209], v[48:51]
	v_mfma_f32_16x16x32_bf16 v[36:39], v[182:185], v[214:217], v[36:39]
	v_mfma_f32_16x16x32_bf16 v[32:35], v[198:201], v[214:217], v[32:35]
	v_mfma_f32_16x16x32_bf16 v[20:23], v[182:185], v[222:225], v[20:23]
	v_mfma_f32_16x16x32_bf16 v[16:19], v[198:201], v[222:225], v[16:19]
	v_mfma_f32_16x16x32_bf16 v[4:7], v[182:185], v[230:233], v[4:7]
	v_mfma_f32_16x16x32_bf16 v[0:3], v[198:201], v[230:233], v[0:3]
	s_setprio 0
	s_barrier
	s_cbranch_scc0 .LBB0_1238
	s_add_u32 s18, s48, 0xffffff00
	s_addc_u32 s19, s49, -1
	s_and_b64 vcc, exec, s[38:39]
	s_cbranch_vccnz .LBB0_1241
	v_mov_b32_e32 v0, 0
	s_mov_b32 s12, s30
	s_mov_b32 s23, s31
	s_mov_b64 s[42:43], s[44:45]
	s_mov_b32 s16, s33
	v_mov_b32_e32 v1, v0
	v_mov_b32_e32 v2, v0
	v_mov_b32_e32 v3, v0
	v_mov_b32_e32 v4, v0
	v_mov_b32_e32 v5, v0
	v_mov_b32_e32 v6, v0
	v_mov_b32_e32 v7, v0
	v_mov_b32_e32 v16, v0
	v_mov_b32_e32 v17, v0
	v_mov_b32_e32 v18, v0
	v_mov_b32_e32 v19, v0
	v_mov_b32_e32 v20, v0
	v_mov_b32_e32 v21, v0
	v_mov_b32_e32 v22, v0
	v_mov_b32_e32 v23, v0
	v_mov_b32_e32 v32, v0
	v_mov_b32_e32 v33, v0
	v_mov_b32_e32 v34, v0
	v_mov_b32_e32 v35, v0
	v_mov_b32_e32 v36, v0
	v_mov_b32_e32 v37, v0
	v_mov_b32_e32 v38, v0
	v_mov_b32_e32 v39, v0
	v_mov_b32_e32 v48, v0
	v_mov_b32_e32 v49, v0
	v_mov_b32_e32 v50, v0
	v_mov_b32_e32 v51, v0
	v_mov_b32_e32 v52, v0
	v_mov_b32_e32 v53, v0
	v_mov_b32_e32 v54, v0
	v_mov_b32_e32 v55, v0
	v_mov_b32_e32 v8, v0
	v_mov_b32_e32 v9, v0
	v_mov_b32_e32 v10, v0
	v_mov_b32_e32 v11, v0
	v_mov_b32_e32 v12, v0
	v_mov_b32_e32 v13, v0
	v_mov_b32_e32 v14, v0
	v_mov_b32_e32 v15, v0
	v_mov_b32_e32 v24, v0
	v_mov_b32_e32 v25, v0
	v_mov_b32_e32 v26, v0
	v_mov_b32_e32 v27, v0
	v_mov_b32_e32 v28, v0
	v_mov_b32_e32 v29, v0
	v_mov_b32_e32 v30, v0
	v_mov_b32_e32 v31, v0
	v_mov_b32_e32 v40, v0
	v_mov_b32_e32 v41, v0
	v_mov_b32_e32 v42, v0
	v_mov_b32_e32 v43, v0
	v_mov_b32_e32 v44, v0
	v_mov_b32_e32 v45, v0
	v_mov_b32_e32 v46, v0
	v_mov_b32_e32 v47, v0
	v_mov_b32_e32 v56, v0
	v_mov_b32_e32 v57, v0
	v_mov_b32_e32 v58, v0
	v_mov_b32_e32 v59, v0
	v_mov_b32_e32 v60, v0
	v_mov_b32_e32 v61, v0
	v_mov_b32_e32 v62, v0
	v_mov_b32_e32 v63, v0
	v_mov_b32_e32 v64, v0
	v_mov_b32_e32 v65, v0
	v_mov_b32_e32 v66, v0
	v_mov_b32_e32 v67, v0
	v_mov_b32_e32 v68, v0
	v_mov_b32_e32 v69, v0
	v_mov_b32_e32 v70, v0
	v_mov_b32_e32 v71, v0
	v_mov_b32_e32 v80, v0
	v_mov_b32_e32 v81, v0
	v_mov_b32_e32 v82, v0
	v_mov_b32_e32 v83, v0
	v_mov_b32_e32 v84, v0
	v_mov_b32_e32 v85, v0
	v_mov_b32_e32 v86, v0
	v_mov_b32_e32 v87, v0
	v_mov_b32_e32 v96, v0
	v_mov_b32_e32 v97, v0
	v_mov_b32_e32 v98, v0
	v_mov_b32_e32 v99, v0
	v_mov_b32_e32 v100, v0
	v_mov_b32_e32 v101, v0
	v_mov_b32_e32 v102, v0
	v_mov_b32_e32 v103, v0
	v_mov_b32_e32 v112, v0
	v_mov_b32_e32 v113, v0
	v_mov_b32_e32 v114, v0
	v_mov_b32_e32 v115, v0
	v_mov_b32_e32 v116, v0
	v_mov_b32_e32 v117, v0
	v_mov_b32_e32 v118, v0
	v_mov_b32_e32 v119, v0
	v_mov_b32_e32 v72, v0
	v_mov_b32_e32 v73, v0
	v_mov_b32_e32 v74, v0
	v_mov_b32_e32 v75, v0
	v_mov_b32_e32 v76, v0
	v_mov_b32_e32 v77, v0
	v_mov_b32_e32 v78, v0
	v_mov_b32_e32 v79, v0
	v_mov_b32_e32 v88, v0
	v_mov_b32_e32 v89, v0
	v_mov_b32_e32 v90, v0
	v_mov_b32_e32 v91, v0
	v_mov_b32_e32 v92, v0
	v_mov_b32_e32 v93, v0
	v_mov_b32_e32 v94, v0
	v_mov_b32_e32 v95, v0
	v_mov_b32_e32 v104, v0
	v_mov_b32_e32 v105, v0
	v_mov_b32_e32 v106, v0
	v_mov_b32_e32 v107, v0
	v_mov_b32_e32 v108, v0
	v_mov_b32_e32 v109, v0
	v_mov_b32_e32 v110, v0
	v_mov_b32_e32 v111, v0
	v_mov_b32_e32 v120, v0
	v_mov_b32_e32 v121, v0
	v_mov_b32_e32 v122, v0
	v_mov_b32_e32 v123, v0
	v_mov_b32_e32 v124, v0
	v_mov_b32_e32 v125, v0
	v_mov_b32_e32 v126, v0
	v_mov_b32_e32 v127, v0
	s_branch .LBB0_1242
